# I + every packed f32 VALU op (v_pk_mul/add/fma_f32) inside the layer loop split into two scalar f32 ops (identical IEEE math)
# baseline (speedup 1.0000x reference)
; #define GAS __attribute__((address_space(1)))
; __device__ __forceinline__ unsigned pk2(float lo, float hi) { return f2bf(lo) | (f2bf(hi) << 16); }
; template <int X> __device__ __forceinline__ float swz(float v) { return __builtin_bit_cast(float, __builtin_amdgcn_ds_swizzle(__builtin_bit_cast(int, v), (X << 10) | 0x1f)); }
; __device__ __forceinline__ float xsum32(float v) { const SwapPair r = swap32(v); return __builtin_bit_cast(float, r.a) + __builtin_bit_cast(float, r.b); }
; __device__ __forceinline__ float wave_sum(float v) {
;     v += swz<1>(v); v += swz<2>(v); v += swz<4>(v); v += swz<8>(v); v += swz<16>(v);
;     return xsum32(v);
; }
; __device__ __forceinline__ void modulate_phase(Frame& F, const float* x, bf16* H, const float* gnorm, const float* modsub) {
;     ...
;         float s = 0.f;
; #pragma unroll
;         for (int j = 0; j < 8; ++j) s += (v[j].x * v[j].x + v[j].y * v[j].y) + (v[j].z * v[j].z + v[j].w * v[j].w);
;         const float rstd = 1.0f / sqrtf(wave_sum(s) * (1.0f / D) + RMS_EPS);
;         GAS unsigned long long* o8 = (GAS unsigned long long*)(H + (size_t)r * D) + F.lane;
; #pragma unroll
;         for (int j = 0; j < 8; ++j) { const f32x4 y = v[j] * rstd * gs[j] + sh[j];
;             o8[64 * j] = (unsigned long long)pk2(y.x, y.y) | ((unsigned long long)pk2(y.z, y.w) << 32); }
.LBB0_216:
	s_waitcnt vmcnt(8)
	v_mul_f32_e32 v0, v95, v95
	v_mul_f32_e32 v149, v97, v97
	v_fmac_f32_e32 v0, v94, v94
	v_fmac_f32_e32 v149, v96, v96
	v_add_f32_e32 v0, v0, v149
	v_mul_f32_e32 v149, v91, v91
	v_mul_f32_e32 v150, v93, v93
	v_fmac_f32_e32 v149, v90, v90
	v_fmac_f32_e32 v150, v92, v92
	v_add_f32_e32 v149, v149, v150
	v_add_f32_e32 v0, v0, v149
	v_mul_f32_e32 v149, v55, v55
	v_mul_f32_e32 v150, v57, v57
	v_fmac_f32_e32 v149, v54, v54
	v_fmac_f32_e32 v150, v56, v56
	v_add_f32_e32 v149, v149, v150
	v_add_f32_e32 v0, v149, v0
	v_mul_f32_e32 v149, v43, v43
	v_mul_f32_e32 v150, v45, v45
	v_fmac_f32_e32 v149, v42, v42
	v_fmac_f32_e32 v150, v44, v44
	v_add_f32_e32 v149, v149, v150
	v_add_f32_e32 v0, v149, v0
	v_mul_f32_e32 v149, v31, v31
	v_mul_f32_e32 v150, v33, v33
	v_fmac_f32_e32 v149, v30, v30
	v_fmac_f32_e32 v150, v32, v32
	v_add_f32_e32 v149, v149, v150
	v_add_f32_e32 v0, v149, v0
	v_mul_f32_e32 v149, v27, v27
	v_mul_f32_e32 v150, v29, v29
	v_fmac_f32_e32 v149, v26, v26
	v_fmac_f32_e32 v150, v28, v28
	v_add_f32_e32 v149, v149, v150
	v_add_f32_e32 v0, v149, v0
	v_mul_f32_e32 v149, v15, v15
	v_mul_f32_e32 v150, v17, v17
	v_fmac_f32_e32 v149, v14, v14
	v_fmac_f32_e32 v150, v16, v16
	v_add_f32_e32 v149, v149, v150
	v_add_f32_e32 v0, v149, v0
	v_mul_f32_e32 v149, v11, v11
	v_mul_f32_e32 v150, v13, v13
	v_fmac_f32_e32 v149, v10, v10
	v_fmac_f32_e32 v150, v12, v12
	v_add_f32_e32 v149, v149, v150
	v_add_f32_e32 v0, v149, v0
	ds_swizzle_b32 v149, v0 offset:swizzle(SWAP,1)
	s_waitcnt lgkmcnt(0)
	v_add_f32_e32 v0, v0, v149
	ds_swizzle_b32 v149, v0 offset:swizzle(SWAP,2)
	s_waitcnt lgkmcnt(0)
	v_add_f32_e32 v0, v0, v149
	ds_swizzle_b32 v149, v0 offset:swizzle(SWAP,4)
	s_waitcnt lgkmcnt(0)
	v_add_f32_e32 v0, v0, v149
	ds_swizzle_b32 v149, v0 offset:swizzle(SWAP,8)
	s_waitcnt lgkmcnt(0)
	v_add_f32_e32 v0, v0, v149
	ds_swizzle_b32 v149, v0 offset:swizzle(SWAP,16)
	s_waitcnt lgkmcnt(0)
	v_add_f32_e32 v0, v0, v149
	v_mov_b32_e32 v149, v0
	s_nop 1
	v_permlane32_swap_b32_e32 v0, v149
	v_add_f32_e32 v0, v0, v149
	v_fmamk_f32 v0, v0, 0x3a000000, v202
	v_mul_f32_e32 v149, 0x4f800000, v0
	v_cmp_gt_f32_e32 vcc, s60, v0
	s_nop 1
	v_cndmask_b32_e32 v0, v0, v149, vcc
	v_sqrt_f32_e32 v149, v0
	s_nop 0
	v_add_u32_e32 v150, -1, v149
	v_fma_f32 v151, -v150, v149, v0
	v_cmp_ge_f32_e64 s[36:37], 0, v151
	v_add_u32_e32 v151, 1, v149
	s_nop 0
	v_cndmask_b32_e64 v150, v149, v150, s[36:37]
	v_fma_f32 v149, -v151, v149, v0
	v_cmp_lt_f32_e64 s[36:37], 0, v149
	s_nop 1
	v_cndmask_b32_e64 v149, v150, v151, s[36:37]
	v_mul_f32_e32 v150, 0x37800000, v149
	v_cndmask_b32_e32 v149, v149, v150, vcc
	v_cmp_class_f32_e32 vcc, v0, v203
	s_nop 1
	v_cndmask_b32_e32 v0, v149, v0, vcc
	v_div_scale_f32 v149, s[12:13], v0, v0, 1.0
	v_rcp_f32_e32 v150, v149
	s_nop 0
	v_fma_f32 v151, -v149, v150, 1.0
	v_fmac_f32_e32 v150, v151, v150
	v_div_scale_f32 v151, vcc, 1.0, v0, 1.0
	v_mul_f32_e32 v152, v151, v150
	v_fma_f32 v153, -v149, v152, v151
	v_fmac_f32_e32 v152, v153, v150
	v_fma_f32 v149, -v149, v152, v151
	v_div_fmas_f32 v149, v149, v150, v152
	v_div_fixup_f32 v0, v149, v0, 1.0
	v_mul_f32_e32 v94, v94, v0
	v_mul_f32_e32 v95, v95, v0
	v_mul_f32_e32 v96, v96, v0
	v_mul_f32_e32 v97, v97, v0
	v_fma_f32 v94, v2, v94, v6
	v_fma_f32 v95, v3, v95, v7
	v_fma_f32 v96, v4, v96, v8
	v_fma_f32 v97, v5, v97, v9
	v_bfe_u32 v150, v94, 16, 1
	v_add3_u32 v94, v94, v150, s94
	v_bfe_u32 v150, v95, 16, 1
	v_lshrrev_b32_e32 v94, 16, v94
	v_add3_u32 v95, v95, v150, s94
	v_and_or_b32 v94, v95, s95, v94
	v_bfe_u32 v95, v96, 16, 1
	v_add3_u32 v95, v96, v95, s94
	v_bfe_u32 v96, v97, 16, 1
	v_lshrrev_b32_e32 v95, 16, v95
	v_add3_u32 v96, v97, v96, s94
	v_mul_f32_e32 v90, v90, v0
	v_mul_f32_e32 v91, v91, v0
	v_lshlrev_b32_e32 v149, 3, v130
	v_and_or_b32 v95, v96, s95, v95
	v_fma_f32 v90, v22, v90, v18
	v_fma_f32 v91, v23, v91, v19
	global_store_dwordx2 v149, v[94:95], s[8:9]
	v_bfe_u32 v94, v90, 16, 1
	v_mul_f32_e32 v92, v92, v0
	v_mul_f32_e32 v93, v93, v0
	v_add3_u32 v90, v90, v94, s94
	v_bfe_u32 v94, v91, 16, 1
	v_fma_f32 v92, v24, v92, v20
	v_fma_f32 v93, v25, v93, v21
	v_lshrrev_b32_e32 v90, 16, v90
	v_add3_u32 v91, v91, v94, s94
	v_and_or_b32 v90, v91, s95, v90
	v_bfe_u32 v91, v92, 16, 1
	v_add3_u32 v91, v92, v91, s94
	v_bfe_u32 v92, v93, 16, 1
	v_lshrrev_b32_e32 v91, 16, v91
	v_add3_u32 v92, v93, v92, s94
	v_mul_f32_e32 v54, v54, v0
	v_mul_f32_e32 v55, v55, v0
	v_and_or_b32 v91, v92, s95, v91
	v_fma_f32 v54, v38, v54, v34
	v_fma_f32 v55, v39, v55, v35
	global_store_dwordx2 v149, v[90:91], s[8:9] offset:512
	v_bfe_u32 v90, v54, 16, 1
	v_mul_f32_e32 v56, v56, v0
	v_mul_f32_e32 v57, v57, v0
	v_add3_u32 v54, v54, v90, s94
	v_bfe_u32 v90, v55, 16, 1
	v_fma_f32 v56, v40, v56, v36
	v_fma_f32 v57, v41, v57, v37
	v_lshrrev_b32_e32 v54, 16, v54
	v_add3_u32 v55, v55, v90, s94
	v_and_or_b32 v54, v55, s95, v54
	v_bfe_u32 v55, v56, 16, 1
	v_add3_u32 v55, v56, v55, s94
	v_bfe_u32 v56, v57, 16, 1
	v_lshrrev_b32_e32 v55, 16, v55
	v_add3_u32 v56, v57, v56, s94
	v_mul_f32_e32 v42, v42, v0
	v_mul_f32_e32 v43, v43, v0
	v_and_or_b32 v55, v56, s95, v55
	v_fma_f32 v42, v86, v42, v78
	v_fma_f32 v43, v87, v43, v79
	global_store_dwordx2 v149, v[54:55], s[8:9] offset:1024
	v_bfe_u32 v54, v42, 16, 1
	v_mul_f32_e32 v44, v44, v0
	v_mul_f32_e32 v45, v45, v0
	v_add3_u32 v42, v42, v54, s94
	v_bfe_u32 v54, v43, 16, 1
	v_fma_f32 v44, v88, v44, v80
	v_fma_f32 v45, v89, v45, v81
	v_lshrrev_b32_e32 v42, 16, v42
	v_add3_u32 v43, v43, v54, s94
	v_and_or_b32 v42, v43, s95, v42
	v_bfe_u32 v43, v44, 16, 1
	v_add3_u32 v43, v44, v43, s94
	v_bfe_u32 v44, v45, 16, 1
	v_lshrrev_b32_e32 v43, 16, v43
	v_add3_u32 v44, v45, v44, s94
	v_mul_f32_e32 v30, v30, v0
; #define GAS __attribute__((address_space(1)))
; __device__ __forceinline__ unsigned pk2(float lo, float hi) { return f2bf(lo) | (f2bf(hi) << 16); }
; __device__ __forceinline__ void modulate_phase(Frame& F, const float* x, bf16* H, const float* gnorm, const float* modsub) {
;     ...
;         GAS unsigned long long* o8 = (GAS unsigned long long*)(H + (size_t)r * D) + F.lane;
; #pragma unroll
;         for (int j = 0; j < 8; ++j) { const f32x4 y = v[j] * rstd * gs[j] + sh[j];
;             o8[64 * j] = (unsigned long long)pk2(y.x, y.y) | ((unsigned long long)pk2(y.z, y.w) << 32); }
; #pragma unroll
;         for (int j = 0; j < 8; ++j) v[j] = nv[j];
	v_mul_f32_e32 v31, v31, v0
	v_and_or_b32 v43, v44, s95, v43
	v_fma_f32 v30, v102, v30, v98
	v_fma_f32 v31, v103, v31, v99
	global_store_dwordx2 v149, v[42:43], s[8:9] offset:1536
	v_bfe_u32 v42, v30, 16, 1
	v_mul_f32_e32 v32, v32, v0
	v_mul_f32_e32 v33, v33, v0
	v_add3_u32 v30, v30, v42, s94
	v_bfe_u32 v42, v31, 16, 1
	v_fma_f32 v32, v104, v32, v100
	v_fma_f32 v33, v105, v33, v101
	v_lshrrev_b32_e32 v30, 16, v30
	v_add3_u32 v31, v31, v42, s94
	v_and_or_b32 v30, v31, s95, v30
	v_bfe_u32 v31, v32, 16, 1
	v_add3_u32 v31, v32, v31, s94
	v_bfe_u32 v32, v33, 16, 1
	v_lshrrev_b32_e32 v31, 16, v31
	v_add3_u32 v32, v33, v32, s94
	v_mul_f32_e32 v26, v26, v0
	v_mul_f32_e32 v27, v27, v0
	v_and_or_b32 v31, v32, s95, v31
	v_fma_f32 v26, v110, v26, v106
	v_fma_f32 v27, v111, v27, v107
	global_store_dwordx2 v149, v[30:31], s[8:9] offset:2048
	v_bfe_u32 v30, v26, 16, 1
	v_mul_f32_e32 v28, v28, v0
	v_mul_f32_e32 v29, v29, v0
	v_add3_u32 v26, v26, v30, s94
	v_bfe_u32 v30, v27, 16, 1
	v_fma_f32 v28, v112, v28, v108
	v_fma_f32 v29, v113, v29, v109
	v_lshrrev_b32_e32 v26, 16, v26
	v_add3_u32 v27, v27, v30, s94
	v_and_or_b32 v26, v27, s95, v26
	v_bfe_u32 v27, v28, 16, 1
	v_add3_u32 v27, v28, v27, s94
	v_bfe_u32 v28, v29, 16, 1
	v_lshrrev_b32_e32 v27, 16, v27
	v_add3_u32 v28, v29, v28, s94
	v_mul_f32_e32 v14, v14, v0
	v_mul_f32_e32 v15, v15, v0
	v_mul_f32_e32 v10, v10, v0
	v_mul_f32_e32 v11, v11, v0
	v_and_or_b32 v27, v28, s95, v27
	v_fma_f32 v14, v118, v14, v114
	v_fma_f32 v15, v119, v15, v115
	v_fma_f32 v10, v122, v10, v126
	v_fma_f32 v11, v123, v11, v127
	global_store_dwordx2 v149, v[26:27], s[8:9] offset:2560
	v_mul_f32_e32 v16, v16, v0
	v_mul_f32_e32 v17, v17, v0
	v_bfe_u32 v26, v14, 16, 1
	v_mul_f32_e32 v12, v12, v0
	v_mul_f32_e32 v13, v13, v0
	v_bfe_u32 v0, v10, 16, 1
	v_add3_u32 v14, v14, v26, s94
	v_bfe_u32 v26, v15, 16, 1
	v_add3_u32 v0, v10, v0, s94
	v_bfe_u32 v10, v11, 16, 1
	v_fma_f32 v16, v120, v16, v116
	v_fma_f32 v17, v121, v17, v117
	v_lshrrev_b32_e32 v14, 16, v14
	v_add3_u32 v15, v15, v26, s94
	v_fma_f32 v12, v124, v12, v128
	v_fma_f32 v13, v125, v13, v129
	v_lshrrev_b32_e32 v0, 16, v0
	v_add3_u32 v10, v11, v10, s94
	v_and_or_b32 v14, v15, s95, v14
	v_bfe_u32 v15, v16, 16, 1
	v_and_or_b32 v10, v10, s95, v0
	v_bfe_u32 v0, v12, 16, 1
	v_add3_u32 v15, v16, v15, s94
	v_bfe_u32 v16, v17, 16, 1
	v_add3_u32 v0, v12, v0, s94
	v_bfe_u32 v11, v13, 16, 1
	v_lshrrev_b32_e32 v15, 16, v15
	v_add3_u32 v16, v17, v16, s94
	v_lshrrev_b32_e32 v0, 16, v0
	v_add3_u32 v11, v13, v11, s94
	v_and_or_b32 v15, v16, s95, v15
	v_and_or_b32 v11, v11, s95, v0
	global_store_dwordx2 v149, v[14:15], s[8:9] offset:3072
	global_store_dwordx2 v149, v[10:11], s[8:9] offset:3584
	s_add_u32 s8, s8, 0x1000
	s_addc_u32 s9, s9, 0
	s_cmp_lt_i32 s6, s2
	s_waitcnt vmcnt(8)
	v_mov_b32_e32 v94, v82
	v_mov_b32_e32 v95, v83
	v_mov_b32_e32 v96, v84
	v_mov_b32_e32 v97, v85
	v_mov_b32_e32 v90, v74
	v_mov_b32_e32 v91, v75
	v_mov_b32_e32 v92, v76
	v_mov_b32_e32 v93, v77
	v_mov_b32_e32 v54, v66
	v_mov_b32_e32 v55, v67
	v_mov_b32_e32 v56, v68
	v_mov_b32_e32 v57, v69
	v_mov_b32_e32 v42, v58
	v_mov_b32_e32 v43, v59
	v_mov_b32_e32 v44, v60
	v_mov_b32_e32 v45, v61
	v_mov_b32_e32 v30, v70
	v_mov_b32_e32 v31, v71
	v_mov_b32_e32 v32, v72
	v_mov_b32_e32 v33, v73
	v_mov_b32_e32 v26, v62
	v_mov_b32_e32 v27, v63
	v_mov_b32_e32 v28, v64
	v_mov_b32_e32 v29, v65
	v_mov_b32_e32 v14, v50
	v_mov_b32_e32 v15, v51
	v_mov_b32_e32 v16, v52
	v_mov_b32_e32 v17, v53
	v_mov_b32_e32 v10, v46
	v_mov_b32_e32 v11, v47
	v_mov_b32_e32 v12, v48
	v_mov_b32_e32 v13, v49
	s_cbranch_scc0 .LBB0_219
; #define GAS __attribute__((address_space(1)))
; __device__ __forceinline__ void modulate_phase(Frame& F, const float* x, bf16* H, const float* gnorm, const float* modsub) {
;     ...
;     for (int r = rbeg; r < rend; ++r) {
;         { const GAS f32x4* xn = (const GAS f32x4*)(x + (size_t)min(r + 1, rend - 1) * D) + F.lane;
; #pragma unroll
;           for (int j = 0; j < 8; ++j) nv[j] = xn[64 * j]; }
;         const int b = r >> 12;
;         if (b != curb) { curb = b;
; #pragma unroll
;             for (int j = 0; j < 8; ++j) { const int c = 4 * F.lane + 256 * j;
;                 const f32x4 g = *(const GAS f32x4*)(gnorm + c), sc = *(const GAS f32x4*)(modsub + (size_t)b * NMOD + D + c);
;                 gs[j] = g * (sc + 1.0f); sh[j] = *(const GAS f32x4*)(modsub + (size_t)b * NMOD + c); } }
.LBB0_217:
	s_mov_b32 s7, s6
	s_add_i32 s6, s6, 1
	s_min_i32 s12, s6, s16
	s_ashr_i32 s13, s12, 31
	s_lshl_b64 s[12:13], s[12:13], 13
	s_add_u32 s12, s0, s12
	s_addc_u32 s13, s1, s13
	v_lshlrev_b32_e32 v0, 4, v130
	v_lshl_add_u64 v[46:47], s[12:13], 0, v[0:1]
	v_add_co_u32_e32 v46, vcc, 0x1000, v46
	global_load_dwordx4 v[82:85], v0, s[12:13]
	global_load_dwordx4 v[74:77], v0, s[12:13] offset:1024
	global_load_dwordx4 v[66:69], v0, s[12:13] offset:2048
	global_load_dwordx4 v[58:61], v0, s[12:13] offset:3072
	v_addc_co_u32_e32 v47, vcc, 0, v47, vcc
	global_load_dwordx4 v[70:73], v[46:47], off
	global_load_dwordx4 v[62:65], v[46:47], off offset:1024
	global_load_dwordx4 v[50:53], v[46:47], off offset:2048
	s_nop 0
	global_load_dwordx4 v[46:49], v[46:47], off offset:3072
	s_ashr_i32 s7, s7, 12
	s_cmp_eq_u32 s7, s10
	s_cbranch_scc1 .LBB0_216
	s_mul_i32 s10, s7, 0x12000
	s_mul_hi_i32 s11, s7, 0x12000
	s_add_u32 s10, s14, s10
	s_addc_u32 s11, s15, s11
	s_add_u32 s12, s10, 0x2000
	s_addc_u32 s13, s11, 0
	global_load_dwordx4 v[2:5], v[132:133], off
	global_load_dwordx4 v[6:9], v131, s[12:13]
	s_waitcnt vmcnt(0)
	v_add_f32_e32 v8, 1.0, v8
	v_add_f32_e32 v9, 1.0, v9
	v_add_f32_e32 v6, 1.0, v6
	v_add_f32_e32 v7, 1.0, v7
	v_mul_f32_e32 v4, v4, v8
	v_mul_f32_e32 v5, v5, v9
	v_mul_f32_e32 v2, v2, v6
	v_mul_f32_e32 v3, v3, v7
	global_load_dwordx4 v[6:9], v131, s[10:11]
	global_load_dwordx4 v[18:21], v[132:133], off offset:1024
	global_load_dwordx4 v[22:25], v142, s[12:13]
	s_waitcnt vmcnt(0)
	v_add_f32_e32 v24, 1.0, v24
	v_add_f32_e32 v25, 1.0, v25
	v_add_f32_e32 v22, 1.0, v22
	v_add_f32_e32 v23, 1.0, v23
	v_mul_f32_e32 v24, v20, v24
	v_mul_f32_e32 v25, v21, v25
	v_mul_f32_e32 v22, v18, v22
	v_mul_f32_e32 v23, v19, v23
	global_load_dwordx4 v[18:21], v131, s[10:11] offset:1024
	global_load_dwordx4 v[34:37], v[132:133], off offset:2048
	global_load_dwordx4 v[38:41], v143, s[12:13]
	s_waitcnt vmcnt(0)
	v_add_f32_e32 v40, 1.0, v40
	v_add_f32_e32 v41, 1.0, v41
	v_add_f32_e32 v38, 1.0, v38
	v_add_f32_e32 v39, 1.0, v39
	v_mul_f32_e32 v40, v36, v40
	v_mul_f32_e32 v41, v37, v41
	v_mul_f32_e32 v38, v34, v38
	v_mul_f32_e32 v39, v35, v39
	global_load_dwordx4 v[34:37], v131, s[10:11] offset:2048
	global_load_dwordx4 v[78:81], v[132:133], off offset:3072
	global_load_dwordx4 v[86:89], v144, s[12:13]
	s_waitcnt vmcnt(0)
	v_add_f32_e32 v88, 1.0, v88
	v_add_f32_e32 v89, 1.0, v89
	v_add_f32_e32 v86, 1.0, v86
	v_add_f32_e32 v87, 1.0, v87
	v_mul_f32_e32 v88, v80, v88
	v_mul_f32_e32 v89, v81, v89
	v_mul_f32_e32 v86, v78, v86
	v_mul_f32_e32 v87, v79, v87
	global_load_dwordx4 v[78:81], v131, s[10:11] offset:3072
	global_load_dwordx4 v[98:101], v[134:135], off
	global_load_dwordx4 v[102:105], v145, s[12:13]
	s_waitcnt vmcnt(0)
	v_add_f32_e32 v104, 1.0, v104
	v_add_f32_e32 v105, 1.0, v105
	v_add_f32_e32 v102, 1.0, v102
	v_add_f32_e32 v103, 1.0, v103
	v_mul_f32_e32 v104, v100, v104
	v_mul_f32_e32 v105, v101, v105
	v_mul_f32_e32 v102, v98, v102
	v_mul_f32_e32 v103, v99, v103
	global_load_dwordx4 v[98:101], v145, s[10:11]
	global_load_dwordx4 v[106:109], v[136:137], off
	global_load_dwordx4 v[110:113], v146, s[12:13]
	s_waitcnt vmcnt(0)
	v_add_f32_e32 v112, 1.0, v112
	v_add_f32_e32 v113, 1.0, v113
	v_add_f32_e32 v110, 1.0, v110
	v_add_f32_e32 v111, 1.0, v111
	v_mul_f32_e32 v112, v108, v112
	v_mul_f32_e32 v113, v109, v113
	v_mul_f32_e32 v110, v106, v110
	v_mul_f32_e32 v111, v107, v111
	global_load_dwordx4 v[106:109], v146, s[10:11]
	global_load_dwordx4 v[114:117], v[138:139], off
	global_load_dwordx4 v[118:121], v147, s[12:13]
	s_waitcnt vmcnt(0)
	v_add_f32_e32 v120, 1.0, v120
	v_add_f32_e32 v121, 1.0, v121
	v_add_f32_e32 v118, 1.0, v118
	v_add_f32_e32 v119, 1.0, v119
	v_mul_f32_e32 v120, v116, v120
	v_mul_f32_e32 v121, v117, v121
	v_mul_f32_e32 v118, v114, v118
	v_mul_f32_e32 v119, v115, v119
	global_load_dwordx4 v[114:117], v147, s[10:11]
	global_load_dwordx4 v[122:125], v[140:141], off
	global_load_dwordx4 v[126:129], v148, s[12:13]
	s_waitcnt vmcnt(0)
	v_add_f32_e32 v128, 1.0, v128
	v_add_f32_e32 v129, 1.0, v129
	v_add_f32_e32 v126, 1.0, v126
	v_add_f32_e32 v127, 1.0, v127
	v_mul_f32_e32 v124, v124, v128
	v_mul_f32_e32 v125, v125, v129
	v_mul_f32_e32 v122, v122, v126
	v_mul_f32_e32 v123, v123, v127
	global_load_dwordx4 v[126:129], v148, s[10:11]
	s_waitcnt vmcnt(0)
	s_mov_b32 s10, s7
	s_branch .LBB0_216

; #define GAS __attribute__((address_space(1)))
; __device__ __forceinline__ unsigned pk2(float lo, float hi) { return f2bf(lo) | (f2bf(hi) << 16); }
; template <int X> __device__ __forceinline__ float swz(float v) { return __builtin_bit_cast(float, __builtin_amdgcn_ds_swizzle(__builtin_bit_cast(int, v), (X << 10) | 0x1f)); }
; __device__ __forceinline__ float xsum32(float v) { const SwapPair r = swap32(v); return __builtin_bit_cast(float, r.a) + __builtin_bit_cast(float, r.b); }
; __device__ __forceinline__ float wave_sum(float v) {
;     v += swz<1>(v); v += swz<2>(v); v += swz<4>(v); v += swz<8>(v); v += swz<16>(v);
;     return xsum32(v);
; }
; __device__ __forceinline__ void modulate_phase(Frame& F, const float* x, bf16* H, const float* gnorm, const float* modsub) {
;     ...
;         float s = 0.f;
; #pragma unroll
;         for (int j = 0; j < 8; ++j) s += (v[j].x * v[j].x + v[j].y * v[j].y) + (v[j].z * v[j].z + v[j].w * v[j].w);
;         const float rstd = 1.0f / sqrtf(wave_sum(s) * (1.0f / D) + RMS_EPS);
;         GAS unsigned long long* o8 = (GAS unsigned long long*)(H + (size_t)r * D) + F.lane;
; #pragma unroll
;         for (int j = 0; j < 8; ++j) { const f32x4 y = v[j] * rstd * gs[j] + sh[j];
;             o8[64 * j] = (unsigned long long)pk2(y.x, y.y) | ((unsigned long long)pk2(y.z, y.w) << 32); }
.LBB0_418:
	s_waitcnt vmcnt(8)
	v_mul_f32_e32 v0, v95, v95
	v_mul_f32_e32 v155, v97, v97
	v_fmac_f32_e32 v0, v94, v94
	v_fmac_f32_e32 v155, v96, v96
	v_add_f32_e32 v0, v0, v155
	v_mul_f32_e32 v155, v83, v83
	v_mul_f32_e32 v156, v85, v85
	v_fmac_f32_e32 v155, v82, v82
	v_fmac_f32_e32 v156, v84, v84
	v_add_f32_e32 v155, v155, v156
	v_add_f32_e32 v0, v0, v155
	v_mul_f32_e32 v155, v47, v47
	v_mul_f32_e32 v156, v49, v49
	v_fmac_f32_e32 v155, v46, v46
	v_fmac_f32_e32 v156, v48, v48
	v_add_f32_e32 v155, v155, v156
	v_add_f32_e32 v0, v155, v0
	v_mul_f32_e32 v155, v35, v35
	v_mul_f32_e32 v156, v37, v37
	v_fmac_f32_e32 v155, v34, v34
	v_fmac_f32_e32 v156, v36, v36
	v_add_f32_e32 v155, v155, v156
	v_add_f32_e32 v0, v155, v0
	v_mul_f32_e32 v155, v31, v31
	v_mul_f32_e32 v156, v33, v33
	v_fmac_f32_e32 v155, v30, v30
	v_fmac_f32_e32 v156, v32, v32
	v_add_f32_e32 v155, v155, v156
	v_add_f32_e32 v0, v155, v0
	v_mul_f32_e32 v155, v19, v19
	v_mul_f32_e32 v156, v21, v21
	v_fmac_f32_e32 v155, v18, v18
	v_fmac_f32_e32 v156, v20, v20
	v_add_f32_e32 v155, v155, v156
	v_add_f32_e32 v0, v155, v0
	v_mul_f32_e32 v155, v15, v15
	v_mul_f32_e32 v156, v17, v17
	v_fmac_f32_e32 v155, v14, v14
	v_fmac_f32_e32 v156, v16, v16
	v_add_f32_e32 v155, v155, v156
	v_add_f32_e32 v0, v155, v0
	v_mul_f32_e32 v155, v3, v3
	v_mul_f32_e32 v156, v5, v5
	v_fmac_f32_e32 v155, v2, v2
	v_fmac_f32_e32 v156, v4, v4
	v_add_f32_e32 v155, v155, v156
	v_add_f32_e32 v0, v155, v0
	ds_swizzle_b32 v155, v0 offset:swizzle(SWAP,1)
	s_waitcnt lgkmcnt(0)
	v_add_f32_e32 v0, v0, v155
	ds_swizzle_b32 v155, v0 offset:swizzle(SWAP,2)
	s_waitcnt lgkmcnt(0)
	v_add_f32_e32 v0, v0, v155
	ds_swizzle_b32 v155, v0 offset:swizzle(SWAP,4)
	s_waitcnt lgkmcnt(0)
	v_add_f32_e32 v0, v0, v155
	ds_swizzle_b32 v155, v0 offset:swizzle(SWAP,8)
	s_waitcnt lgkmcnt(0)
	v_add_f32_e32 v0, v0, v155
	ds_swizzle_b32 v155, v0 offset:swizzle(SWAP,16)
	s_waitcnt lgkmcnt(0)
	v_add_f32_e32 v0, v0, v155
	v_mov_b32_e32 v155, v0
	s_nop 1
	v_permlane32_swap_b32_e32 v0, v155
	v_add_f32_e32 v0, v0, v155
	v_fmamk_f32 v0, v0, 0x3a000000, v202
	v_mul_f32_e32 v155, 0x4f800000, v0
	v_cmp_gt_f32_e32 vcc, s60, v0
	s_nop 1
	v_cndmask_b32_e32 v0, v0, v155, vcc
	v_sqrt_f32_e32 v155, v0
	s_nop 0
	v_add_u32_e32 v156, -1, v155
	v_fma_f32 v157, -v156, v155, v0
	v_cmp_ge_f32_e64 s[38:39], 0, v157
	v_add_u32_e32 v157, 1, v155
	s_nop 0
	v_cndmask_b32_e64 v156, v155, v156, s[38:39]
	v_fma_f32 v155, -v157, v155, v0
	v_cmp_lt_f32_e64 s[38:39], 0, v155
	s_nop 1
	v_cndmask_b32_e64 v155, v156, v157, s[38:39]
	v_mul_f32_e32 v156, 0x37800000, v155
	v_cndmask_b32_e32 v155, v155, v156, vcc
	v_cmp_class_f32_e32 vcc, v0, v203
	s_nop 1
	v_cndmask_b32_e32 v0, v155, v0, vcc
	v_div_scale_f32 v155, s[10:11], v0, v0, 1.0
	v_rcp_f32_e32 v156, v155
	s_nop 0
	v_fma_f32 v157, -v155, v156, 1.0
	v_fmac_f32_e32 v156, v157, v156
	v_div_scale_f32 v157, vcc, 1.0, v0, 1.0
	v_mul_f32_e32 v158, v157, v156
	v_fma_f32 v159, -v155, v158, v157
	v_fmac_f32_e32 v158, v159, v156
	v_fma_f32 v155, -v155, v158, v157
	v_div_fmas_f32 v155, v155, v156, v158
	v_div_fixup_f32 v0, v155, v0, 1.0
	v_mul_f32_e32 v94, v94, v0
	v_mul_f32_e32 v95, v95, v0
	v_mul_f32_e32 v96, v96, v0
	v_mul_f32_e32 v97, v97, v0
	v_fma_f32 v94, v6, v94, v10
	v_fma_f32 v95, v7, v95, v11
	v_fma_f32 v96, v8, v96, v12
	v_fma_f32 v97, v9, v97, v13
	v_bfe_u32 v156, v94, 16, 1
	v_add3_u32 v94, v94, v156, s94
	v_bfe_u32 v156, v95, 16, 1
	v_lshrrev_b32_e32 v94, 16, v94
	v_add3_u32 v95, v95, v156, s94
	v_and_or_b32 v94, v95, s95, v94
	v_bfe_u32 v95, v96, 16, 1
	v_add3_u32 v95, v96, v95, s94
	v_bfe_u32 v96, v97, 16, 1
	v_lshrrev_b32_e32 v95, 16, v95
	v_add3_u32 v96, v97, v96, s94
	v_mul_f32_e32 v82, v82, v0
	v_mul_f32_e32 v83, v83, v0
	v_lshlrev_b32_e32 v155, 3, v130
	v_and_or_b32 v95, v96, s95, v95
	v_fma_f32 v82, v26, v82, v22
	v_fma_f32 v83, v27, v83, v23
	global_store_dwordx2 v155, v[94:95], s[6:7]
	v_bfe_u32 v94, v82, 16, 1
	v_mul_f32_e32 v84, v84, v0
	v_mul_f32_e32 v85, v85, v0
	v_add3_u32 v82, v82, v94, s94
	v_bfe_u32 v94, v83, 16, 1
	v_fma_f32 v84, v28, v84, v24
	v_fma_f32 v85, v29, v85, v25
	v_lshrrev_b32_e32 v82, 16, v82
	v_add3_u32 v83, v83, v94, s94
	v_and_or_b32 v82, v83, s95, v82
	v_bfe_u32 v83, v84, 16, 1
	v_add3_u32 v83, v84, v83, s94
	v_bfe_u32 v84, v85, 16, 1
	v_lshrrev_b32_e32 v83, 16, v83
	v_add3_u32 v84, v85, v84, s94
	v_mul_f32_e32 v46, v46, v0
	v_mul_f32_e32 v47, v47, v0
	v_and_or_b32 v83, v84, s95, v83
	v_fma_f32 v46, v42, v46, v38
	v_fma_f32 v47, v43, v47, v39
	global_store_dwordx2 v155, v[82:83], s[6:7] offset:512
	v_bfe_u32 v82, v46, 16, 1
	v_mul_f32_e32 v48, v48, v0
	v_mul_f32_e32 v49, v49, v0
	v_add3_u32 v46, v46, v82, s94
	v_bfe_u32 v82, v47, 16, 1
	v_fma_f32 v48, v44, v48, v40
	v_fma_f32 v49, v45, v49, v41
	v_lshrrev_b32_e32 v46, 16, v46
	v_add3_u32 v47, v47, v82, s94
	v_and_or_b32 v46, v47, s95, v46
	v_bfe_u32 v47, v48, 16, 1
	v_add3_u32 v47, v48, v47, s94
	v_bfe_u32 v48, v49, 16, 1
	v_lshrrev_b32_e32 v47, 16, v47
	v_add3_u32 v48, v49, v48, s94
	v_mul_f32_e32 v34, v34, v0
	v_mul_f32_e32 v35, v35, v0
	v_and_or_b32 v47, v48, s95, v47
	v_fma_f32 v34, v90, v34, v78
	v_fma_f32 v35, v91, v35, v79
	global_store_dwordx2 v155, v[46:47], s[6:7] offset:1024
	v_bfe_u32 v46, v34, 16, 1
	v_mul_f32_e32 v36, v36, v0
	v_mul_f32_e32 v37, v37, v0
	v_add3_u32 v34, v34, v46, s94
	v_bfe_u32 v46, v35, 16, 1
	v_fma_f32 v36, v92, v36, v80
	v_fma_f32 v37, v93, v37, v81
	v_lshrrev_b32_e32 v34, 16, v34
	v_add3_u32 v35, v35, v46, s94
	v_and_or_b32 v34, v35, s95, v34
	v_bfe_u32 v35, v36, 16, 1
	v_add3_u32 v35, v36, v35, s94
	v_bfe_u32 v36, v37, 16, 1
	v_lshrrev_b32_e32 v35, 16, v35
	v_add3_u32 v36, v37, v36, s94
	v_mul_f32_e32 v30, v30, v0
; #define GAS __attribute__((address_space(1)))
; __device__ __forceinline__ unsigned pk2(float lo, float hi) { return f2bf(lo) | (f2bf(hi) << 16); }
; __device__ __forceinline__ void modulate_phase(Frame& F, const float* x, bf16* H, const float* gnorm, const float* modsub) {
;     ...
;         GAS unsigned long long* o8 = (GAS unsigned long long*)(H + (size_t)r * D) + F.lane;
; #pragma unroll
;         for (int j = 0; j < 8; ++j) { const f32x4 y = v[j] * rstd * gs[j] + sh[j];
;             o8[64 * j] = (unsigned long long)pk2(y.x, y.y) | ((unsigned long long)pk2(y.z, y.w) << 32); }
; #pragma unroll
;         for (int j = 0; j < 8; ++j) v[j] = nv[j];
	v_mul_f32_e32 v31, v31, v0
	v_and_or_b32 v35, v36, s95, v35
	v_fma_f32 v30, v102, v30, v98
	v_fma_f32 v31, v103, v31, v99
	global_store_dwordx2 v155, v[34:35], s[6:7] offset:1536
	v_bfe_u32 v34, v30, 16, 1
	v_mul_f32_e32 v32, v32, v0
	v_mul_f32_e32 v33, v33, v0
	v_add3_u32 v30, v30, v34, s94
	v_bfe_u32 v34, v31, 16, 1
	v_fma_f32 v32, v104, v32, v100
	v_fma_f32 v33, v105, v33, v101
	v_lshrrev_b32_e32 v30, 16, v30
	v_add3_u32 v31, v31, v34, s94
	v_and_or_b32 v30, v31, s95, v30
	v_bfe_u32 v31, v32, 16, 1
	v_add3_u32 v31, v32, v31, s94
	v_bfe_u32 v32, v33, 16, 1
	v_lshrrev_b32_e32 v31, 16, v31
	v_add3_u32 v32, v33, v32, s94
	v_mul_f32_e32 v18, v18, v0
	v_mul_f32_e32 v19, v19, v0
	v_and_or_b32 v31, v32, s95, v31
	v_fma_f32 v18, v110, v18, v106
	v_fma_f32 v19, v111, v19, v107
	global_store_dwordx2 v155, v[30:31], s[6:7] offset:2048
	v_bfe_u32 v30, v18, 16, 1
	v_mul_f32_e32 v20, v20, v0
	v_mul_f32_e32 v21, v21, v0
	v_add3_u32 v18, v18, v30, s94
	v_bfe_u32 v30, v19, 16, 1
	v_fma_f32 v20, v112, v20, v108
	v_fma_f32 v21, v113, v21, v109
	v_lshrrev_b32_e32 v18, 16, v18
	v_add3_u32 v19, v19, v30, s94
	v_and_or_b32 v18, v19, s95, v18
	v_bfe_u32 v19, v20, 16, 1
	v_add3_u32 v19, v20, v19, s94
	v_bfe_u32 v20, v21, 16, 1
	v_lshrrev_b32_e32 v19, 16, v19
	v_add3_u32 v20, v21, v20, s94
	v_mul_f32_e32 v14, v14, v0
	v_mul_f32_e32 v15, v15, v0
	v_mul_f32_e32 v2, v2, v0
	v_mul_f32_e32 v3, v3, v0
	v_and_or_b32 v19, v20, s95, v19
	v_fma_f32 v14, v118, v14, v114
	v_fma_f32 v15, v119, v15, v115
	v_fma_f32 v2, v122, v2, v126
	v_fma_f32 v3, v123, v3, v127
	global_store_dwordx2 v155, v[18:19], s[6:7] offset:2560
	v_mul_f32_e32 v16, v16, v0
	v_mul_f32_e32 v17, v17, v0
	v_bfe_u32 v18, v14, 16, 1
	v_mul_f32_e32 v4, v4, v0
	v_mul_f32_e32 v5, v5, v0
	v_bfe_u32 v0, v2, 16, 1
	v_add3_u32 v14, v14, v18, s94
	v_bfe_u32 v18, v15, 16, 1
	v_add3_u32 v0, v2, v0, s94
	v_bfe_u32 v2, v3, 16, 1
	v_fma_f32 v16, v120, v16, v116
	v_fma_f32 v17, v121, v17, v117
	v_lshrrev_b32_e32 v14, 16, v14
	v_add3_u32 v15, v15, v18, s94
	v_fma_f32 v4, v124, v4, v128
	v_fma_f32 v5, v125, v5, v129
	v_lshrrev_b32_e32 v0, 16, v0
	v_add3_u32 v2, v3, v2, s94
	v_and_or_b32 v14, v15, s95, v14
	v_bfe_u32 v15, v16, 16, 1
	v_and_or_b32 v2, v2, s95, v0
	v_bfe_u32 v0, v4, 16, 1
	v_add3_u32 v15, v16, v15, s94
	v_bfe_u32 v16, v17, 16, 1
	v_add3_u32 v0, v4, v0, s94
	v_bfe_u32 v3, v5, 16, 1
	v_lshrrev_b32_e32 v15, 16, v15
	v_add3_u32 v16, v17, v16, s94
	v_lshrrev_b32_e32 v0, 16, v0
	v_add3_u32 v3, v5, v3, s94
	v_and_or_b32 v15, v16, s95, v15
	v_and_or_b32 v3, v3, s95, v0
	global_store_dwordx2 v155, v[14:15], s[6:7] offset:3072
	global_store_dwordx2 v155, v[2:3], s[6:7] offset:3584
	s_add_u32 s6, s6, 0x1000
	s_addc_u32 s7, s7, 0
	s_cmp_lt_i32 s0, s2
	s_waitcnt vmcnt(8)
	v_mov_b32_e32 v94, v86
	v_mov_b32_e32 v95, v87
	v_mov_b32_e32 v96, v88
	v_mov_b32_e32 v97, v89
	v_mov_b32_e32 v82, v74
	v_mov_b32_e32 v83, v75
	v_mov_b32_e32 v84, v76
	v_mov_b32_e32 v85, v77
	v_mov_b32_e32 v46, v66
	v_mov_b32_e32 v47, v67
	v_mov_b32_e32 v48, v68
	v_mov_b32_e32 v49, v69
	v_mov_b32_e32 v34, v58
	v_mov_b32_e32 v35, v59
	v_mov_b32_e32 v36, v60
	v_mov_b32_e32 v37, v61
	v_mov_b32_e32 v30, v70
	v_mov_b32_e32 v31, v71
	v_mov_b32_e32 v32, v72
	v_mov_b32_e32 v33, v73
	v_mov_b32_e32 v18, v62
	v_mov_b32_e32 v19, v63
	v_mov_b32_e32 v20, v64
	v_mov_b32_e32 v21, v65
	v_mov_b32_e32 v14, v54
	v_mov_b32_e32 v15, v55
	v_mov_b32_e32 v16, v56
	v_mov_b32_e32 v17, v57
	v_mov_b32_e32 v2, v50
	v_mov_b32_e32 v3, v51
	v_mov_b32_e32 v4, v52
	v_mov_b32_e32 v5, v53
	s_cbranch_scc0 .LBB0_421
; #define GAS __attribute__((address_space(1)))
; __device__ __forceinline__ void modulate_phase(Frame& F, const float* x, bf16* H, const float* gnorm, const float* modsub) {
;     ...
;     for (int r = rbeg; r < rend; ++r) {
;         { const GAS f32x4* xn = (const GAS f32x4*)(x + (size_t)min(r + 1, rend - 1) * D) + F.lane;
; #pragma unroll
;           for (int j = 0; j < 8; ++j) nv[j] = xn[64 * j]; }
;         const int b = r >> 12;
;         if (b != curb) { curb = b;
; #pragma unroll
;             for (int j = 0; j < 8; ++j) { const int c = 4 * F.lane + 256 * j;
;                 const f32x4 g = *(const GAS f32x4*)(gnorm + c), sc = *(const GAS f32x4*)(modsub + (size_t)b * NMOD + D + c);
;                 gs[j] = g * (sc + 1.0f); sh[j] = *(const GAS f32x4*)(modsub + (size_t)b * NMOD + c); } }
.LBB0_419:
	s_mov_b32 s1, s0
	s_add_i32 s0, s0, 1
	s_min_i32 s10, s0, s16
	s_ashr_i32 s11, s10, 31
	s_lshl_b64 s[10:11], s[10:11], 13
	s_add_u32 s10, s12, s10
	s_addc_u32 s11, s13, s11
	v_lshlrev_b32_e32 v0, 4, v130
	v_lshl_add_u64 v[50:51], s[10:11], 0, v[0:1]
	v_add_co_u32_e32 v50, vcc, 0x1000, v50
	global_load_dwordx4 v[86:89], v0, s[10:11]
	global_load_dwordx4 v[74:77], v0, s[10:11] offset:1024
	global_load_dwordx4 v[66:69], v0, s[10:11] offset:2048
	global_load_dwordx4 v[58:61], v0, s[10:11] offset:3072
	v_addc_co_u32_e32 v51, vcc, 0, v51, vcc
	global_load_dwordx4 v[70:73], v[50:51], off
	global_load_dwordx4 v[62:65], v[50:51], off offset:1024
	global_load_dwordx4 v[54:57], v[50:51], off offset:2048
	s_nop 0
	global_load_dwordx4 v[50:53], v[50:51], off offset:3072
	s_ashr_i32 s1, s1, 12
	s_cmp_eq_u32 s1, s8
	s_cbranch_scc1 .LBB0_418
	s_mul_i32 s8, s1, 0x12000
	s_mul_hi_i32 s9, s1, 0x12000
	s_add_u32 s8, s14, s8
	s_addc_u32 s9, s15, s9
	s_add_u32 s10, s8, 0x2000
	s_addc_u32 s11, s9, 0
	global_load_dwordx4 v[6:9], v[132:133], off
	global_load_dwordx4 v[10:13], v131, s[10:11]
	s_waitcnt vmcnt(0)
	v_add_f32_e32 v12, 1.0, v12
	v_add_f32_e32 v13, 1.0, v13
	v_add_f32_e32 v10, 1.0, v10
	v_add_f32_e32 v11, 1.0, v11
	v_mul_f32_e32 v8, v8, v12
	v_mul_f32_e32 v9, v9, v13
	v_mul_f32_e32 v6, v6, v10
	v_mul_f32_e32 v7, v7, v11
	global_load_dwordx4 v[10:13], v131, s[8:9]
	global_load_dwordx4 v[22:25], v[134:135], off
	global_load_dwordx4 v[26:29], v148, s[10:11]
	s_waitcnt vmcnt(0)
	v_add_f32_e32 v28, 1.0, v28
	v_add_f32_e32 v29, 1.0, v29
	v_add_f32_e32 v26, 1.0, v26
	v_add_f32_e32 v27, 1.0, v27
	v_mul_f32_e32 v28, v24, v28
	v_mul_f32_e32 v29, v25, v29
	v_mul_f32_e32 v26, v22, v26
	v_mul_f32_e32 v27, v23, v27
	global_load_dwordx4 v[22:25], v131, s[8:9] offset:1024
	global_load_dwordx4 v[38:41], v[136:137], off
	global_load_dwordx4 v[42:45], v149, s[10:11]
	s_waitcnt vmcnt(0)
	v_add_f32_e32 v44, 1.0, v44
	v_add_f32_e32 v45, 1.0, v45
	v_add_f32_e32 v42, 1.0, v42
	v_add_f32_e32 v43, 1.0, v43
	v_mul_f32_e32 v44, v40, v44
	v_mul_f32_e32 v45, v41, v45
	v_mul_f32_e32 v42, v38, v42
	v_mul_f32_e32 v43, v39, v43
	global_load_dwordx4 v[38:41], v131, s[8:9] offset:2048
	global_load_dwordx4 v[78:81], v[138:139], off
	global_load_dwordx4 v[90:93], v150, s[10:11]
	s_waitcnt vmcnt(0)
	v_add_f32_e32 v92, 1.0, v92
	v_add_f32_e32 v93, 1.0, v93
	v_add_f32_e32 v90, 1.0, v90
	v_add_f32_e32 v91, 1.0, v91
	v_mul_f32_e32 v92, v80, v92
	v_mul_f32_e32 v93, v81, v93
	v_mul_f32_e32 v90, v78, v90
	v_mul_f32_e32 v91, v79, v91
	global_load_dwordx4 v[78:81], v131, s[8:9] offset:3072
	global_load_dwordx4 v[98:101], v[140:141], off
	global_load_dwordx4 v[102:105], v151, s[10:11]
	s_waitcnt vmcnt(0)
	v_add_f32_e32 v104, 1.0, v104
	v_add_f32_e32 v105, 1.0, v105
	v_add_f32_e32 v102, 1.0, v102
	v_add_f32_e32 v103, 1.0, v103
	v_mul_f32_e32 v104, v100, v104
	v_mul_f32_e32 v105, v101, v105
	v_mul_f32_e32 v102, v98, v102
	v_mul_f32_e32 v103, v99, v103
	global_load_dwordx4 v[98:101], v151, s[8:9]
	global_load_dwordx4 v[106:109], v[142:143], off
	global_load_dwordx4 v[110:113], v152, s[10:11]
	s_waitcnt vmcnt(0)
	v_add_f32_e32 v112, 1.0, v112
	v_add_f32_e32 v113, 1.0, v113
	v_add_f32_e32 v110, 1.0, v110
	v_add_f32_e32 v111, 1.0, v111
	v_mul_f32_e32 v112, v108, v112
	v_mul_f32_e32 v113, v109, v113
	v_mul_f32_e32 v110, v106, v110
	v_mul_f32_e32 v111, v107, v111
	global_load_dwordx4 v[106:109], v152, s[8:9]
	global_load_dwordx4 v[114:117], v[144:145], off
	global_load_dwordx4 v[118:121], v153, s[10:11]
	s_waitcnt vmcnt(0)
	v_add_f32_e32 v120, 1.0, v120
	v_add_f32_e32 v121, 1.0, v121
	v_add_f32_e32 v118, 1.0, v118
	v_add_f32_e32 v119, 1.0, v119
	v_mul_f32_e32 v120, v116, v120
	v_mul_f32_e32 v121, v117, v121
	v_mul_f32_e32 v118, v114, v118
	v_mul_f32_e32 v119, v115, v119
	global_load_dwordx4 v[114:117], v153, s[8:9]
	global_load_dwordx4 v[122:125], v[146:147], off
	global_load_dwordx4 v[126:129], v154, s[10:11]
	s_waitcnt vmcnt(0)
	v_add_f32_e32 v128, 1.0, v128
	v_add_f32_e32 v129, 1.0, v129
	v_add_f32_e32 v126, 1.0, v126
	v_add_f32_e32 v127, 1.0, v127
	v_mul_f32_e32 v124, v124, v128
	v_mul_f32_e32 v125, v125, v129
	v_mul_f32_e32 v122, v122, v126
	v_mul_f32_e32 v123, v123, v127
	global_load_dwordx4 v[126:129], v154, s[8:9]
	s_waitcnt vmcnt(0)
	s_mov_b32 s8, s1
	s_branch .LBB0_418

; __device__ __forceinline__ unsigned cvt_pk_bf16(float lo, float hi) { const pk_f2_t v = {lo, hi}; return __builtin_bit_cast(unsigned, __builtin_convertvector(v, pk_bf2_t)); }
; __device__ __forceinline__ float sigmoid_f(float g) { return __builtin_amdgcn_rcpf(1.0f + __builtin_amdgcn_exp2f(-1.4426950408889634f * g)); }
;     __device__ __forceinline__ void operator()(const pg8::f32x4 (&acc)[2][2][4][2], const pg8::Unit& u, int wr, int wc, int fr, int fq) const {
;     ...
;                     pg8::f32x4 v0 = acc[ai][bj][m][0], v1 = acc[ai][bj][m][1];
;                     if (mode & 1) { v0 = (pg8::f32x4){sigmoid_f(v0[0]), sigmoid_f(v0[1]), sigmoid_f(v0[2]), sigmoid_f(v0[3])}; v1 = (pg8::f32x4){sigmoid_f(v1[0]), sigmoid_f(v1[1]), sigmoid_f(v1[2]), sigmoid_f(v1[3])}; }
;                     else { v0 = v0 * sc; v1 = v1 * sc; }
;                     const size_t ro = (size_t)(ai * 128 + m * 16) * rs;
;                     if (mode < 2) { pg8::u32x4 w; w.x = pg8::cvt_pk_bf16(v0[0], v0[1]); w.y = pg8::cvt_pk_bf16(v0[2], v0[3]); w.z = pg8::cvt_pk_bf16(v1[0], v1[1]); w.w = pg8::cvt_pk_bf16(v1[2], v1[3]);
;                         *(pg8::u32x4*)(d16 + ro) = w; }
;                     else { *(pg8::f32x4*)(d32 + ro) = v0; *(pg8::f32x4*)(d32 + ro + 4) = v1; }
.LBB0_520:
	s_or_saveexec_b64 s[50:51], s[50:51]
	v_mov_b32_e32 v177, v176
	s_xor_b64 exec, exec, s[50:51]
	v_mov_b32_e32 v134, v176
	v_mov_b32_e32 v135, v176
	v_mul_f32_e32 v132, v128, v134
	v_mul_f32_e32 v133, v129, v135
	v_mul_f32_e32 v130, v126, v176
	v_mul_f32_e32 v131, v127, v177
	v_mul_f32_e32 v136, v124, v134
	v_mul_f32_e32 v137, v125, v135
	v_mul_f32_e32 v134, v122, v176
	v_mul_f32_e32 v135, v123, v177
	s_or_b64 exec, exec, s[50:51]
	s_xor_b64 s[46:47], s[46:47], -1
	s_and_saveexec_b64 s[26:27], s[46:47]
	s_xor_b64 s[50:51], exec, s[26:27]
	s_cbranch_execz .LBB0_524
	flat_store_dwordx4 v[162:163], v[130:133]
	flat_store_dwordx4 v[162:163], v[134:137] offset:16

; __device__ __forceinline__ unsigned cvt_pk_bf16(float lo, float hi) { const pk_f2_t v = {lo, hi}; return __builtin_bit_cast(unsigned, __builtin_convertvector(v, pk_bf2_t)); }
; __device__ __forceinline__ float sigmoid_f(float g) { return __builtin_amdgcn_rcpf(1.0f + __builtin_amdgcn_exp2f(-1.4426950408889634f * g)); }
;     __device__ __forceinline__ void operator()(const pg8::f32x4 (&acc)[2][2][4][2], const pg8::Unit& u, int wr, int wc, int fr, int fq) const {
;     ...
;                     pg8::f32x4 v0 = acc[ai][bj][m][0], v1 = acc[ai][bj][m][1];
;                     if (mode & 1) { v0 = (pg8::f32x4){sigmoid_f(v0[0]), sigmoid_f(v0[1]), sigmoid_f(v0[2]), sigmoid_f(v0[3])}; v1 = (pg8::f32x4){sigmoid_f(v1[0]), sigmoid_f(v1[1]), sigmoid_f(v1[2]), sigmoid_f(v1[3])}; }
;                     else { v0 = v0 * sc; v1 = v1 * sc; }
;                     const size_t ro = (size_t)(ai * 128 + m * 16) * rs;
;                     if (mode < 2) { pg8::u32x4 w; w.x = pg8::cvt_pk_bf16(v0[0], v0[1]); w.y = pg8::cvt_pk_bf16(v0[2], v0[3]); w.z = pg8::cvt_pk_bf16(v1[0], v1[1]); w.w = pg8::cvt_pk_bf16(v1[2], v1[3]);
;                         *(pg8::u32x4*)(d16 + ro) = w; }
;                     else { *(pg8::f32x4*)(d32 + ro) = v0; *(pg8::f32x4*)(d32 + ro + 4) = v1; }
.LBB0_528:
	s_andn2_saveexec_b64 s[50:51], s[50:51]
	v_mov_b32_e32 v126, v176
	v_mov_b32_e32 v127, v176
	v_mul_f32_e32 v124, v120, v126
	v_mul_f32_e32 v125, v121, v127
	v_mul_f32_e32 v122, v118, v176
	v_mul_f32_e32 v123, v119, v177
	v_mul_f32_e32 v128, v116, v126
	v_mul_f32_e32 v129, v117, v127
	v_mul_f32_e32 v126, v114, v176
	v_mul_f32_e32 v127, v115, v177
	s_or_b64 exec, exec, s[50:51]
	v_lshlrev_b64 v[114:115], 4, v[166:167]
	s_and_saveexec_b64 s[26:27], s[46:47]
	s_xor_b64 s[50:51], exec, s[26:27]
	s_cbranch_execz .LBB0_532
	v_lshl_add_u64 v[114:115], v[114:115], 2, v[162:163]
	flat_store_dwordx4 v[114:115], v[122:125]
	flat_store_dwordx4 v[114:115], v[126:129] offset:16

; __device__ __forceinline__ unsigned cvt_pk_bf16(float lo, float hi) { const pk_f2_t v = {lo, hi}; return __builtin_bit_cast(unsigned, __builtin_convertvector(v, pk_bf2_t)); }
; __device__ __forceinline__ float sigmoid_f(float g) { return __builtin_amdgcn_rcpf(1.0f + __builtin_amdgcn_exp2f(-1.4426950408889634f * g)); }
;     __device__ __forceinline__ void operator()(const pg8::f32x4 (&acc)[2][2][4][2], const pg8::Unit& u, int wr, int wc, int fr, int fq) const {
;     ...
;                     pg8::f32x4 v0 = acc[ai][bj][m][0], v1 = acc[ai][bj][m][1];
;                     if (mode & 1) { v0 = (pg8::f32x4){sigmoid_f(v0[0]), sigmoid_f(v0[1]), sigmoid_f(v0[2]), sigmoid_f(v0[3])}; v1 = (pg8::f32x4){sigmoid_f(v1[0]), sigmoid_f(v1[1]), sigmoid_f(v1[2]), sigmoid_f(v1[3])}; }
;                     else { v0 = v0 * sc; v1 = v1 * sc; }
;                     const size_t ro = (size_t)(ai * 128 + m * 16) * rs;
;                     if (mode < 2) { pg8::u32x4 w; w.x = pg8::cvt_pk_bf16(v0[0], v0[1]); w.y = pg8::cvt_pk_bf16(v0[2], v0[3]); w.z = pg8::cvt_pk_bf16(v1[0], v1[1]); w.w = pg8::cvt_pk_bf16(v1[2], v1[3]);
;                         *(pg8::u32x4*)(d16 + ro) = w; }
;                     else { *(pg8::f32x4*)(d32 + ro) = v0; *(pg8::f32x4*)(d32 + ro + 4) = v1; }
.LBB0_536:
	s_andn2_saveexec_b64 s[50:51], s[50:51]
	v_mov_b32_e32 v118, v176
	v_mov_b32_e32 v119, v176
	v_mul_f32_e32 v116, v112, v118
	v_mul_f32_e32 v117, v113, v119
	v_mul_f32_e32 v114, v110, v176
	v_mul_f32_e32 v115, v111, v177
	v_mul_f32_e32 v120, v108, v118
	v_mul_f32_e32 v121, v109, v119
	v_mul_f32_e32 v118, v106, v176
	v_mul_f32_e32 v119, v107, v177
	s_or_b64 exec, exec, s[50:51]
	v_lshlrev_b64 v[106:107], 5, v[166:167]
	s_and_saveexec_b64 s[26:27], s[46:47]
	s_xor_b64 s[50:51], exec, s[26:27]
	s_cbranch_execz .LBB0_540
	v_lshl_add_u64 v[106:107], v[106:107], 2, v[162:163]
	flat_store_dwordx4 v[106:107], v[114:117]
	flat_store_dwordx4 v[106:107], v[118:121] offset:16

; __device__ __forceinline__ unsigned cvt_pk_bf16(float lo, float hi) { const pk_f2_t v = {lo, hi}; return __builtin_bit_cast(unsigned, __builtin_convertvector(v, pk_bf2_t)); }
; __device__ __forceinline__ float sigmoid_f(float g) { return __builtin_amdgcn_rcpf(1.0f + __builtin_amdgcn_exp2f(-1.4426950408889634f * g)); }
;     __device__ __forceinline__ void operator()(const pg8::f32x4 (&acc)[2][2][4][2], const pg8::Unit& u, int wr, int wc, int fr, int fq) const {
;     ...
;                     pg8::f32x4 v0 = acc[ai][bj][m][0], v1 = acc[ai][bj][m][1];
;                     if (mode & 1) { v0 = (pg8::f32x4){sigmoid_f(v0[0]), sigmoid_f(v0[1]), sigmoid_f(v0[2]), sigmoid_f(v0[3])}; v1 = (pg8::f32x4){sigmoid_f(v1[0]), sigmoid_f(v1[1]), sigmoid_f(v1[2]), sigmoid_f(v1[3])}; }
;                     else { v0 = v0 * sc; v1 = v1 * sc; }
;                     const size_t ro = (size_t)(ai * 128 + m * 16) * rs;
;                     if (mode < 2) { pg8::u32x4 w; w.x = pg8::cvt_pk_bf16(v0[0], v0[1]); w.y = pg8::cvt_pk_bf16(v0[2], v0[3]); w.z = pg8::cvt_pk_bf16(v1[0], v1[1]); w.w = pg8::cvt_pk_bf16(v1[2], v1[3]);
;                         *(pg8::u32x4*)(d16 + ro) = w; }
;                     else { *(pg8::f32x4*)(d32 + ro) = v0; *(pg8::f32x4*)(d32 + ro + 4) = v1; }
.LBB0_544:
	s_andn2_saveexec_b64 s[50:51], s[50:51]
	v_mov_b32_e32 v110, v176
	v_mov_b32_e32 v111, v176
	v_mul_f32_e32 v108, v104, v110
	v_mul_f32_e32 v109, v105, v111
	v_mul_f32_e32 v106, v102, v176
	v_mul_f32_e32 v107, v103, v177
	v_mul_f32_e32 v112, v100, v110
	v_mul_f32_e32 v113, v101, v111
	v_mul_f32_e32 v110, v98, v176
	v_mul_f32_e32 v111, v99, v177
	s_or_b64 exec, exec, s[50:51]
	v_mul_u32_u24_e32 v0, 48, v166
	s_and_saveexec_b64 s[26:27], s[46:47]
	s_xor_b64 s[50:51], exec, s[26:27]
	s_cbranch_execz .LBB0_548
	v_lshlrev_b32_e32 v0, 2, v0
	v_lshl_add_u64 v[98:99], v[162:163], 0, v[0:1]
	flat_store_dwordx4 v[98:99], v[106:109]
	flat_store_dwordx4 v[98:99], v[110:113] offset:16

; __device__ __forceinline__ unsigned cvt_pk_bf16(float lo, float hi) { const pk_f2_t v = {lo, hi}; return __builtin_bit_cast(unsigned, __builtin_convertvector(v, pk_bf2_t)); }
; __device__ __forceinline__ float sigmoid_f(float g) { return __builtin_amdgcn_rcpf(1.0f + __builtin_amdgcn_exp2f(-1.4426950408889634f * g)); }
;     __device__ __forceinline__ void operator()(const pg8::f32x4 (&acc)[2][2][4][2], const pg8::Unit& u, int wr, int wc, int fr, int fq) const {
;     ...
;                     pg8::f32x4 v0 = acc[ai][bj][m][0], v1 = acc[ai][bj][m][1];
;                     if (mode & 1) { v0 = (pg8::f32x4){sigmoid_f(v0[0]), sigmoid_f(v0[1]), sigmoid_f(v0[2]), sigmoid_f(v0[3])}; v1 = (pg8::f32x4){sigmoid_f(v1[0]), sigmoid_f(v1[1]), sigmoid_f(v1[2]), sigmoid_f(v1[3])}; }
;                     else { v0 = v0 * sc; v1 = v1 * sc; }
;                     const size_t ro = (size_t)(ai * 128 + m * 16) * rs;
;                     if (mode < 2) { pg8::u32x4 w; w.x = pg8::cvt_pk_bf16(v0[0], v0[1]); w.y = pg8::cvt_pk_bf16(v0[2], v0[3]); w.z = pg8::cvt_pk_bf16(v1[0], v1[1]); w.w = pg8::cvt_pk_bf16(v1[2], v1[3]);
;                         *(pg8::u32x4*)(d16 + ro) = w; }
;                     else { *(pg8::f32x4*)(d32 + ro) = v0; *(pg8::f32x4*)(d32 + ro + 4) = v1; }
.LBB0_552:
	s_andn2_saveexec_b64 s[50:51], s[50:51]
	v_mov_b32_e32 v102, v176
	v_mov_b32_e32 v103, v176
	v_mul_f32_e32 v100, v96, v102
	v_mul_f32_e32 v101, v97, v103
	v_mul_f32_e32 v98, v94, v176
	v_mul_f32_e32 v99, v95, v177
	v_mul_f32_e32 v104, v92, v102
	v_mul_f32_e32 v105, v93, v103
	v_mul_f32_e32 v102, v90, v176
	v_mul_f32_e32 v103, v91, v177
	s_or_b64 exec, exec, s[50:51]
	v_lshlrev_b64 v[90:91], 7, v[166:167]
	s_and_saveexec_b64 s[26:27], s[46:47]
	s_xor_b64 s[50:51], exec, s[26:27]
	s_cbranch_execz .LBB0_556
	v_lshl_add_u64 v[90:91], v[90:91], 2, v[162:163]
	flat_store_dwordx4 v[90:91], v[98:101]
	flat_store_dwordx4 v[90:91], v[102:105] offset:16

; __device__ __forceinline__ unsigned cvt_pk_bf16(float lo, float hi) { const pk_f2_t v = {lo, hi}; return __builtin_bit_cast(unsigned, __builtin_convertvector(v, pk_bf2_t)); }
; __device__ __forceinline__ float sigmoid_f(float g) { return __builtin_amdgcn_rcpf(1.0f + __builtin_amdgcn_exp2f(-1.4426950408889634f * g)); }
;     __device__ __forceinline__ void operator()(const pg8::f32x4 (&acc)[2][2][4][2], const pg8::Unit& u, int wr, int wc, int fr, int fq) const {
;     ...
;                     pg8::f32x4 v0 = acc[ai][bj][m][0], v1 = acc[ai][bj][m][1];
;                     if (mode & 1) { v0 = (pg8::f32x4){sigmoid_f(v0[0]), sigmoid_f(v0[1]), sigmoid_f(v0[2]), sigmoid_f(v0[3])}; v1 = (pg8::f32x4){sigmoid_f(v1[0]), sigmoid_f(v1[1]), sigmoid_f(v1[2]), sigmoid_f(v1[3])}; }
;                     else { v0 = v0 * sc; v1 = v1 * sc; }
;                     const size_t ro = (size_t)(ai * 128 + m * 16) * rs;
;                     if (mode < 2) { pg8::u32x4 w; w.x = pg8::cvt_pk_bf16(v0[0], v0[1]); w.y = pg8::cvt_pk_bf16(v0[2], v0[3]); w.z = pg8::cvt_pk_bf16(v1[0], v1[1]); w.w = pg8::cvt_pk_bf16(v1[2], v1[3]);
;                         *(pg8::u32x4*)(d16 + ro) = w; }
;                     else { *(pg8::f32x4*)(d32 + ro) = v0; *(pg8::f32x4*)(d32 + ro + 4) = v1; }
.LBB0_560:
	s_andn2_saveexec_b64 s[50:51], s[50:51]
	v_mov_b32_e32 v94, v176
	v_mov_b32_e32 v95, v176
	v_mul_f32_e32 v92, v88, v94
	v_mul_f32_e32 v93, v89, v95
	v_mul_f32_e32 v90, v86, v176
	v_mul_f32_e32 v91, v87, v177
	v_mul_f32_e32 v96, v84, v94
	v_mul_f32_e32 v97, v85, v95
	v_mul_f32_e32 v94, v82, v176
	v_mul_f32_e32 v95, v83, v177
	s_or_b64 exec, exec, s[50:51]
	v_mul_hi_u32_u24_e32 v83, 0x90, v166
	v_mul_u32_u24_e32 v82, 0x90, v166
	s_and_saveexec_b64 s[26:27], s[46:47]
	s_xor_b64 s[50:51], exec, s[26:27]
	s_cbranch_execz .LBB0_564
	v_lshl_add_u64 v[82:83], v[82:83], 2, v[162:163]
	flat_store_dwordx4 v[82:83], v[90:93]
	flat_store_dwordx4 v[82:83], v[94:97] offset:16

; __device__ __forceinline__ unsigned cvt_pk_bf16(float lo, float hi) { const pk_f2_t v = {lo, hi}; return __builtin_bit_cast(unsigned, __builtin_convertvector(v, pk_bf2_t)); }
; __device__ __forceinline__ float sigmoid_f(float g) { return __builtin_amdgcn_rcpf(1.0f + __builtin_amdgcn_exp2f(-1.4426950408889634f * g)); }
;     __device__ __forceinline__ void operator()(const pg8::f32x4 (&acc)[2][2][4][2], const pg8::Unit& u, int wr, int wc, int fr, int fq) const {
;     ...
;                     pg8::f32x4 v0 = acc[ai][bj][m][0], v1 = acc[ai][bj][m][1];
;                     if (mode & 1) { v0 = (pg8::f32x4){sigmoid_f(v0[0]), sigmoid_f(v0[1]), sigmoid_f(v0[2]), sigmoid_f(v0[3])}; v1 = (pg8::f32x4){sigmoid_f(v1[0]), sigmoid_f(v1[1]), sigmoid_f(v1[2]), sigmoid_f(v1[3])}; }
;                     else { v0 = v0 * sc; v1 = v1 * sc; }
;                     const size_t ro = (size_t)(ai * 128 + m * 16) * rs;
;                     if (mode < 2) { pg8::u32x4 w; w.x = pg8::cvt_pk_bf16(v0[0], v0[1]); w.y = pg8::cvt_pk_bf16(v0[2], v0[3]); w.z = pg8::cvt_pk_bf16(v1[0], v1[1]); w.w = pg8::cvt_pk_bf16(v1[2], v1[3]);
;                         *(pg8::u32x4*)(d16 + ro) = w; }
;                     else { *(pg8::f32x4*)(d32 + ro) = v0; *(pg8::f32x4*)(d32 + ro + 4) = v1; }
.LBB0_568:
	s_andn2_saveexec_b64 s[50:51], s[50:51]
	v_mov_b32_e32 v86, v176
	v_mov_b32_e32 v87, v176
	v_mul_f32_e32 v84, v80, v86
	v_mul_f32_e32 v85, v81, v87
	v_mul_f32_e32 v82, v78, v176
	v_mul_f32_e32 v83, v79, v177
	v_mul_f32_e32 v88, v76, v86
	v_mul_f32_e32 v89, v77, v87
	v_mul_f32_e32 v86, v74, v176
	v_mul_f32_e32 v87, v75, v177
	s_or_b64 exec, exec, s[50:51]
	v_mul_hi_u32_u24_e32 v75, 0xa0, v166
	v_mul_u32_u24_e32 v74, 0xa0, v166
	s_and_saveexec_b64 s[26:27], s[46:47]
	s_xor_b64 s[50:51], exec, s[26:27]
	s_cbranch_execz .LBB0_572
	v_lshl_add_u64 v[74:75], v[74:75], 2, v[162:163]
	flat_store_dwordx4 v[74:75], v[82:85]
	flat_store_dwordx4 v[74:75], v[86:89] offset:16

; __device__ __forceinline__ unsigned cvt_pk_bf16(float lo, float hi) { const pk_f2_t v = {lo, hi}; return __builtin_bit_cast(unsigned, __builtin_convertvector(v, pk_bf2_t)); }
; __device__ __forceinline__ float sigmoid_f(float g) { return __builtin_amdgcn_rcpf(1.0f + __builtin_amdgcn_exp2f(-1.4426950408889634f * g)); }
;     __device__ __forceinline__ void operator()(const pg8::f32x4 (&acc)[2][2][4][2], const pg8::Unit& u, int wr, int wc, int fr, int fq) const {
;     ...
;                     pg8::f32x4 v0 = acc[ai][bj][m][0], v1 = acc[ai][bj][m][1];
;                     if (mode & 1) { v0 = (pg8::f32x4){sigmoid_f(v0[0]), sigmoid_f(v0[1]), sigmoid_f(v0[2]), sigmoid_f(v0[3])}; v1 = (pg8::f32x4){sigmoid_f(v1[0]), sigmoid_f(v1[1]), sigmoid_f(v1[2]), sigmoid_f(v1[3])}; }
;                     else { v0 = v0 * sc; v1 = v1 * sc; }
;                     const size_t ro = (size_t)(ai * 128 + m * 16) * rs;
;                     if (mode < 2) { pg8::u32x4 w; w.x = pg8::cvt_pk_bf16(v0[0], v0[1]); w.y = pg8::cvt_pk_bf16(v0[2], v0[3]); w.z = pg8::cvt_pk_bf16(v1[0], v1[1]); w.w = pg8::cvt_pk_bf16(v1[2], v1[3]);
;                         *(pg8::u32x4*)(d16 + ro) = w; }
;                     else { *(pg8::f32x4*)(d32 + ro) = v0; *(pg8::f32x4*)(d32 + ro + 4) = v1; }
.LBB0_576:
	s_andn2_saveexec_b64 s[48:49], s[48:49]
	v_mov_b32_e32 v78, v176
	v_mov_b32_e32 v79, v176
	v_mul_f32_e32 v76, v72, v78
	v_mul_f32_e32 v77, v73, v79
	v_mul_f32_e32 v74, v70, v176
	v_mul_f32_e32 v75, v71, v177
	v_mul_f32_e32 v80, v68, v78
	v_mul_f32_e32 v81, v69, v79
	v_mul_f32_e32 v78, v66, v176
	v_mul_f32_e32 v79, v67, v177
	s_or_b64 exec, exec, s[48:49]
	v_mul_hi_u32_u24_e32 v67, 0xb0, v166
	v_mul_u32_u24_e32 v66, 0xb0, v166
	s_and_saveexec_b64 s[26:27], s[46:47]
	s_xor_b64 s[46:47], exec, s[26:27]
	s_cbranch_execz .LBB0_580
	v_lshl_add_u64 v[66:67], v[66:67], 2, v[162:163]
	flat_store_dwordx4 v[66:67], v[74:77]
	flat_store_dwordx4 v[66:67], v[78:81] offset:16

; __device__ __forceinline__ unsigned cvt_pk_bf16(float lo, float hi) { const pk_f2_t v = {lo, hi}; return __builtin_bit_cast(unsigned, __builtin_convertvector(v, pk_bf2_t)); }
; __device__ __forceinline__ float sigmoid_f(float g) { return __builtin_amdgcn_rcpf(1.0f + __builtin_amdgcn_exp2f(-1.4426950408889634f * g)); }
;     __device__ __forceinline__ void operator()(const pg8::f32x4 (&acc)[2][2][4][2], const pg8::Unit& u, int wr, int wc, int fr, int fq) const {
;     ...
;                     pg8::f32x4 v0 = acc[ai][bj][m][0], v1 = acc[ai][bj][m][1];
;                     if (mode & 1) { v0 = (pg8::f32x4){sigmoid_f(v0[0]), sigmoid_f(v0[1]), sigmoid_f(v0[2]), sigmoid_f(v0[3])}; v1 = (pg8::f32x4){sigmoid_f(v1[0]), sigmoid_f(v1[1]), sigmoid_f(v1[2]), sigmoid_f(v1[3])}; }
;                     else { v0 = v0 * sc; v1 = v1 * sc; }
;                     const size_t ro = (size_t)(ai * 128 + m * 16) * rs;
;                     if (mode < 2) { pg8::u32x4 w; w.x = pg8::cvt_pk_bf16(v0[0], v0[1]); w.y = pg8::cvt_pk_bf16(v0[2], v0[3]); w.z = pg8::cvt_pk_bf16(v1[0], v1[1]); w.w = pg8::cvt_pk_bf16(v1[2], v1[3]);
;                         *(pg8::u32x4*)(d16 + ro) = w; }
;                     else { *(pg8::f32x4*)(d32 + ro) = v0; *(pg8::f32x4*)(d32 + ro + 4) = v1; }
.LBB0_620:
	s_or_saveexec_b64 s[18:19], s[18:19]
	v_mov_b32_e32 v81, v80
	s_xor_b64 exec, exec, s[18:19]
	v_mov_b32_e32 v70, v80
	v_mov_b32_e32 v71, v80
	v_mul_f32_e32 v68, v64, v70
	v_mul_f32_e32 v69, v65, v71
	v_mul_f32_e32 v66, v62, v80
	v_mul_f32_e32 v67, v63, v81
	v_mul_f32_e32 v72, v60, v70
	v_mul_f32_e32 v73, v61, v71
	v_mul_f32_e32 v70, v58, v80
	v_mul_f32_e32 v71, v59, v81
	s_or_b64 exec, exec, s[18:19]
	s_xor_b64 s[18:19], s[36:37], -1
	s_and_saveexec_b64 s[26:27], s[18:19]
	s_xor_b64 s[36:37], exec, s[26:27]
	s_cbranch_execz .LBB0_624
	flat_store_dwordx4 v[74:75], v[66:69]
	flat_store_dwordx4 v[74:75], v[70:73] offset:16

; __device__ __forceinline__ unsigned cvt_pk_bf16(float lo, float hi) { const pk_f2_t v = {lo, hi}; return __builtin_bit_cast(unsigned, __builtin_convertvector(v, pk_bf2_t)); }
; __device__ __forceinline__ float sigmoid_f(float g) { return __builtin_amdgcn_rcpf(1.0f + __builtin_amdgcn_exp2f(-1.4426950408889634f * g)); }
;     __device__ __forceinline__ void operator()(const pg8::f32x4 (&acc)[2][2][4][2], const pg8::Unit& u, int wr, int wc, int fr, int fq) const {
;     ...
;                     pg8::f32x4 v0 = acc[ai][bj][m][0], v1 = acc[ai][bj][m][1];
;                     if (mode & 1) { v0 = (pg8::f32x4){sigmoid_f(v0[0]), sigmoid_f(v0[1]), sigmoid_f(v0[2]), sigmoid_f(v0[3])}; v1 = (pg8::f32x4){sigmoid_f(v1[0]), sigmoid_f(v1[1]), sigmoid_f(v1[2]), sigmoid_f(v1[3])}; }
;                     else { v0 = v0 * sc; v1 = v1 * sc; }
;                     const size_t ro = (size_t)(ai * 128 + m * 16) * rs;
;                     if (mode < 2) { pg8::u32x4 w; w.x = pg8::cvt_pk_bf16(v0[0], v0[1]); w.y = pg8::cvt_pk_bf16(v0[2], v0[3]); w.z = pg8::cvt_pk_bf16(v1[0], v1[1]); w.w = pg8::cvt_pk_bf16(v1[2], v1[3]);
;                         *(pg8::u32x4*)(d16 + ro) = w; }
;                     else { *(pg8::f32x4*)(d32 + ro) = v0; *(pg8::f32x4*)(d32 + ro + 4) = v1; }
.LBB0_628:
	s_andn2_saveexec_b64 s[36:37], s[36:37]
	v_mov_b32_e32 v62, v80
	v_mov_b32_e32 v63, v80
	v_mul_f32_e32 v60, v56, v62
	v_mul_f32_e32 v61, v57, v63
	v_mul_f32_e32 v58, v54, v80
	v_mul_f32_e32 v59, v55, v81
	v_mul_f32_e32 v64, v52, v62
	v_mul_f32_e32 v65, v53, v63
	v_mul_f32_e32 v62, v50, v80
	v_mul_f32_e32 v63, v51, v81
	s_or_b64 exec, exec, s[36:37]
	v_lshlrev_b64 v[50:51], 4, v[76:77]
	s_and_saveexec_b64 s[26:27], s[18:19]
	s_xor_b64 s[36:37], exec, s[26:27]
	s_cbranch_execz .LBB0_632
	v_lshl_add_u64 v[50:51], v[50:51], 2, v[74:75]
	flat_store_dwordx4 v[50:51], v[58:61]
	flat_store_dwordx4 v[50:51], v[62:65] offset:16

; __device__ __forceinline__ unsigned cvt_pk_bf16(float lo, float hi) { const pk_f2_t v = {lo, hi}; return __builtin_bit_cast(unsigned, __builtin_convertvector(v, pk_bf2_t)); }
; __device__ __forceinline__ float sigmoid_f(float g) { return __builtin_amdgcn_rcpf(1.0f + __builtin_amdgcn_exp2f(-1.4426950408889634f * g)); }
;     __device__ __forceinline__ void operator()(const pg8::f32x4 (&acc)[2][2][4][2], const pg8::Unit& u, int wr, int wc, int fr, int fq) const {
;     ...
;                     pg8::f32x4 v0 = acc[ai][bj][m][0], v1 = acc[ai][bj][m][1];
;                     if (mode & 1) { v0 = (pg8::f32x4){sigmoid_f(v0[0]), sigmoid_f(v0[1]), sigmoid_f(v0[2]), sigmoid_f(v0[3])}; v1 = (pg8::f32x4){sigmoid_f(v1[0]), sigmoid_f(v1[1]), sigmoid_f(v1[2]), sigmoid_f(v1[3])}; }
;                     else { v0 = v0 * sc; v1 = v1 * sc; }
;                     const size_t ro = (size_t)(ai * 128 + m * 16) * rs;
;                     if (mode < 2) { pg8::u32x4 w; w.x = pg8::cvt_pk_bf16(v0[0], v0[1]); w.y = pg8::cvt_pk_bf16(v0[2], v0[3]); w.z = pg8::cvt_pk_bf16(v1[0], v1[1]); w.w = pg8::cvt_pk_bf16(v1[2], v1[3]);
;                         *(pg8::u32x4*)(d16 + ro) = w; }
;                     else { *(pg8::f32x4*)(d32 + ro) = v0; *(pg8::f32x4*)(d32 + ro + 4) = v1; }
.LBB0_636:
	s_andn2_saveexec_b64 s[36:37], s[36:37]
	v_mov_b32_e32 v54, v80
	v_mov_b32_e32 v55, v80
	v_mul_f32_e32 v52, v48, v54
	v_mul_f32_e32 v53, v49, v55
	v_mul_f32_e32 v50, v46, v80
	v_mul_f32_e32 v51, v47, v81
	v_mul_f32_e32 v56, v44, v54
	v_mul_f32_e32 v57, v45, v55
	v_mul_f32_e32 v54, v42, v80
	v_mul_f32_e32 v55, v43, v81
	s_or_b64 exec, exec, s[36:37]
	v_lshlrev_b64 v[42:43], 5, v[76:77]
	s_and_saveexec_b64 s[26:27], s[18:19]
	s_xor_b64 s[36:37], exec, s[26:27]
	s_cbranch_execz .LBB0_640
	v_lshl_add_u64 v[42:43], v[42:43], 2, v[74:75]
	flat_store_dwordx4 v[42:43], v[50:53]
	flat_store_dwordx4 v[42:43], v[54:57] offset:16

; __device__ __forceinline__ unsigned cvt_pk_bf16(float lo, float hi) { const pk_f2_t v = {lo, hi}; return __builtin_bit_cast(unsigned, __builtin_convertvector(v, pk_bf2_t)); }
; __device__ __forceinline__ float sigmoid_f(float g) { return __builtin_amdgcn_rcpf(1.0f + __builtin_amdgcn_exp2f(-1.4426950408889634f * g)); }
;     __device__ __forceinline__ void operator()(const pg8::f32x4 (&acc)[2][2][4][2], const pg8::Unit& u, int wr, int wc, int fr, int fq) const {
;     ...
;                     pg8::f32x4 v0 = acc[ai][bj][m][0], v1 = acc[ai][bj][m][1];
;                     if (mode & 1) { v0 = (pg8::f32x4){sigmoid_f(v0[0]), sigmoid_f(v0[1]), sigmoid_f(v0[2]), sigmoid_f(v0[3])}; v1 = (pg8::f32x4){sigmoid_f(v1[0]), sigmoid_f(v1[1]), sigmoid_f(v1[2]), sigmoid_f(v1[3])}; }
;                     else { v0 = v0 * sc; v1 = v1 * sc; }
;                     const size_t ro = (size_t)(ai * 128 + m * 16) * rs;
;                     if (mode < 2) { pg8::u32x4 w; w.x = pg8::cvt_pk_bf16(v0[0], v0[1]); w.y = pg8::cvt_pk_bf16(v0[2], v0[3]); w.z = pg8::cvt_pk_bf16(v1[0], v1[1]); w.w = pg8::cvt_pk_bf16(v1[2], v1[3]);
;                         *(pg8::u32x4*)(d16 + ro) = w; }
;                     else { *(pg8::f32x4*)(d32 + ro) = v0; *(pg8::f32x4*)(d32 + ro + 4) = v1; }
.LBB0_644:
	s_andn2_saveexec_b64 s[36:37], s[36:37]
	v_mov_b32_e32 v46, v80
	v_mov_b32_e32 v47, v80
	v_mul_f32_e32 v44, v40, v46
	v_mul_f32_e32 v45, v41, v47
	v_mul_f32_e32 v42, v38, v80
	v_mul_f32_e32 v43, v39, v81
	v_mul_f32_e32 v48, v36, v46
	v_mul_f32_e32 v49, v37, v47
	v_mul_f32_e32 v46, v34, v80
	v_mul_f32_e32 v47, v35, v81
	s_or_b64 exec, exec, s[36:37]
	v_mul_u32_u24_e32 v0, 48, v76
	s_and_saveexec_b64 s[26:27], s[18:19]
	s_xor_b64 s[36:37], exec, s[26:27]
	s_cbranch_execz .LBB0_648
	v_lshlrev_b32_e32 v0, 2, v0
	v_lshl_add_u64 v[34:35], v[74:75], 0, v[0:1]
	flat_store_dwordx4 v[34:35], v[42:45]
	flat_store_dwordx4 v[34:35], v[46:49] offset:16

; __device__ __forceinline__ unsigned cvt_pk_bf16(float lo, float hi) { const pk_f2_t v = {lo, hi}; return __builtin_bit_cast(unsigned, __builtin_convertvector(v, pk_bf2_t)); }
; __device__ __forceinline__ float sigmoid_f(float g) { return __builtin_amdgcn_rcpf(1.0f + __builtin_amdgcn_exp2f(-1.4426950408889634f * g)); }
;     __device__ __forceinline__ void operator()(const pg8::f32x4 (&acc)[2][2][4][2], const pg8::Unit& u, int wr, int wc, int fr, int fq) const {
;     ...
;                     pg8::f32x4 v0 = acc[ai][bj][m][0], v1 = acc[ai][bj][m][1];
;                     if (mode & 1) { v0 = (pg8::f32x4){sigmoid_f(v0[0]), sigmoid_f(v0[1]), sigmoid_f(v0[2]), sigmoid_f(v0[3])}; v1 = (pg8::f32x4){sigmoid_f(v1[0]), sigmoid_f(v1[1]), sigmoid_f(v1[2]), sigmoid_f(v1[3])}; }
;                     else { v0 = v0 * sc; v1 = v1 * sc; }
;                     const size_t ro = (size_t)(ai * 128 + m * 16) * rs;
;                     if (mode < 2) { pg8::u32x4 w; w.x = pg8::cvt_pk_bf16(v0[0], v0[1]); w.y = pg8::cvt_pk_bf16(v0[2], v0[3]); w.z = pg8::cvt_pk_bf16(v1[0], v1[1]); w.w = pg8::cvt_pk_bf16(v1[2], v1[3]);
;                         *(pg8::u32x4*)(d16 + ro) = w; }
;                     else { *(pg8::f32x4*)(d32 + ro) = v0; *(pg8::f32x4*)(d32 + ro + 4) = v1; }
.LBB0_652:
	s_andn2_saveexec_b64 s[36:37], s[36:37]
	v_mov_b32_e32 v38, v80
	v_mov_b32_e32 v39, v80
	v_mul_f32_e32 v36, v32, v38
	v_mul_f32_e32 v37, v33, v39
	v_mul_f32_e32 v34, v30, v80
	v_mul_f32_e32 v35, v31, v81
	v_mul_f32_e32 v40, v28, v38
	v_mul_f32_e32 v41, v29, v39
	v_mul_f32_e32 v38, v26, v80
	v_mul_f32_e32 v39, v27, v81
	s_or_b64 exec, exec, s[36:37]
	v_lshlrev_b64 v[26:27], 7, v[76:77]
	s_and_saveexec_b64 s[26:27], s[18:19]
	s_xor_b64 s[36:37], exec, s[26:27]
	s_cbranch_execz .LBB0_656
	v_lshl_add_u64 v[26:27], v[26:27], 2, v[74:75]
	flat_store_dwordx4 v[26:27], v[34:37]
	flat_store_dwordx4 v[26:27], v[38:41] offset:16

; __device__ __forceinline__ unsigned cvt_pk_bf16(float lo, float hi) { const pk_f2_t v = {lo, hi}; return __builtin_bit_cast(unsigned, __builtin_convertvector(v, pk_bf2_t)); }
; __device__ __forceinline__ float sigmoid_f(float g) { return __builtin_amdgcn_rcpf(1.0f + __builtin_amdgcn_exp2f(-1.4426950408889634f * g)); }
;     __device__ __forceinline__ void operator()(const pg8::f32x4 (&acc)[2][2][4][2], const pg8::Unit& u, int wr, int wc, int fr, int fq) const {
;     ...
;                     pg8::f32x4 v0 = acc[ai][bj][m][0], v1 = acc[ai][bj][m][1];
;                     if (mode & 1) { v0 = (pg8::f32x4){sigmoid_f(v0[0]), sigmoid_f(v0[1]), sigmoid_f(v0[2]), sigmoid_f(v0[3])}; v1 = (pg8::f32x4){sigmoid_f(v1[0]), sigmoid_f(v1[1]), sigmoid_f(v1[2]), sigmoid_f(v1[3])}; }
;                     else { v0 = v0 * sc; v1 = v1 * sc; }
;                     const size_t ro = (size_t)(ai * 128 + m * 16) * rs;
;                     if (mode < 2) { pg8::u32x4 w; w.x = pg8::cvt_pk_bf16(v0[0], v0[1]); w.y = pg8::cvt_pk_bf16(v0[2], v0[3]); w.z = pg8::cvt_pk_bf16(v1[0], v1[1]); w.w = pg8::cvt_pk_bf16(v1[2], v1[3]);
;                         *(pg8::u32x4*)(d16 + ro) = w; }
;                     else { *(pg8::f32x4*)(d32 + ro) = v0; *(pg8::f32x4*)(d32 + ro + 4) = v1; }
.LBB0_660:
	s_andn2_saveexec_b64 s[36:37], s[36:37]
	v_mov_b32_e32 v30, v80
	v_mov_b32_e32 v31, v80
	v_mul_f32_e32 v28, v24, v30
	v_mul_f32_e32 v29, v25, v31
	v_mul_f32_e32 v26, v22, v80
	v_mul_f32_e32 v27, v23, v81
	v_mul_f32_e32 v32, v20, v30
	v_mul_f32_e32 v33, v21, v31
	v_mul_f32_e32 v30, v18, v80
	v_mul_f32_e32 v31, v19, v81
	s_or_b64 exec, exec, s[36:37]
	v_mul_hi_u32_u24_e32 v19, 0x90, v76
	v_mul_u32_u24_e32 v18, 0x90, v76
	s_and_saveexec_b64 s[26:27], s[18:19]
	s_xor_b64 s[36:37], exec, s[26:27]
	s_cbranch_execz .LBB0_664
	v_lshl_add_u64 v[18:19], v[18:19], 2, v[74:75]
	flat_store_dwordx4 v[18:19], v[26:29]
	flat_store_dwordx4 v[18:19], v[30:33] offset:16

; __device__ __forceinline__ unsigned cvt_pk_bf16(float lo, float hi) { const pk_f2_t v = {lo, hi}; return __builtin_bit_cast(unsigned, __builtin_convertvector(v, pk_bf2_t)); }
; __device__ __forceinline__ float sigmoid_f(float g) { return __builtin_amdgcn_rcpf(1.0f + __builtin_amdgcn_exp2f(-1.4426950408889634f * g)); }
;     __device__ __forceinline__ void operator()(const pg8::f32x4 (&acc)[2][2][4][2], const pg8::Unit& u, int wr, int wc, int fr, int fq) const {
;     ...
;                     pg8::f32x4 v0 = acc[ai][bj][m][0], v1 = acc[ai][bj][m][1];
;                     if (mode & 1) { v0 = (pg8::f32x4){sigmoid_f(v0[0]), sigmoid_f(v0[1]), sigmoid_f(v0[2]), sigmoid_f(v0[3])}; v1 = (pg8::f32x4){sigmoid_f(v1[0]), sigmoid_f(v1[1]), sigmoid_f(v1[2]), sigmoid_f(v1[3])}; }
;                     else { v0 = v0 * sc; v1 = v1 * sc; }
;                     const size_t ro = (size_t)(ai * 128 + m * 16) * rs;
;                     if (mode < 2) { pg8::u32x4 w; w.x = pg8::cvt_pk_bf16(v0[0], v0[1]); w.y = pg8::cvt_pk_bf16(v0[2], v0[3]); w.z = pg8::cvt_pk_bf16(v1[0], v1[1]); w.w = pg8::cvt_pk_bf16(v1[2], v1[3]);
;                         *(pg8::u32x4*)(d16 + ro) = w; }
;                     else { *(pg8::f32x4*)(d32 + ro) = v0; *(pg8::f32x4*)(d32 + ro + 4) = v1; }
.LBB0_668:
	s_andn2_saveexec_b64 s[36:37], s[36:37]
	v_mov_b32_e32 v22, v80
	v_mov_b32_e32 v23, v80
	v_mul_f32_e32 v20, v16, v22
	v_mul_f32_e32 v21, v17, v23
	v_mul_f32_e32 v18, v14, v80
	v_mul_f32_e32 v19, v15, v81
	v_mul_f32_e32 v24, v12, v22
	v_mul_f32_e32 v25, v13, v23
	v_mul_f32_e32 v22, v10, v80
	v_mul_f32_e32 v23, v11, v81
	s_or_b64 exec, exec, s[36:37]
	v_mul_hi_u32_u24_e32 v11, 0xa0, v76
	v_mul_u32_u24_e32 v10, 0xa0, v76
	s_and_saveexec_b64 s[26:27], s[18:19]
	s_xor_b64 s[36:37], exec, s[26:27]
	s_cbranch_execz .LBB0_672
	v_lshl_add_u64 v[10:11], v[10:11], 2, v[74:75]
	flat_store_dwordx4 v[10:11], v[18:21]
	flat_store_dwordx4 v[10:11], v[22:25] offset:16

; __device__ __forceinline__ unsigned cvt_pk_bf16(float lo, float hi) { const pk_f2_t v = {lo, hi}; return __builtin_bit_cast(unsigned, __builtin_convertvector(v, pk_bf2_t)); }
; __device__ __forceinline__ float sigmoid_f(float g) { return __builtin_amdgcn_rcpf(1.0f + __builtin_amdgcn_exp2f(-1.4426950408889634f * g)); }
;     __device__ __forceinline__ void operator()(const pg8::f32x4 (&acc)[2][2][4][2], const pg8::Unit& u, int wr, int wc, int fr, int fq) const {
;     ...
;                     pg8::f32x4 v0 = acc[ai][bj][m][0], v1 = acc[ai][bj][m][1];
;                     if (mode & 1) { v0 = (pg8::f32x4){sigmoid_f(v0[0]), sigmoid_f(v0[1]), sigmoid_f(v0[2]), sigmoid_f(v0[3])}; v1 = (pg8::f32x4){sigmoid_f(v1[0]), sigmoid_f(v1[1]), sigmoid_f(v1[2]), sigmoid_f(v1[3])}; }
;                     else { v0 = v0 * sc; v1 = v1 * sc; }
;                     const size_t ro = (size_t)(ai * 128 + m * 16) * rs;
;                     if (mode < 2) { pg8::u32x4 w; w.x = pg8::cvt_pk_bf16(v0[0], v0[1]); w.y = pg8::cvt_pk_bf16(v0[2], v0[3]); w.z = pg8::cvt_pk_bf16(v1[0], v1[1]); w.w = pg8::cvt_pk_bf16(v1[2], v1[3]);
;                         *(pg8::u32x4*)(d16 + ro) = w; }
;                     else { *(pg8::f32x4*)(d32 + ro) = v0; *(pg8::f32x4*)(d32 + ro + 4) = v1; }
.LBB0_676:
	s_andn2_saveexec_b64 s[20:21], s[20:21]
	v_mov_b32_e32 v14, v80
	v_mov_b32_e32 v15, v80
	v_mul_f32_e32 v12, v8, v14
	v_mul_f32_e32 v13, v9, v15
	v_mul_f32_e32 v10, v6, v80
	v_mul_f32_e32 v11, v7, v81
	v_mul_f32_e32 v16, v4, v14
	v_mul_f32_e32 v17, v5, v15
	v_mul_f32_e32 v14, v2, v80
	v_mul_f32_e32 v15, v3, v81
	s_or_b64 exec, exec, s[20:21]
	v_mul_hi_u32_u24_e32 v3, 0xb0, v76
	v_mul_u32_u24_e32 v2, 0xb0, v76
	s_and_saveexec_b64 s[20:21], s[18:19]
	s_xor_b64 s[18:19], exec, s[20:21]
	s_cbranch_execz .LBB0_680
	v_lshl_add_u64 v[2:3], v[2:3], 2, v[74:75]
	flat_store_dwordx4 v[2:3], v[10:13]
	flat_store_dwordx4 v[2:3], v[14:17] offset:16

; __device__ __forceinline__ unsigned cvt_pk_bf16(float lo, float hi) { const pk_f2_t v = {lo, hi}; return __builtin_bit_cast(unsigned, __builtin_convertvector(v, pk_bf2_t)); }
; __device__ __forceinline__ float silu_f(float g) { return g * __builtin_amdgcn_rcpf(1.0f + __builtin_amdgcn_exp2f(-1.4426950408889634f * g)); }
;     __device__ __forceinline__ void operator()(const pg8::f32x4 (&acc)[2][2][4][2], const pg8::Unit& u, int wr, int wc, int fr, int fq) const {
;     ...
;         for (int bj = 0; bj < 2; ++bj) {
;             const int col0 = bj * 128 + wc * 32 + 8 * fq;
;             const pg8::f32x4 bA = *(const pg8::f32x4*)(b1 + u.pn * 256 + col0), bB = *(const pg8::f32x4*)(b1 + u.pn * 256 + col0 + 4);
; #pragma unroll
;             for (int ai = 0; ai < 2; ++ai)
; #pragma unroll
;                 for (int m = 0; m < 4; ++m) {
;                     const pg8::f32x4 v0 = acc[ai][bj][m][0] + bA, v1 = acc[ai][bj][m][1] + bB;
;                     pg8::u32x4 w; w.x = pg8::cvt_pk_bf16(silu_f(v0[0]), silu_f(v0[1])); w.y = pg8::cvt_pk_bf16(silu_f(v0[2]), silu_f(v0[3]));
;                     w.z = pg8::cvt_pk_bf16(silu_f(v1[0]), silu_f(v1[1])); w.w = pg8::cvt_pk_bf16(silu_f(v1[2]), silu_f(v1[3]));
;                     *(pg8::u32x4*)(O + (size_t)(row0 + ai * 128 + m * 16) * 256 + col0) = w;
.LBB0_750:
	s_lshl_b32 s16, s26, 8
	s_ashr_i32 s17, s16, 31
	v_lshl_add_u64 v[152:153], s[16:17], 2, v[144:145]
	flat_load_dwordx4 v[102:105], v[152:153]
	flat_load_dwordx4 v[98:101], v[152:153] offset:16
	v_lshl_add_u32 v154, s27, 8, v156
	v_ashrrev_i32_e32 v155, 31, v154
	s_mov_b32 s16, 0x10000
	s_waitcnt vmcnt(0) lgkmcnt(0)
	v_add_f32_e32 v134, v134, v102
	v_add_f32_e32 v135, v135, v103
	v_add_f32_e32 v160, v132, v100
	v_add_f32_e32 v161, v133, v101
	v_mul_f32_e32 v132, 0xbfb8aa3b, v134
	v_mul_f32_e32 v133, 0xbfb8aa3b, v135
	v_exp_f32_e32 v132, v132
	v_exp_f32_e32 v133, v133
	v_add_f32_e32 v136, v136, v104
	v_add_f32_e32 v137, v137, v105
	v_add_f32_e32 v130, v130, v98
	v_add_f32_e32 v131, v131, v99
	v_add_f32_e32 v132, 1.0, v132
	v_add_f32_e32 v133, 1.0, v133
	v_rcp_f32_e32 v132, v132
	v_rcp_f32_e32 v133, v133
	v_add_f32_e32 v128, v128, v104
	v_add_f32_e32 v129, v129, v105
	v_add_f32_e32 v118, v118, v102
	v_add_f32_e32 v119, v119, v103
	v_add_f32_e32 v120, v120, v104
	v_add_f32_e32 v121, v121, v105
	v_mul_f32_e32 v132, v134, v132
	v_mul_f32_e32 v133, v135, v133
	v_add_f32_e32 v114, v114, v98
	v_add_f32_e32 v115, v115, v99
	v_cvt_pk_bf16_f32 v132, v132, v133
	v_mul_f32_e32 v133, 0xbfb8aa3b, v136
	v_exp_f32_e32 v133, v133
	v_add_f32_e32 v110, v110, v102
	v_add_f32_e32 v111, v111, v103
	v_add_f32_e32 v112, v112, v104
	v_add_f32_e32 v113, v113, v105
	v_add_f32_e32 v106, v106, v98
	v_add_f32_e32 v107, v107, v99
	v_add_f32_e32 v133, 1.0, v133
	v_rcp_f32_e32 v134, v133
	v_mul_f32_e32 v133, 0xbfb8aa3b, v137
	v_exp_f32_e32 v133, v133
	v_add_f32_e32 v94, v94, v102
	v_add_f32_e32 v95, v95, v103
	v_add_f32_e32 v96, v96, v104
	v_add_f32_e32 v97, v97, v105
	v_add_f32_e32 v90, v90, v98
	v_add_f32_e32 v91, v91, v99
	v_add_f32_e32 v133, 1.0, v133
	v_rcp_f32_e32 v135, v133
	v_add_f32_e32 v86, v86, v102
	v_add_f32_e32 v87, v87, v103
	v_add_f32_e32 v88, v88, v104
	v_add_f32_e32 v89, v89, v105
	v_add_f32_e32 v82, v82, v98
	v_add_f32_e32 v83, v83, v99
	v_mul_f32_e32 v134, v136, v134
	v_mul_f32_e32 v135, v137, v135
	v_add_f32_e32 v78, v78, v102
	v_add_f32_e32 v79, v79, v103
	v_cvt_pk_bf16_f32 v133, v134, v135
	v_mul_f32_e32 v134, 0xbfb8aa3b, v130
	v_mul_f32_e32 v135, 0xbfb8aa3b, v131
	v_exp_f32_e32 v134, v134
	v_exp_f32_e32 v135, v135
	v_add_f32_e32 v80, v80, v104
	v_add_f32_e32 v81, v81, v105
	v_add_f32_e32 v74, v74, v98
	v_add_f32_e32 v75, v75, v99
	v_add_f32_e32 v134, 1.0, v134
	v_add_f32_e32 v135, 1.0, v135
	v_rcp_f32_e32 v134, v134
	v_rcp_f32_e32 v135, v135
	v_add_f32_e32 v70, v70, v102
	v_add_f32_e32 v71, v71, v103
	v_add_f32_e32 v72, v72, v104
	v_add_f32_e32 v73, v73, v105
	v_mul_f32_e32 v130, v130, v134
	v_mul_f32_e32 v131, v131, v135
	s_nop 0
	v_cvt_pk_bf16_f32 v134, v130, v131
	v_mul_f32_e32 v130, 0xbfb8aa3b, v160
	v_mul_f32_e32 v131, 0xbfb8aa3b, v161
	v_exp_f32_e32 v130, v130
	v_exp_f32_e32 v131, v131
	v_add_f32_e32 v130, 1.0, v130
	v_add_f32_e32 v131, 1.0, v131
	v_rcp_f32_e32 v130, v130
	v_rcp_f32_e32 v131, v131
	s_nop 0
	v_mul_f32_e32 v130, v160, v130
	v_mul_f32_e32 v131, v161, v131
	s_nop 0
	v_cvt_pk_bf16_f32 v135, v130, v131
	v_lshlrev_b64 v[130:131], 9, v[154:155]
	v_lshl_add_u64 v[130:131], v[146:147], 0, v[130:131]
	flat_store_dwordx4 v[130:131], v[132:135]
	s_nop 1
	v_add_f32_e32 v132, v126, v102
	v_add_f32_e32 v133, v127, v103
	v_add_f32_e32 v126, v124, v100
	v_add_f32_e32 v127, v125, v101
	v_add_f32_e32 v124, v122, v98
	v_add_f32_e32 v125, v123, v99
	v_mul_f32_e32 v122, 0xbfb8aa3b, v132
	v_mul_f32_e32 v123, 0xbfb8aa3b, v133
	v_exp_f32_e32 v122, v122
	v_exp_f32_e32 v123, v123
	v_add_f32_e32 v122, 1.0, v122
	v_add_f32_e32 v123, 1.0, v123
	v_rcp_f32_e32 v122, v122
	v_rcp_f32_e32 v123, v123
	s_nop 0
	v_mul_f32_e32 v122, v132, v122
	v_mul_f32_e32 v123, v133, v123
	s_nop 0
	v_cvt_pk_bf16_f32 v122, v122, v123
	v_mul_f32_e32 v123, 0xbfb8aa3b, v128
	v_exp_f32_e32 v123, v123
	s_nop 0
	v_add_f32_e32 v123, 1.0, v123
	v_rcp_f32_e32 v132, v123
	v_mul_f32_e32 v123, 0xbfb8aa3b, v129
	v_exp_f32_e32 v123, v123
	s_nop 0
	v_add_f32_e32 v123, 1.0, v123
	v_rcp_f32_e32 v133, v123
	s_nop 0
	v_mul_f32_e32 v128, v128, v132
	v_mul_f32_e32 v129, v129, v133
	s_nop 0
	v_cvt_pk_bf16_f32 v123, v128, v129
	v_mul_f32_e32 v128, 0xbfb8aa3b, v124
	v_mul_f32_e32 v129, 0xbfb8aa3b, v125
	v_exp_f32_e32 v128, v128
	v_exp_f32_e32 v129, v129
	v_add_f32_e32 v128, 1.0, v128
	v_add_f32_e32 v129, 1.0, v129
	v_rcp_f32_e32 v128, v128
	v_rcp_f32_e32 v129, v129
	s_nop 0
	v_mul_f32_e32 v124, v124, v128
	v_mul_f32_e32 v125, v125, v129
	s_nop 0
	v_cvt_pk_bf16_f32 v124, v124, v125
	v_mul_f32_e32 v125, 0xbfb8aa3b, v126
	v_exp_f32_e32 v125, v125
	s_nop 0
	v_add_f32_e32 v125, 1.0, v125
	v_rcp_f32_e32 v128, v125
	v_mul_f32_e32 v125, 0xbfb8aa3b, v127
	v_exp_f32_e32 v125, v125
	s_nop 0
	v_add_f32_e32 v125, 1.0, v125
	v_rcp_f32_e32 v129, v125
	s_nop 0
	v_mul_f32_e32 v126, v126, v128
	v_mul_f32_e32 v127, v127, v129
	s_nop 0
	v_cvt_pk_bf16_f32 v125, v126, v127
	v_or_b32_e32 v126, 16, v154
	v_ashrrev_i32_e32 v127, 31, v126
	v_lshlrev_b64 v[126:127], 9, v[126:127]
	v_lshl_add_u64 v[126:127], v[146:147], 0, v[126:127]
	flat_store_dwordx4 v[126:127], v[122:125]
	s_nop 1
	v_add_f32_e32 v122, v116, v100
	v_add_f32_e32 v123, v117, v101
	v_mul_f32_e32 v116, 0xbfb8aa3b, v118
	v_mul_f32_e32 v117, 0xbfb8aa3b, v119
	v_exp_f32_e32 v116, v116
	v_exp_f32_e32 v117, v117
	v_add_f32_e32 v116, 1.0, v116
	v_add_f32_e32 v117, 1.0, v117
	v_rcp_f32_e32 v116, v116
	v_rcp_f32_e32 v117, v117
	s_nop 0
	v_mul_f32_e32 v116, v118, v116
	v_mul_f32_e32 v117, v119, v117
	s_nop 0
	v_cvt_pk_bf16_f32 v116, v116, v117
	v_mul_f32_e32 v117, 0xbfb8aa3b, v120
	v_exp_f32_e32 v117, v117
	s_nop 0
	v_add_f32_e32 v117, 1.0, v117
; __device__ __forceinline__ unsigned cvt_pk_bf16(float lo, float hi) { const pk_f2_t v = {lo, hi}; return __builtin_bit_cast(unsigned, __builtin_convertvector(v, pk_bf2_t)); }
; __device__ __forceinline__ float silu_f(float g) { return g * __builtin_amdgcn_rcpf(1.0f + __builtin_amdgcn_exp2f(-1.4426950408889634f * g)); }
;     __device__ __forceinline__ void operator()(const pg8::f32x4 (&acc)[2][2][4][2], const pg8::Unit& u, int wr, int wc, int fr, int fq) const {
;     ...
;                 for (int m = 0; m < 4; ++m) {
;                     const pg8::f32x4 v0 = acc[ai][bj][m][0] + bA, v1 = acc[ai][bj][m][1] + bB;
;                     pg8::u32x4 w; w.x = pg8::cvt_pk_bf16(silu_f(v0[0]), silu_f(v0[1])); w.y = pg8::cvt_pk_bf16(silu_f(v0[2]), silu_f(v0[3]));
;                     w.z = pg8::cvt_pk_bf16(silu_f(v1[0]), silu_f(v1[1])); w.w = pg8::cvt_pk_bf16(silu_f(v1[2]), silu_f(v1[3]));
;                     *(pg8::u32x4*)(O + (size_t)(row0 + ai * 128 + m * 16) * 256 + col0) = w;
;                     asm volatile("" ::: "memory");
	v_rcp_f32_e32 v118, v117
	v_mul_f32_e32 v117, 0xbfb8aa3b, v121
	v_exp_f32_e32 v117, v117
	s_nop 0
	v_add_f32_e32 v117, 1.0, v117
	v_rcp_f32_e32 v119, v117
	s_nop 0
	v_mul_f32_e32 v118, v120, v118
	v_mul_f32_e32 v119, v121, v119
	s_nop 0
	v_cvt_pk_bf16_f32 v117, v118, v119
	v_mul_f32_e32 v118, 0xbfb8aa3b, v114
	v_mul_f32_e32 v119, 0xbfb8aa3b, v115
	v_exp_f32_e32 v118, v118
	v_exp_f32_e32 v119, v119
	v_add_f32_e32 v118, 1.0, v118
	v_add_f32_e32 v119, 1.0, v119
	v_rcp_f32_e32 v118, v118
	v_rcp_f32_e32 v119, v119
	s_nop 0
	v_mul_f32_e32 v114, v114, v118
	v_mul_f32_e32 v115, v115, v119
	s_nop 0
	v_cvt_pk_bf16_f32 v118, v114, v115
	v_mul_f32_e32 v114, 0xbfb8aa3b, v122
	v_mul_f32_e32 v115, 0xbfb8aa3b, v123
	v_exp_f32_e32 v114, v114
	v_exp_f32_e32 v115, v115
	v_add_f32_e32 v114, 1.0, v114
	v_add_f32_e32 v115, 1.0, v115
	v_rcp_f32_e32 v114, v114
	v_rcp_f32_e32 v115, v115
	s_nop 0
	v_mul_f32_e32 v114, v122, v114
	v_mul_f32_e32 v115, v123, v115
	s_nop 0
	v_cvt_pk_bf16_f32 v119, v114, v115
	v_or_b32_e32 v114, 32, v154
	v_ashrrev_i32_e32 v115, 31, v114
	v_lshlrev_b64 v[114:115], 9, v[114:115]
	v_lshl_add_u64 v[114:115], v[146:147], 0, v[114:115]
	flat_store_dwordx4 v[114:115], v[116:119]
	s_nop 1
	v_add_f32_e32 v116, v108, v100
	v_add_f32_e32 v117, v109, v101
	v_mul_f32_e32 v108, 0xbfb8aa3b, v110
	v_mul_f32_e32 v109, 0xbfb8aa3b, v111
	v_exp_f32_e32 v108, v108
	v_exp_f32_e32 v109, v109
	v_add_f32_e32 v108, 1.0, v108
	v_add_f32_e32 v109, 1.0, v109
	v_rcp_f32_e32 v108, v108
	v_rcp_f32_e32 v109, v109
	s_nop 0
	v_mul_f32_e32 v108, v110, v108
	v_mul_f32_e32 v109, v111, v109
	s_nop 0
	v_cvt_pk_bf16_f32 v108, v108, v109
	v_mul_f32_e32 v109, 0xbfb8aa3b, v112
	v_exp_f32_e32 v109, v109
	s_nop 0
	v_add_f32_e32 v109, 1.0, v109
	v_rcp_f32_e32 v110, v109
	v_mul_f32_e32 v109, 0xbfb8aa3b, v113
	v_exp_f32_e32 v109, v109
	s_nop 0
	v_add_f32_e32 v109, 1.0, v109
	v_rcp_f32_e32 v111, v109
	s_nop 0
	v_mul_f32_e32 v110, v112, v110
	v_mul_f32_e32 v111, v113, v111
	s_nop 0
	v_cvt_pk_bf16_f32 v109, v110, v111
	v_mul_f32_e32 v110, 0xbfb8aa3b, v106
	v_mul_f32_e32 v111, 0xbfb8aa3b, v107
	v_exp_f32_e32 v110, v110
	v_exp_f32_e32 v111, v111
	v_add_f32_e32 v110, 1.0, v110
	v_add_f32_e32 v111, 1.0, v111
	v_rcp_f32_e32 v110, v110
	v_rcp_f32_e32 v111, v111
	s_nop 0
	v_mul_f32_e32 v106, v106, v110
	v_mul_f32_e32 v107, v107, v111
	s_nop 0
	v_cvt_pk_bf16_f32 v110, v106, v107
	v_mul_f32_e32 v106, 0xbfb8aa3b, v116
	v_mul_f32_e32 v107, 0xbfb8aa3b, v117
	v_exp_f32_e32 v106, v106
	v_exp_f32_e32 v107, v107
	v_add_f32_e32 v106, 1.0, v106
	v_add_f32_e32 v107, 1.0, v107
	v_rcp_f32_e32 v106, v106
	v_rcp_f32_e32 v107, v107
	s_nop 0
	v_mul_f32_e32 v106, v116, v106
	v_mul_f32_e32 v107, v117, v107
	s_nop 0
	v_cvt_pk_bf16_f32 v111, v106, v107
	v_or_b32_e32 v106, 48, v154
	v_ashrrev_i32_e32 v107, 31, v106
	v_lshlrev_b64 v[106:107], 9, v[106:107]
	v_lshl_add_u64 v[106:107], v[146:147], 0, v[106:107]
	flat_store_dwordx4 v[106:107], v[108:111]
	s_nop 1
	v_add_f32_e32 v108, v92, v100
	v_add_f32_e32 v109, v93, v101
	v_mul_f32_e32 v92, 0xbfb8aa3b, v94
	v_mul_f32_e32 v93, 0xbfb8aa3b, v95
	v_exp_f32_e32 v92, v92
	v_exp_f32_e32 v93, v93
	v_add_f32_e32 v92, 1.0, v92
	v_add_f32_e32 v93, 1.0, v93
	v_rcp_f32_e32 v92, v92
	v_rcp_f32_e32 v93, v93
	s_nop 0
	v_mul_f32_e32 v92, v94, v92
	v_mul_f32_e32 v93, v95, v93
	s_nop 0
	v_cvt_pk_bf16_f32 v92, v92, v93
	v_mul_f32_e32 v93, 0xbfb8aa3b, v96
	v_exp_f32_e32 v93, v93
	s_nop 0
	v_add_f32_e32 v93, 1.0, v93
	v_rcp_f32_e32 v94, v93
	v_mul_f32_e32 v93, 0xbfb8aa3b, v97
	v_exp_f32_e32 v93, v93
	s_nop 0
	v_add_f32_e32 v93, 1.0, v93
	v_rcp_f32_e32 v95, v93
	s_nop 0
	v_mul_f32_e32 v94, v96, v94
	v_mul_f32_e32 v95, v97, v95
	s_nop 0
	v_cvt_pk_bf16_f32 v93, v94, v95
	v_mul_f32_e32 v94, 0xbfb8aa3b, v90
	v_mul_f32_e32 v95, 0xbfb8aa3b, v91
	v_exp_f32_e32 v94, v94
	v_exp_f32_e32 v95, v95
	v_add_co_u32_e32 v96, vcc, s16, v130
	v_add_f32_e32 v94, 1.0, v94
	v_add_f32_e32 v95, 1.0, v95
	v_rcp_f32_e32 v94, v94
	v_rcp_f32_e32 v95, v95
	v_addc_co_u32_e32 v97, vcc, 0, v131, vcc
	s_mov_b64 s[16:17], 0x12000
	v_mul_f32_e32 v90, v90, v94
	v_mul_f32_e32 v91, v91, v95
	s_nop 0
	v_cvt_pk_bf16_f32 v94, v90, v91
	v_mul_f32_e32 v90, 0xbfb8aa3b, v108
	v_mul_f32_e32 v91, 0xbfb8aa3b, v109
	v_exp_f32_e32 v90, v90
	v_exp_f32_e32 v91, v91
	v_add_f32_e32 v90, 1.0, v90
	v_add_f32_e32 v91, 1.0, v91
	v_rcp_f32_e32 v90, v90
	v_rcp_f32_e32 v91, v91
	s_nop 0
	v_mul_f32_e32 v90, v108, v90
	v_mul_f32_e32 v91, v109, v91
	s_nop 0
	v_cvt_pk_bf16_f32 v95, v90, v91
	flat_store_dwordx4 v[96:97], v[92:95]
	v_lshl_add_u64 v[90:91], v[130:131], 0, s[68:69]
	s_nop 0
	v_add_f32_e32 v92, v84, v100
	v_add_f32_e32 v93, v85, v101
	v_mul_f32_e32 v84, 0xbfb8aa3b, v86
	v_mul_f32_e32 v85, 0xbfb8aa3b, v87
	v_exp_f32_e32 v84, v84
	v_exp_f32_e32 v85, v85
	v_add_f32_e32 v84, 1.0, v84
	v_add_f32_e32 v85, 1.0, v85
	v_rcp_f32_e32 v84, v84
	v_rcp_f32_e32 v85, v85
	s_nop 0
	v_mul_f32_e32 v84, v86, v84
	v_mul_f32_e32 v85, v87, v85
	s_nop 0
	v_cvt_pk_bf16_f32 v84, v84, v85
	v_mul_f32_e32 v85, 0xbfb8aa3b, v88
	v_exp_f32_e32 v85, v85
	s_nop 0
	v_add_f32_e32 v85, 1.0, v85
	v_rcp_f32_e32 v86, v85
	v_mul_f32_e32 v85, 0xbfb8aa3b, v89
	v_exp_f32_e32 v85, v85
	s_nop 0
	v_add_f32_e32 v85, 1.0, v85
	v_rcp_f32_e32 v87, v85
	s_nop 0
	v_mul_f32_e32 v86, v88, v86
	v_mul_f32_e32 v87, v89, v87
	s_nop 0
	v_cvt_pk_bf16_f32 v85, v86, v87
	v_mul_f32_e32 v86, 0xbfb8aa3b, v82
	v_mul_f32_e32 v87, 0xbfb8aa3b, v83
	v_exp_f32_e32 v86, v86
	v_exp_f32_e32 v87, v87
	v_add_f32_e32 v86, 1.0, v86
	v_add_f32_e32 v87, 1.0, v87
	v_rcp_f32_e32 v86, v86
	v_rcp_f32_e32 v87, v87
	s_nop 0
	v_mul_f32_e32 v82, v82, v86
	v_mul_f32_e32 v83, v83, v87
	s_nop 0
	v_cvt_pk_bf16_f32 v86, v82, v83
; __device__ __forceinline__ unsigned cvt_pk_bf16(float lo, float hi) { const pk_f2_t v = {lo, hi}; return __builtin_bit_cast(unsigned, __builtin_convertvector(v, pk_bf2_t)); }
; __device__ __forceinline__ float silu_f(float g) { return g * __builtin_amdgcn_rcpf(1.0f + __builtin_amdgcn_exp2f(-1.4426950408889634f * g)); }
;     __device__ __forceinline__ void operator()(const pg8::f32x4 (&acc)[2][2][4][2], const pg8::Unit& u, int wr, int wc, int fr, int fq) const {
;     ...
;         for (int bj = 0; bj < 2; ++bj) {
;             const int col0 = bj * 128 + wc * 32 + 8 * fq;
;             const pg8::f32x4 bA = *(const pg8::f32x4*)(b1 + u.pn * 256 + col0), bB = *(const pg8::f32x4*)(b1 + u.pn * 256 + col0 + 4);
; #pragma unroll
;             for (int ai = 0; ai < 2; ++ai)
; #pragma unroll
;                 for (int m = 0; m < 4; ++m) {
;                     const pg8::f32x4 v0 = acc[ai][bj][m][0] + bA, v1 = acc[ai][bj][m][1] + bB;
;                     pg8::u32x4 w; w.x = pg8::cvt_pk_bf16(silu_f(v0[0]), silu_f(v0[1])); w.y = pg8::cvt_pk_bf16(silu_f(v0[2]), silu_f(v0[3]));
;                     w.z = pg8::cvt_pk_bf16(silu_f(v1[0]), silu_f(v1[1])); w.w = pg8::cvt_pk_bf16(silu_f(v1[2]), silu_f(v1[3]));
;                     *(pg8::u32x4*)(O + (size_t)(row0 + ai * 128 + m * 16) * 256 + col0) = w;
;                     asm volatile("" ::: "memory");
	v_mul_f32_e32 v82, 0xbfb8aa3b, v92
	v_mul_f32_e32 v83, 0xbfb8aa3b, v93
	v_exp_f32_e32 v82, v82
	v_exp_f32_e32 v83, v83
	v_add_f32_e32 v82, 1.0, v82
	v_add_f32_e32 v83, 1.0, v83
	v_rcp_f32_e32 v82, v82
	v_rcp_f32_e32 v83, v83
	s_nop 0
	v_mul_f32_e32 v82, v92, v82
	v_mul_f32_e32 v83, v93, v83
	s_nop 0
	v_cvt_pk_bf16_f32 v87, v82, v83
	v_lshl_add_u64 v[82:83], v[130:131], 0, s[16:17]
	s_mov_b32 s16, 0x12000
	v_add_co_u32_e32 v88, vcc, s16, v130
	s_mov_b64 s[16:17], 0x14000
	s_nop 0
	v_addc_co_u32_e32 v89, vcc, 0, v131, vcc
	flat_store_dwordx4 v[88:89], v[84:87]
	s_nop 1
	v_add_f32_e32 v84, v76, v100
	v_add_f32_e32 v85, v77, v101
	v_mul_f32_e32 v76, 0xbfb8aa3b, v78
	v_mul_f32_e32 v77, 0xbfb8aa3b, v79
	v_exp_f32_e32 v76, v76
	v_exp_f32_e32 v77, v77
	v_add_f32_e32 v76, 1.0, v76
	v_add_f32_e32 v77, 1.0, v77
	v_rcp_f32_e32 v76, v76
	v_rcp_f32_e32 v77, v77
	s_nop 0
	v_mul_f32_e32 v76, v78, v76
	v_mul_f32_e32 v77, v79, v77
	s_nop 0
	v_cvt_pk_bf16_f32 v76, v76, v77
	v_mul_f32_e32 v77, 0xbfb8aa3b, v80
	v_exp_f32_e32 v77, v77
	s_nop 0
	v_add_f32_e32 v77, 1.0, v77
	v_rcp_f32_e32 v78, v77
	v_mul_f32_e32 v77, 0xbfb8aa3b, v81
	v_exp_f32_e32 v77, v77
	s_nop 0
	v_add_f32_e32 v77, 1.0, v77
	v_rcp_f32_e32 v79, v77
	s_nop 0
	v_mul_f32_e32 v78, v80, v78
	v_mul_f32_e32 v79, v81, v79
	s_nop 0
	v_cvt_pk_bf16_f32 v77, v78, v79
	v_mul_f32_e32 v78, 0xbfb8aa3b, v74
	v_mul_f32_e32 v79, 0xbfb8aa3b, v75
	v_exp_f32_e32 v78, v78
	v_exp_f32_e32 v79, v79
	v_add_f32_e32 v78, 1.0, v78
	v_add_f32_e32 v79, 1.0, v79
	v_rcp_f32_e32 v78, v78
	v_rcp_f32_e32 v79, v79
	s_nop 0
	v_mul_f32_e32 v74, v74, v78
	v_mul_f32_e32 v75, v75, v79
	s_nop 0
	v_cvt_pk_bf16_f32 v78, v74, v75
	v_mul_f32_e32 v74, 0xbfb8aa3b, v84
	v_mul_f32_e32 v75, 0xbfb8aa3b, v85
	v_exp_f32_e32 v74, v74
	v_exp_f32_e32 v75, v75
	v_add_f32_e32 v74, 1.0, v74
	v_add_f32_e32 v75, 1.0, v75
	v_rcp_f32_e32 v74, v74
	v_rcp_f32_e32 v75, v75
	s_nop 0
	v_mul_f32_e32 v74, v84, v74
	v_mul_f32_e32 v75, v85, v75
	s_nop 0
	v_cvt_pk_bf16_f32 v79, v74, v75
	v_lshl_add_u64 v[74:75], v[130:131], 0, s[16:17]
	s_mov_b32 s16, 0x14000
	v_add_co_u32_e32 v80, vcc, s16, v130
	s_mov_b64 s[16:17], 0x16000
	s_nop 0
	v_addc_co_u32_e32 v81, vcc, 0, v131, vcc
	flat_store_dwordx4 v[80:81], v[76:79]
	s_nop 1
	v_add_f32_e32 v76, v68, v100
	v_add_f32_e32 v77, v69, v101
	v_add_f32_e32 v68, v66, v98
	v_add_f32_e32 v69, v67, v99
	v_mul_f32_e32 v66, 0xbfb8aa3b, v70
	v_mul_f32_e32 v67, 0xbfb8aa3b, v71
	v_exp_f32_e32 v66, v66
	v_exp_f32_e32 v67, v67
	v_add_f32_e32 v66, 1.0, v66
	v_add_f32_e32 v67, 1.0, v67
	v_rcp_f32_e32 v66, v66
	v_rcp_f32_e32 v67, v67
	s_nop 0
	v_mul_f32_e32 v66, v70, v66
	v_mul_f32_e32 v67, v71, v67
	s_nop 0
	v_cvt_pk_bf16_f32 v66, v66, v67
	v_mul_f32_e32 v67, 0xbfb8aa3b, v72
	v_exp_f32_e32 v67, v67
	s_nop 0
	v_add_f32_e32 v67, 1.0, v67
	v_rcp_f32_e32 v70, v67
	v_mul_f32_e32 v67, 0xbfb8aa3b, v73
	v_exp_f32_e32 v67, v67
	s_nop 0
	v_add_f32_e32 v67, 1.0, v67
	v_rcp_f32_e32 v71, v67
	s_nop 0
	v_mul_f32_e32 v70, v72, v70
	v_mul_f32_e32 v71, v73, v71
	s_nop 0
	v_cvt_pk_bf16_f32 v67, v70, v71
	v_mul_f32_e32 v70, 0xbfb8aa3b, v68
	v_mul_f32_e32 v71, 0xbfb8aa3b, v69
	v_exp_f32_e32 v70, v70
	v_exp_f32_e32 v71, v71
	v_add_f32_e32 v70, 1.0, v70
	v_add_f32_e32 v71, 1.0, v71
	v_rcp_f32_e32 v70, v70
	v_rcp_f32_e32 v71, v71
	s_nop 0
	v_mul_f32_e32 v68, v68, v70
	v_mul_f32_e32 v69, v69, v71
	s_nop 0
	v_cvt_pk_bf16_f32 v68, v68, v69
	v_mul_f32_e32 v69, 0xbfb8aa3b, v76
	v_exp_f32_e32 v69, v69
	s_nop 0
	v_add_f32_e32 v69, 1.0, v69
	v_rcp_f32_e32 v70, v69
	v_mul_f32_e32 v69, 0xbfb8aa3b, v77
	v_exp_f32_e32 v69, v69
	s_nop 0
	v_add_f32_e32 v69, 1.0, v69
	v_rcp_f32_e32 v71, v69
	s_nop 0
	v_mul_f32_e32 v70, v76, v70
	v_mul_f32_e32 v71, v77, v71
	v_lshl_add_u64 v[76:77], v[130:131], 0, s[16:17]
	s_mov_b32 s16, 0x16000
	v_cvt_pk_bf16_f32 v69, v70, v71
	v_add_co_u32_e32 v70, vcc, s16, v130
	s_mov_b64 s[16:17], -1
	s_nop 0
	v_addc_co_u32_e32 v71, vcc, 0, v131, vcc
	flat_store_dwordx4 v[70:71], v[66:69]
	flat_load_dwordx4 v[70:73], v[152:153] offset:512
	flat_load_dwordx4 v[66:69], v[152:153] offset:528
	s_andn2_b64 vcc, exec, s[0:1]
	s_waitcnt vmcnt(0) lgkmcnt(0)
	v_add_f32_e32 v62, v62, v70
	v_add_f32_e32 v63, v63, v71
	v_add_f32_e32 v78, v60, v68
	v_add_f32_e32 v79, v61, v69
	v_add_f32_e32 v60, v58, v66
	v_add_f32_e32 v61, v59, v67
	v_mul_f32_e32 v58, 0xbfb8aa3b, v62
	v_mul_f32_e32 v59, 0xbfb8aa3b, v63
	v_exp_f32_e32 v58, v58
	v_exp_f32_e32 v59, v59
	v_add_f32_e32 v64, v64, v72
	v_add_f32_e32 v65, v65, v73
	v_add_f32_e32 v54, v54, v70
	v_add_f32_e32 v55, v55, v71
	v_add_f32_e32 v58, 1.0, v58
	v_add_f32_e32 v59, 1.0, v59
	v_rcp_f32_e32 v58, v58
	v_rcp_f32_e32 v59, v59
	v_add_f32_e32 v56, v56, v72
	v_add_f32_e32 v57, v57, v73
	v_add_f32_e32 v46, v46, v70
	v_add_f32_e32 v47, v47, v71
	v_add_f32_e32 v48, v48, v72
	v_add_f32_e32 v49, v49, v73
	v_mul_f32_e32 v58, v62, v58
	v_mul_f32_e32 v59, v63, v59
	v_add_f32_e32 v38, v38, v70
	v_add_f32_e32 v39, v39, v71
	v_cvt_pk_bf16_f32 v58, v58, v59
	v_mul_f32_e32 v59, 0xbfb8aa3b, v64
	v_exp_f32_e32 v59, v59
	v_add_f32_e32 v40, v40, v72
	v_add_f32_e32 v41, v41, v73
	v_add_f32_e32 v30, v30, v70
	v_add_f32_e32 v31, v31, v71
	v_add_f32_e32 v32, v32, v72
	v_add_f32_e32 v33, v33, v73
	v_add_f32_e32 v59, 1.0, v59
	v_rcp_f32_e32 v62, v59
	v_mul_f32_e32 v59, 0xbfb8aa3b, v65
	v_exp_f32_e32 v59, v59
	v_add_f32_e32 v22, v22, v70
	v_add_f32_e32 v23, v23, v71
	v_add_f32_e32 v24, v24, v72
	v_add_f32_e32 v25, v25, v73
	v_add_f32_e32 v14, v14, v70
	v_add_f32_e32 v15, v15, v71
	v_add_f32_e32 v59, 1.0, v59
	v_rcp_f32_e32 v63, v59
	v_add_f32_e32 v16, v16, v72
	v_add_f32_e32 v17, v17, v73
	v_add_f32_e32 v6, v6, v70
	v_add_f32_e32 v7, v7, v71
; __device__ __forceinline__ unsigned cvt_pk_bf16(float lo, float hi) { const pk_f2_t v = {lo, hi}; return __builtin_bit_cast(unsigned, __builtin_convertvector(v, pk_bf2_t)); }
; __device__ __forceinline__ float silu_f(float g) { return g * __builtin_amdgcn_rcpf(1.0f + __builtin_amdgcn_exp2f(-1.4426950408889634f * g)); }
;     __device__ __forceinline__ void operator()(const pg8::f32x4 (&acc)[2][2][4][2], const pg8::Unit& u, int wr, int wc, int fr, int fq) const {
;     ...
;                 for (int m = 0; m < 4; ++m) {
;                     const pg8::f32x4 v0 = acc[ai][bj][m][0] + bA, v1 = acc[ai][bj][m][1] + bB;
;                     pg8::u32x4 w; w.x = pg8::cvt_pk_bf16(silu_f(v0[0]), silu_f(v0[1])); w.y = pg8::cvt_pk_bf16(silu_f(v0[2]), silu_f(v0[3]));
;                     w.z = pg8::cvt_pk_bf16(silu_f(v1[0]), silu_f(v1[1])); w.w = pg8::cvt_pk_bf16(silu_f(v1[2]), silu_f(v1[3]));
;                     *(pg8::u32x4*)(O + (size_t)(row0 + ai * 128 + m * 16) * 256 + col0) = w;
;                     asm volatile("" ::: "memory");
	v_add_f32_e32 v8, v8, v72
	v_add_f32_e32 v9, v9, v73
	v_mul_f32_e32 v62, v64, v62
	v_mul_f32_e32 v63, v65, v63
	s_nop 0
	v_cvt_pk_bf16_f32 v59, v62, v63
	v_mul_f32_e32 v62, 0xbfb8aa3b, v60
	v_mul_f32_e32 v63, 0xbfb8aa3b, v61
	v_exp_f32_e32 v62, v62
	v_exp_f32_e32 v63, v63
	v_add_f32_e32 v62, 1.0, v62
	v_add_f32_e32 v63, 1.0, v63
	v_rcp_f32_e32 v62, v62
	v_rcp_f32_e32 v63, v63
	s_nop 0
	v_mul_f32_e32 v60, v60, v62
	v_mul_f32_e32 v61, v61, v63
	s_nop 0
	v_cvt_pk_bf16_f32 v60, v60, v61
	v_mul_f32_e32 v61, 0xbfb8aa3b, v78
	v_exp_f32_e32 v61, v61
	s_nop 0
	v_add_f32_e32 v61, 1.0, v61
	v_rcp_f32_e32 v62, v61
	v_mul_f32_e32 v61, 0xbfb8aa3b, v79
	v_exp_f32_e32 v61, v61
	s_nop 0
	v_add_f32_e32 v61, 1.0, v61
	v_rcp_f32_e32 v63, v61
	s_nop 0
	v_mul_f32_e32 v62, v78, v62
	v_mul_f32_e32 v63, v79, v63
	s_nop 0
	v_cvt_pk_bf16_f32 v61, v62, v63
	flat_store_dwordx4 v[130:131], v[58:61] offset:256
	s_nop 1
	v_add_f32_e32 v58, v52, v68
	v_add_f32_e32 v59, v53, v69
	v_add_f32_e32 v52, v50, v66
	v_add_f32_e32 v53, v51, v67
	v_mul_f32_e32 v50, 0xbfb8aa3b, v54
	v_mul_f32_e32 v51, 0xbfb8aa3b, v55
	v_exp_f32_e32 v50, v50
	v_exp_f32_e32 v51, v51
	v_add_f32_e32 v50, 1.0, v50
	v_add_f32_e32 v51, 1.0, v51
	v_rcp_f32_e32 v50, v50
	v_rcp_f32_e32 v51, v51
	s_nop 0
	v_mul_f32_e32 v50, v54, v50
	v_mul_f32_e32 v51, v55, v51
	s_nop 0
	v_cvt_pk_bf16_f32 v50, v50, v51
	v_mul_f32_e32 v51, 0xbfb8aa3b, v56
	v_exp_f32_e32 v51, v51
	s_nop 0
	v_add_f32_e32 v51, 1.0, v51
	v_rcp_f32_e32 v54, v51
	v_mul_f32_e32 v51, 0xbfb8aa3b, v57
	v_exp_f32_e32 v51, v51
	s_nop 0
	v_add_f32_e32 v51, 1.0, v51
	v_rcp_f32_e32 v55, v51
	s_nop 0
	v_mul_f32_e32 v54, v56, v54
	v_mul_f32_e32 v55, v57, v55
	s_nop 0
	v_cvt_pk_bf16_f32 v51, v54, v55
	v_mul_f32_e32 v54, 0xbfb8aa3b, v52
	v_mul_f32_e32 v55, 0xbfb8aa3b, v53
	v_exp_f32_e32 v54, v54
	v_exp_f32_e32 v55, v55
	v_add_f32_e32 v54, 1.0, v54
	v_add_f32_e32 v55, 1.0, v55
	v_rcp_f32_e32 v54, v54
	v_rcp_f32_e32 v55, v55
	s_nop 0
	v_mul_f32_e32 v52, v52, v54
	v_mul_f32_e32 v53, v53, v55
	s_nop 0
	v_cvt_pk_bf16_f32 v52, v52, v53
	v_mul_f32_e32 v53, 0xbfb8aa3b, v58
	v_exp_f32_e32 v53, v53
	s_nop 0
	v_add_f32_e32 v53, 1.0, v53
	v_rcp_f32_e32 v54, v53
	v_mul_f32_e32 v53, 0xbfb8aa3b, v59
	v_exp_f32_e32 v53, v53
	s_nop 0
	v_add_f32_e32 v53, 1.0, v53
	v_rcp_f32_e32 v55, v53
	s_nop 0
	v_mul_f32_e32 v54, v58, v54
	v_mul_f32_e32 v55, v59, v55
	s_nop 0
	v_cvt_pk_bf16_f32 v53, v54, v55
	flat_store_dwordx4 v[126:127], v[50:53] offset:256
	s_nop 1
	v_add_f32_e32 v50, v44, v68
	v_add_f32_e32 v51, v45, v69
	v_add_f32_e32 v44, v42, v66
	v_add_f32_e32 v45, v43, v67
	v_mul_f32_e32 v42, 0xbfb8aa3b, v46
	v_mul_f32_e32 v43, 0xbfb8aa3b, v47
	v_exp_f32_e32 v42, v42
	v_exp_f32_e32 v43, v43
	v_add_f32_e32 v42, 1.0, v42
	v_add_f32_e32 v43, 1.0, v43
	v_rcp_f32_e32 v42, v42
	v_rcp_f32_e32 v43, v43
	s_nop 0
	v_mul_f32_e32 v42, v46, v42
	v_mul_f32_e32 v43, v47, v43
	s_nop 0
	v_cvt_pk_bf16_f32 v42, v42, v43
	v_mul_f32_e32 v43, 0xbfb8aa3b, v48
	v_exp_f32_e32 v43, v43
	s_nop 0
	v_add_f32_e32 v43, 1.0, v43
	v_rcp_f32_e32 v46, v43
	v_mul_f32_e32 v43, 0xbfb8aa3b, v49
	v_exp_f32_e32 v43, v43
	s_nop 0
	v_add_f32_e32 v43, 1.0, v43
	v_rcp_f32_e32 v47, v43
	s_nop 0
	v_mul_f32_e32 v46, v48, v46
	v_mul_f32_e32 v47, v49, v47
	s_nop 0
	v_cvt_pk_bf16_f32 v43, v46, v47
	v_mul_f32_e32 v46, 0xbfb8aa3b, v44
	v_mul_f32_e32 v47, 0xbfb8aa3b, v45
	v_exp_f32_e32 v46, v46
	v_exp_f32_e32 v47, v47
	v_add_f32_e32 v46, 1.0, v46
	v_add_f32_e32 v47, 1.0, v47
	v_rcp_f32_e32 v46, v46
	v_rcp_f32_e32 v47, v47
	s_nop 0
	v_mul_f32_e32 v44, v44, v46
	v_mul_f32_e32 v45, v45, v47
	s_nop 0
	v_cvt_pk_bf16_f32 v44, v44, v45
	v_mul_f32_e32 v45, 0xbfb8aa3b, v50
	v_exp_f32_e32 v45, v45
	s_nop 0
	v_add_f32_e32 v45, 1.0, v45
	v_rcp_f32_e32 v46, v45
	v_mul_f32_e32 v45, 0xbfb8aa3b, v51
	v_exp_f32_e32 v45, v45
	s_nop 0
	v_add_f32_e32 v45, 1.0, v45
	v_rcp_f32_e32 v47, v45
	s_nop 0
	v_mul_f32_e32 v46, v50, v46
	v_mul_f32_e32 v47, v51, v47
	s_nop 0
	v_cvt_pk_bf16_f32 v45, v46, v47
	flat_store_dwordx4 v[114:115], v[42:45] offset:256
	s_nop 1
	v_add_f32_e32 v42, v36, v68
	v_add_f32_e32 v43, v37, v69
	v_add_f32_e32 v36, v34, v66
	v_add_f32_e32 v37, v35, v67
	v_mul_f32_e32 v34, 0xbfb8aa3b, v38
	v_mul_f32_e32 v35, 0xbfb8aa3b, v39
	v_exp_f32_e32 v34, v34
	v_exp_f32_e32 v35, v35
	v_add_f32_e32 v34, 1.0, v34
	v_add_f32_e32 v35, 1.0, v35
	v_rcp_f32_e32 v34, v34
	v_rcp_f32_e32 v35, v35
	s_nop 0
	v_mul_f32_e32 v34, v38, v34
	v_mul_f32_e32 v35, v39, v35
	s_nop 0
	v_cvt_pk_bf16_f32 v34, v34, v35
	v_mul_f32_e32 v35, 0xbfb8aa3b, v40
	v_exp_f32_e32 v35, v35
	s_nop 0
	v_add_f32_e32 v35, 1.0, v35
	v_rcp_f32_e32 v38, v35
	v_mul_f32_e32 v35, 0xbfb8aa3b, v41
	v_exp_f32_e32 v35, v35
	s_nop 0
	v_add_f32_e32 v35, 1.0, v35
	v_rcp_f32_e32 v39, v35
	s_nop 0
	v_mul_f32_e32 v38, v40, v38
	v_mul_f32_e32 v39, v41, v39
	s_nop 0
	v_cvt_pk_bf16_f32 v35, v38, v39
	v_mul_f32_e32 v38, 0xbfb8aa3b, v36
	v_mul_f32_e32 v39, 0xbfb8aa3b, v37
	v_exp_f32_e32 v38, v38
	v_exp_f32_e32 v39, v39
	v_add_f32_e32 v38, 1.0, v38
	v_add_f32_e32 v39, 1.0, v39
	v_rcp_f32_e32 v38, v38
	v_rcp_f32_e32 v39, v39
	s_nop 0
	v_mul_f32_e32 v36, v36, v38
	v_mul_f32_e32 v37, v37, v39
	s_nop 0
	v_cvt_pk_bf16_f32 v36, v36, v37
	v_mul_f32_e32 v37, 0xbfb8aa3b, v42
	v_exp_f32_e32 v37, v37
	s_nop 0
	v_add_f32_e32 v37, 1.0, v37
	v_rcp_f32_e32 v38, v37
	v_mul_f32_e32 v37, 0xbfb8aa3b, v43
	v_exp_f32_e32 v37, v37
	s_nop 0
	v_add_f32_e32 v37, 1.0, v37
	v_rcp_f32_e32 v39, v37
	s_nop 0
	v_mul_f32_e32 v38, v42, v38
	v_mul_f32_e32 v39, v43, v39
	s_nop 0
	v_cvt_pk_bf16_f32 v37, v38, v39
	flat_store_dwordx4 v[106:107], v[34:37] offset:256
	s_nop 1
	v_add_f32_e32 v34, v28, v68
	v_add_f32_e32 v35, v29, v69
	v_add_f32_e32 v28, v26, v66
; __device__ __forceinline__ unsigned cvt_pk_bf16(float lo, float hi) { const pk_f2_t v = {lo, hi}; return __builtin_bit_cast(unsigned, __builtin_convertvector(v, pk_bf2_t)); }
; __device__ __forceinline__ float silu_f(float g) { return g * __builtin_amdgcn_rcpf(1.0f + __builtin_amdgcn_exp2f(-1.4426950408889634f * g)); }
;     __device__ __forceinline__ void operator()(const pg8::f32x4 (&acc)[2][2][4][2], const pg8::Unit& u, int wr, int wc, int fr, int fq) const {
;     ...
;         for (int bj = 0; bj < 2; ++bj) {
;             const int col0 = bj * 128 + wc * 32 + 8 * fq;
;             const pg8::f32x4 bA = *(const pg8::f32x4*)(b1 + u.pn * 256 + col0), bB = *(const pg8::f32x4*)(b1 + u.pn * 256 + col0 + 4);
; #pragma unroll
;             for (int ai = 0; ai < 2; ++ai)
; #pragma unroll
;                 for (int m = 0; m < 4; ++m) {
;                     const pg8::f32x4 v0 = acc[ai][bj][m][0] + bA, v1 = acc[ai][bj][m][1] + bB;
;                     pg8::u32x4 w; w.x = pg8::cvt_pk_bf16(silu_f(v0[0]), silu_f(v0[1])); w.y = pg8::cvt_pk_bf16(silu_f(v0[2]), silu_f(v0[3]));
;                     w.z = pg8::cvt_pk_bf16(silu_f(v1[0]), silu_f(v1[1])); w.w = pg8::cvt_pk_bf16(silu_f(v1[2]), silu_f(v1[3]));
;                     *(pg8::u32x4*)(O + (size_t)(row0 + ai * 128 + m * 16) * 256 + col0) = w;
;                     asm volatile("" ::: "memory");
;                 }
	v_add_f32_e32 v29, v27, v67
	v_mul_f32_e32 v26, 0xbfb8aa3b, v30
	v_mul_f32_e32 v27, 0xbfb8aa3b, v31
	v_exp_f32_e32 v26, v26
	v_exp_f32_e32 v27, v27
	v_add_f32_e32 v26, 1.0, v26
	v_add_f32_e32 v27, 1.0, v27
	v_rcp_f32_e32 v26, v26
	v_rcp_f32_e32 v27, v27
	s_nop 0
	v_mul_f32_e32 v26, v30, v26
	v_mul_f32_e32 v27, v31, v27
	s_nop 0
	v_cvt_pk_bf16_f32 v26, v26, v27
	v_mul_f32_e32 v27, 0xbfb8aa3b, v32
	v_exp_f32_e32 v27, v27
	s_nop 0
	v_add_f32_e32 v27, 1.0, v27
	v_rcp_f32_e32 v30, v27
	v_mul_f32_e32 v27, 0xbfb8aa3b, v33
	v_exp_f32_e32 v27, v27
	s_nop 0
	v_add_f32_e32 v27, 1.0, v27
	v_rcp_f32_e32 v31, v27
	s_nop 0
	v_mul_f32_e32 v30, v32, v30
	v_mul_f32_e32 v31, v33, v31
	s_nop 0
	v_cvt_pk_bf16_f32 v27, v30, v31
	v_mul_f32_e32 v30, 0xbfb8aa3b, v28
	v_mul_f32_e32 v31, 0xbfb8aa3b, v29
	v_exp_f32_e32 v30, v30
	v_exp_f32_e32 v31, v31
	v_add_f32_e32 v30, 1.0, v30
	v_add_f32_e32 v31, 1.0, v31
	v_rcp_f32_e32 v30, v30
	v_rcp_f32_e32 v31, v31
	s_nop 0
	v_mul_f32_e32 v28, v28, v30
	v_mul_f32_e32 v29, v29, v31
	s_nop 0
	v_cvt_pk_bf16_f32 v28, v28, v29
	v_mul_f32_e32 v29, 0xbfb8aa3b, v34
	v_exp_f32_e32 v29, v29
	s_nop 0
	v_add_f32_e32 v29, 1.0, v29
	v_rcp_f32_e32 v30, v29
	v_mul_f32_e32 v29, 0xbfb8aa3b, v35
	v_exp_f32_e32 v29, v29
	s_nop 0
	v_add_f32_e32 v29, 1.0, v29
	v_rcp_f32_e32 v31, v29
	s_nop 0
	v_mul_f32_e32 v30, v34, v30
	v_mul_f32_e32 v31, v35, v31
	s_nop 0
	v_cvt_pk_bf16_f32 v29, v30, v31
	flat_store_dwordx4 v[90:91], v[26:29] offset:256
	s_nop 1
	v_add_f32_e32 v26, v20, v68
	v_add_f32_e32 v27, v21, v69
	v_add_f32_e32 v20, v18, v66
	v_add_f32_e32 v21, v19, v67
	v_mul_f32_e32 v18, 0xbfb8aa3b, v22
	v_mul_f32_e32 v19, 0xbfb8aa3b, v23
	v_exp_f32_e32 v18, v18
	v_exp_f32_e32 v19, v19
	v_add_f32_e32 v18, 1.0, v18
	v_add_f32_e32 v19, 1.0, v19
	v_rcp_f32_e32 v18, v18
	v_rcp_f32_e32 v19, v19
	s_nop 0
	v_mul_f32_e32 v18, v22, v18
	v_mul_f32_e32 v19, v23, v19
	s_nop 0
	v_cvt_pk_bf16_f32 v18, v18, v19
	v_mul_f32_e32 v19, 0xbfb8aa3b, v24
	v_exp_f32_e32 v19, v19
	s_nop 0
	v_add_f32_e32 v19, 1.0, v19
	v_rcp_f32_e32 v22, v19
	v_mul_f32_e32 v19, 0xbfb8aa3b, v25
	v_exp_f32_e32 v19, v19
	s_nop 0
	v_add_f32_e32 v19, 1.0, v19
	v_rcp_f32_e32 v23, v19
	s_nop 0
	v_mul_f32_e32 v22, v24, v22
	v_mul_f32_e32 v23, v25, v23
	s_nop 0
	v_cvt_pk_bf16_f32 v19, v22, v23
	v_mul_f32_e32 v22, 0xbfb8aa3b, v20
	v_mul_f32_e32 v23, 0xbfb8aa3b, v21
	v_exp_f32_e32 v22, v22
	v_exp_f32_e32 v23, v23
	v_add_f32_e32 v22, 1.0, v22
	v_add_f32_e32 v23, 1.0, v23
	v_rcp_f32_e32 v22, v22
	v_rcp_f32_e32 v23, v23
	s_nop 0
	v_mul_f32_e32 v20, v20, v22
	v_mul_f32_e32 v21, v21, v23
	s_nop 0
	v_cvt_pk_bf16_f32 v20, v20, v21
	v_mul_f32_e32 v21, 0xbfb8aa3b, v26
	v_exp_f32_e32 v21, v21
	s_nop 0
	v_add_f32_e32 v21, 1.0, v21
	v_rcp_f32_e32 v22, v21
	v_mul_f32_e32 v21, 0xbfb8aa3b, v27
	v_exp_f32_e32 v21, v21
	s_nop 0
	v_add_f32_e32 v21, 1.0, v21
	v_rcp_f32_e32 v23, v21
	s_nop 0
	v_mul_f32_e32 v22, v26, v22
	v_mul_f32_e32 v23, v27, v23
	s_nop 0
	v_cvt_pk_bf16_f32 v21, v22, v23
	flat_store_dwordx4 v[82:83], v[18:21] offset:256
	s_nop 1
	v_add_f32_e32 v18, v12, v68
	v_add_f32_e32 v19, v13, v69
	v_add_f32_e32 v12, v10, v66
	v_add_f32_e32 v13, v11, v67
	v_mul_f32_e32 v10, 0xbfb8aa3b, v14
	v_mul_f32_e32 v11, 0xbfb8aa3b, v15
	v_exp_f32_e32 v10, v10
	v_exp_f32_e32 v11, v11
	v_add_f32_e32 v10, 1.0, v10
	v_add_f32_e32 v11, 1.0, v11
	v_rcp_f32_e32 v10, v10
	v_rcp_f32_e32 v11, v11
	s_nop 0
	v_mul_f32_e32 v10, v14, v10
	v_mul_f32_e32 v11, v15, v11
	s_nop 0
	v_cvt_pk_bf16_f32 v10, v10, v11
	v_mul_f32_e32 v11, 0xbfb8aa3b, v16
	v_exp_f32_e32 v11, v11
	s_nop 0
	v_add_f32_e32 v11, 1.0, v11
	v_rcp_f32_e32 v14, v11
	v_mul_f32_e32 v11, 0xbfb8aa3b, v17
	v_exp_f32_e32 v11, v11
	s_nop 0
	v_add_f32_e32 v11, 1.0, v11
	v_rcp_f32_e32 v15, v11
	s_nop 0
	v_mul_f32_e32 v14, v16, v14
	v_mul_f32_e32 v15, v17, v15
	s_nop 0
	v_cvt_pk_bf16_f32 v11, v14, v15
	v_mul_f32_e32 v14, 0xbfb8aa3b, v12
	v_mul_f32_e32 v15, 0xbfb8aa3b, v13
	v_exp_f32_e32 v14, v14
	v_exp_f32_e32 v15, v15
	v_add_f32_e32 v14, 1.0, v14
	v_add_f32_e32 v15, 1.0, v15
	v_rcp_f32_e32 v14, v14
	v_rcp_f32_e32 v15, v15
	s_nop 0
	v_mul_f32_e32 v12, v12, v14
	v_mul_f32_e32 v13, v13, v15
	s_nop 0
	v_cvt_pk_bf16_f32 v12, v12, v13
	v_mul_f32_e32 v13, 0xbfb8aa3b, v18
	v_exp_f32_e32 v13, v13
	s_nop 0
	v_add_f32_e32 v13, 1.0, v13
	v_rcp_f32_e32 v14, v13
	v_mul_f32_e32 v13, 0xbfb8aa3b, v19
	v_exp_f32_e32 v13, v13
	s_nop 0
	v_add_f32_e32 v13, 1.0, v13
	v_rcp_f32_e32 v15, v13
	s_nop 0
	v_mul_f32_e32 v14, v18, v14
	v_mul_f32_e32 v15, v19, v15
	s_nop 0
	v_cvt_pk_bf16_f32 v13, v14, v15
	flat_store_dwordx4 v[74:75], v[10:13] offset:256
	s_nop 1
	v_add_f32_e32 v10, v4, v68
	v_add_f32_e32 v11, v5, v69
	v_add_f32_e32 v4, v2, v66
	v_add_f32_e32 v5, v3, v67
	v_mul_f32_e32 v2, 0xbfb8aa3b, v6
	v_mul_f32_e32 v3, 0xbfb8aa3b, v7
	v_exp_f32_e32 v2, v2
	v_exp_f32_e32 v3, v3
	v_add_f32_e32 v2, 1.0, v2
	v_add_f32_e32 v3, 1.0, v3
	v_rcp_f32_e32 v2, v2
	v_rcp_f32_e32 v3, v3
	s_nop 0
	v_mul_f32_e32 v2, v6, v2
	v_mul_f32_e32 v3, v7, v3
	s_nop 0
	v_cvt_pk_bf16_f32 v2, v2, v3
	v_mul_f32_e32 v3, 0xbfb8aa3b, v8
	v_exp_f32_e32 v3, v3
	s_nop 0
	v_add_f32_e32 v3, 1.0, v3
	v_rcp_f32_e32 v6, v3
	v_mul_f32_e32 v3, 0xbfb8aa3b, v9
	v_exp_f32_e32 v3, v3
	s_nop 0
	v_add_f32_e32 v3, 1.0, v3
	v_rcp_f32_e32 v7, v3
	s_nop 0
	v_mul_f32_e32 v6, v8, v6
	v_mul_f32_e32 v7, v9, v7
	s_nop 0
	v_cvt_pk_bf16_f32 v3, v6, v7
	v_mul_f32_e32 v6, 0xbfb8aa3b, v4
	v_mul_f32_e32 v7, 0xbfb8aa3b, v5
	v_exp_f32_e32 v6, v6
	v_exp_f32_e32 v7, v7
	v_add_f32_e32 v6, 1.0, v6
	v_add_f32_e32 v7, 1.0, v7
	v_rcp_f32_e32 v6, v6
	v_rcp_f32_e32 v7, v7
	s_nop 0
	v_mul_f32_e32 v4, v4, v6
	v_mul_f32_e32 v5, v5, v7
	s_nop 0
	v_cvt_pk_bf16_f32 v4, v4, v5
	v_mul_f32_e32 v5, 0xbfb8aa3b, v10
	v_exp_f32_e32 v5, v5
	s_nop 0
	v_add_f32_e32 v5, 1.0, v5
	v_rcp_f32_e32 v6, v5
	v_mul_f32_e32 v5, 0xbfb8aa3b, v11
	v_exp_f32_e32 v5, v5
	s_nop 0
	v_add_f32_e32 v5, 1.0, v5
	v_rcp_f32_e32 v7, v5
	s_nop 0
	v_mul_f32_e32 v6, v10, v6
	v_mul_f32_e32 v7, v11, v7
	s_nop 0
	v_cvt_pk_bf16_f32 v5, v6, v7
	flat_store_dwordx4 v[76:77], v[2:5] offset:256
	s_cbranch_vccnz .LBB0_745
	s_andn2_b64 vcc, exec, s[14:15]
	s_cbranch_vccnz .LBB0_744
	s_barrier
	s_branch .LBB0_744

; #define GAS __attribute__((address_space(1)))
; __device__ __forceinline__ unsigned pk2(float lo, float hi) { return f2bf(lo) | (f2bf(hi) << 16); }
; __device__ __forceinline__ void ckvnorm_rows(const float* raw, bf16* out, const float* gkv, int w0, int nw, int lane) {
;     ...
;     for (int r = w0; r < M; r += 4 * nw) {
;         f32x4 v[4];
; #pragma unroll
;         for (int u = 0; u < 4; ++u) { const int rr = min(r + u * nw, M - 1); v[u] = *(const GAS f32x4*)(raw + (size_t)rr * 256 + 4 * lane); }
; #pragma unroll
;         for (int u = 0; u < 4; ++u) { const int rr = r + u * nw;
;             const float ss = wave_sum((v[u].x * v[u].x + v[u].y * v[u].y) + (v[u].z * v[u].z + v[u].w * v[u].w));
;             const float rstd = 1.0f / sqrtf(ss * (1.0f / 256.0f) + RMS_EPS);
;             const f32x4 y = v[u] * rstd * g;
;             if (rr < M) *(GAS unsigned long long*)(out + (size_t)rr * 256 + 4 * lane) = (unsigned long long)pk2(y.x, y.y) | ((unsigned long long)pk2(y.z, y.w) << 32); }
.LBB0_762:
	global_load_dwordx4 v[26:29], v[24:25], off
	v_readlane_b32 s0, v255, 4
	s_add_i32 s10, s0, s12
	s_min_i32 s0, s10, 0x3fff
	s_ashr_i32 s1, s0, 31
	s_lshl_b64 s[0:1], s[0:1], 10
	v_lshl_add_u64 v[6:7], v[18:19], 0, s[0:1]
	global_load_dwordx4 v[14:17], v[6:7], off
	v_readlane_b32 s0, v255, 1
	s_add_i32 s8, s0, s12
	s_min_i32 s0, s8, 0x3fff
	s_ashr_i32 s1, s0, 31
	s_lshl_b64 s[0:1], s[0:1], 10
	v_lshl_add_u64 v[6:7], v[18:19], 0, s[0:1]
	v_readlane_b32 s0, v255, 2
	s_add_i32 s0, s0, s12
	s_min_i32 s14, s0, 0x3fff
	s_ashr_i32 s15, s14, 31
	s_lshl_b64 s[14:15], s[14:15], 10
	global_load_dwordx4 v[10:13], v[6:7], off
	v_lshl_add_u64 v[6:7], v[18:19], 0, s[14:15]
	global_load_dwordx4 v[6:9], v[6:7], off
	s_cmpk_gt_i32 s10, 0x3fff
	s_waitcnt vmcnt(0)
	v_mul_f32_e32 v0, v27, v27
	v_mul_f32_e32 v30, v29, v29
	v_fmac_f32_e32 v0, v26, v26
	v_fmac_f32_e32 v30, v28, v28
	v_add_f32_e32 v0, v0, v30
	ds_swizzle_b32 v30, v0 offset:swizzle(SWAP,1)
	s_waitcnt lgkmcnt(0)
	v_add_f32_e32 v0, v0, v30
	ds_swizzle_b32 v30, v0 offset:swizzle(SWAP,2)
	s_waitcnt lgkmcnt(0)
	v_add_f32_e32 v0, v0, v30
	ds_swizzle_b32 v30, v0 offset:swizzle(SWAP,4)
	s_waitcnt lgkmcnt(0)
	v_add_f32_e32 v0, v0, v30
	ds_swizzle_b32 v30, v0 offset:swizzle(SWAP,8)
	s_waitcnt lgkmcnt(0)
	v_add_f32_e32 v0, v0, v30
	ds_swizzle_b32 v30, v0 offset:swizzle(SWAP,16)
	s_waitcnt lgkmcnt(0)
	v_add_f32_e32 v0, v0, v30
	v_mov_b32_e32 v30, v0
	s_nop 1
	v_permlane32_swap_b32_e32 v0, v30
	v_add_f32_e32 v0, v0, v30
	v_fmamk_f32 v0, v0, 0x3b800000, v202
	v_cmp_gt_f32_e32 vcc, s60, v0
	v_mul_f32_e32 v30, 0x4f800000, v0
	s_nop 0
	v_cndmask_b32_e32 v0, v0, v30, vcc
	v_sqrt_f32_e32 v30, v0
	s_nop 0
	v_add_u32_e32 v31, -1, v30
	v_fma_f32 v32, -v31, v30, v0
	v_cmp_ge_f32_e64 s[38:39], 0, v32
	v_add_u32_e32 v32, 1, v30
	s_nop 0
	v_cndmask_b32_e64 v31, v30, v31, s[38:39]
	v_fma_f32 v30, -v32, v30, v0
	v_cmp_lt_f32_e64 s[38:39], 0, v30
	s_nop 1
	v_cndmask_b32_e64 v30, v31, v32, s[38:39]
	v_mul_f32_e32 v31, 0x37800000, v30
	v_cndmask_b32_e32 v30, v30, v31, vcc
	v_cmp_class_f32_e32 vcc, v0, v203
	s_nop 1
	v_cndmask_b32_e32 v0, v30, v0, vcc
	v_div_scale_f32 v30, s[14:15], v0, v0, 1.0
	v_rcp_f32_e32 v31, v30
	s_nop 0
	v_fma_f32 v32, -v30, v31, 1.0
	v_fmac_f32_e32 v31, v32, v31
	v_div_scale_f32 v32, vcc, 1.0, v0, 1.0
	v_mul_f32_e32 v33, v32, v31
	v_fma_f32 v34, -v30, v33, v32
	v_fmac_f32_e32 v33, v34, v31
	v_fma_f32 v30, -v30, v33, v32
	v_div_fmas_f32 v30, v30, v31, v33
	v_div_fixup_f32 v0, v30, v0, 1.0
	v_mul_f32_e32 v26, v26, v0
	v_mul_f32_e32 v27, v27, v0
	v_mul_f32_e32 v28, v28, v0
	v_mul_f32_e32 v29, v29, v0
	v_mul_f32_e32 v26, v2, v26
	v_mul_f32_e32 v27, v3, v27
	v_mul_f32_e32 v28, v4, v28
	v_mul_f32_e32 v29, v5, v29
	v_bfe_u32 v0, v26, 16, 1
	v_add3_u32 v0, v26, v0, s94
	v_bfe_u32 v26, v27, 16, 1
	v_lshrrev_b32_e32 v0, 16, v0
	v_add3_u32 v26, v27, v26, s94
	v_and_or_b32 v26, v26, s95, v0
	v_bfe_u32 v0, v28, 16, 1
	v_add3_u32 v0, v28, v0, s94
	v_bfe_u32 v27, v29, 16, 1
	v_lshrrev_b32_e32 v0, 16, v0
	v_add3_u32 v27, v29, v27, s94
	v_and_or_b32 v27, v27, s95, v0
	global_store_dwordx2 v[22:23], v[26:27], off
	v_mul_f32_e32 v0, v15, v15
	v_mul_f32_e32 v26, v17, v17
	v_fmac_f32_e32 v0, v14, v14
	v_fmac_f32_e32 v26, v16, v16
	v_add_f32_e32 v0, v0, v26
	ds_swizzle_b32 v26, v0 offset:swizzle(SWAP,1)
	s_waitcnt lgkmcnt(0)
	v_add_f32_e32 v0, v0, v26
	ds_swizzle_b32 v26, v0 offset:swizzle(SWAP,2)
	s_waitcnt lgkmcnt(0)
	v_add_f32_e32 v0, v0, v26
	ds_swizzle_b32 v26, v0 offset:swizzle(SWAP,4)
	s_waitcnt lgkmcnt(0)
	v_add_f32_e32 v0, v0, v26
	ds_swizzle_b32 v26, v0 offset:swizzle(SWAP,8)
	s_waitcnt lgkmcnt(0)
	v_add_f32_e32 v0, v0, v26
	ds_swizzle_b32 v26, v0 offset:swizzle(SWAP,16)
	s_waitcnt lgkmcnt(0)
	v_add_f32_e32 v0, v0, v26
	v_mov_b32_e32 v26, v0
	s_nop 1
	v_permlane32_swap_b32_e32 v0, v26
	s_cbranch_scc1 .LBB0_764
	v_add_f32_e32 v0, v0, v26
	v_fmamk_f32 v0, v0, 0x3b800000, v202
	v_mul_f32_e32 v26, 0x4f800000, v0
	v_cmp_gt_f32_e32 vcc, s60, v0
	s_ashr_i32 s11, s10, 31
	s_lshl_b64 s[10:11], s[10:11], 9
	v_cndmask_b32_e32 v0, v0, v26, vcc
	v_sqrt_f32_e32 v26, v0
	s_nop 0
	v_add_u32_e32 v27, -1, v26
	v_fma_f32 v29, -v27, v26, v0
	v_add_u32_e32 v28, 1, v26
	v_cmp_ge_f32_e64 s[38:39], 0, v29
	s_nop 1
	v_cndmask_b32_e64 v27, v26, v27, s[38:39]
	v_fma_f32 v26, -v28, v26, v0
	v_cmp_lt_f32_e64 s[38:39], 0, v26
	s_nop 1
	v_cndmask_b32_e64 v26, v27, v28, s[38:39]
	v_mul_f32_e32 v27, 0x37800000, v26
	v_cndmask_b32_e32 v26, v26, v27, vcc
	v_cmp_class_f32_e32 vcc, v0, v203
	s_nop 1
	v_cndmask_b32_e32 v0, v26, v0, vcc
	v_div_scale_f32 v26, s[14:15], v0, v0, 1.0
	v_rcp_f32_e32 v27, v26
	s_nop 0
	v_fma_f32 v28, -v26, v27, 1.0
	v_fmac_f32_e32 v27, v28, v27
	v_div_scale_f32 v28, vcc, 1.0, v0, 1.0
	v_mul_f32_e32 v29, v28, v27
	v_fma_f32 v30, -v26, v29, v28
	v_fmac_f32_e32 v29, v30, v27
	v_fma_f32 v26, -v26, v29, v28
	v_div_fmas_f32 v26, v26, v27, v29
	v_div_fixup_f32 v0, v26, v0, 1.0
	v_mul_f32_e32 v14, v14, v0
	v_mul_f32_e32 v15, v15, v0
	v_mul_f32_e32 v16, v16, v0
	v_mul_f32_e32 v17, v17, v0
	v_mul_f32_e32 v14, v2, v14
	v_mul_f32_e32 v15, v3, v15
	v_mul_f32_e32 v16, v4, v16
	v_mul_f32_e32 v17, v5, v17
	v_bfe_u32 v0, v14, 16, 1
	v_add3_u32 v0, v14, v0, s94
	v_bfe_u32 v14, v15, 16, 1
	v_lshrrev_b32_e32 v0, 16, v0
	v_add3_u32 v14, v15, v14, s94
	v_and_or_b32 v14, v14, s95, v0
	v_bfe_u32 v0, v16, 16, 1
	v_add3_u32 v0, v16, v0, s94
	v_bfe_u32 v15, v17, 16, 1
	v_lshrrev_b32_e32 v0, 16, v0
	v_add3_u32 v15, v17, v15, s94
	v_and_or_b32 v15, v15, s95, v0
	v_lshl_add_u64 v[16:17], v[20:21], 0, s[10:11]
	global_store_dwordx2 v[16:17], v[14:15], off
; #define GAS __attribute__((address_space(1)))
; __device__ __forceinline__ unsigned pk2(float lo, float hi) { return f2bf(lo) | (f2bf(hi) << 16); }
; __device__ __forceinline__ void ckvnorm_rows(const float* raw, bf16* out, const float* gkv, int w0, int nw, int lane) {
;     ...
;         for (int u = 0; u < 4; ++u) { const int rr = r + u * nw;
;             const float ss = wave_sum((v[u].x * v[u].x + v[u].y * v[u].y) + (v[u].z * v[u].z + v[u].w * v[u].w));
;             const float rstd = 1.0f / sqrtf(ss * (1.0f / 256.0f) + RMS_EPS);
;             const f32x4 y = v[u] * rstd * g;
;             if (rr < M) *(GAS unsigned long long*)(out + (size_t)rr * 256 + 4 * lane) = (unsigned long long)pk2(y.x, y.y) | ((unsigned long long)pk2(y.z, y.w) << 32); }
.LBB0_764:
	v_mul_f32_e32 v0, v11, v11
	v_mul_f32_e32 v14, v13, v13
	v_fmac_f32_e32 v0, v10, v10
	v_fmac_f32_e32 v14, v12, v12
	v_add_f32_e32 v0, v0, v14
	ds_swizzle_b32 v14, v0 offset:swizzle(SWAP,1)
	s_cmpk_gt_i32 s8, 0x3fff
	s_waitcnt lgkmcnt(0)
	v_add_f32_e32 v0, v0, v14
	ds_swizzle_b32 v14, v0 offset:swizzle(SWAP,2)
	s_waitcnt lgkmcnt(0)
	v_add_f32_e32 v0, v0, v14
	ds_swizzle_b32 v14, v0 offset:swizzle(SWAP,4)
	s_waitcnt lgkmcnt(0)
	v_add_f32_e32 v0, v0, v14
	ds_swizzle_b32 v14, v0 offset:swizzle(SWAP,8)
	s_waitcnt lgkmcnt(0)
	v_add_f32_e32 v0, v0, v14
	ds_swizzle_b32 v14, v0 offset:swizzle(SWAP,16)
	s_waitcnt lgkmcnt(0)
	v_add_f32_e32 v0, v0, v14
	v_mov_b32_e32 v14, v0
	s_nop 1
	v_permlane32_swap_b32_e32 v0, v14
	s_cbranch_scc1 .LBB0_766
	v_add_f32_e32 v0, v0, v14
	v_fmamk_f32 v0, v0, 0x3b800000, v202
	v_mul_f32_e32 v14, 0x4f800000, v0
	v_cmp_gt_f32_e32 vcc, s60, v0
	s_ashr_i32 s9, s8, 31
	s_lshl_b64 s[8:9], s[8:9], 9
	v_cndmask_b32_e32 v0, v0, v14, vcc
	v_sqrt_f32_e32 v14, v0
	s_nop 0
	v_add_u32_e32 v15, -1, v14
	v_fma_f32 v17, -v15, v14, v0
	v_add_u32_e32 v16, 1, v14
	v_cmp_ge_f32_e64 s[38:39], 0, v17
	s_nop 1
	v_cndmask_b32_e64 v15, v14, v15, s[38:39]
	v_fma_f32 v14, -v16, v14, v0
	v_cmp_lt_f32_e64 s[38:39], 0, v14
	s_nop 1
	v_cndmask_b32_e64 v14, v15, v16, s[38:39]
	v_mul_f32_e32 v15, 0x37800000, v14
	v_cndmask_b32_e32 v14, v14, v15, vcc
	v_cmp_class_f32_e32 vcc, v0, v203
	s_nop 1
	v_cndmask_b32_e32 v0, v14, v0, vcc
	v_div_scale_f32 v14, s[10:11], v0, v0, 1.0
	v_rcp_f32_e32 v15, v14
	s_nop 0
	v_fma_f32 v16, -v14, v15, 1.0
	v_fmac_f32_e32 v15, v16, v15
	v_div_scale_f32 v16, vcc, 1.0, v0, 1.0
	v_mul_f32_e32 v17, v16, v15
	v_fma_f32 v26, -v14, v17, v16
	v_fmac_f32_e32 v17, v26, v15
	v_fma_f32 v14, -v14, v17, v16
	v_div_fmas_f32 v14, v14, v15, v17
	v_div_fixup_f32 v0, v14, v0, 1.0
	v_mul_f32_e32 v10, v10, v0
	v_mul_f32_e32 v11, v11, v0
	v_mul_f32_e32 v12, v12, v0
	v_mul_f32_e32 v13, v13, v0
	v_mul_f32_e32 v10, v2, v10
	v_mul_f32_e32 v11, v3, v11
	v_mul_f32_e32 v12, v4, v12
	v_mul_f32_e32 v13, v5, v13
	v_bfe_u32 v0, v10, 16, 1
	v_add3_u32 v0, v10, v0, s94
	v_bfe_u32 v10, v11, 16, 1
	v_lshrrev_b32_e32 v0, 16, v0
	v_add3_u32 v10, v11, v10, s94
	v_and_or_b32 v10, v10, s95, v0
	v_bfe_u32 v0, v12, 16, 1
	v_add3_u32 v0, v12, v0, s94
	v_bfe_u32 v11, v13, 16, 1
	v_lshrrev_b32_e32 v0, 16, v0
	v_add3_u32 v11, v13, v11, s94
	v_and_or_b32 v11, v11, s95, v0
	v_lshl_add_u64 v[12:13], v[20:21], 0, s[8:9]
	global_store_dwordx2 v[12:13], v[10:11], off
.LBB0_766:
	v_mul_f32_e32 v0, v7, v7
	v_mul_f32_e32 v10, v9, v9
	v_fmac_f32_e32 v0, v6, v6
	v_fmac_f32_e32 v10, v8, v8
	v_add_f32_e32 v0, v0, v10
	ds_swizzle_b32 v10, v0 offset:swizzle(SWAP,1)
	s_cmpk_gt_i32 s0, 0x3fff
	s_waitcnt lgkmcnt(0)
	v_add_f32_e32 v0, v0, v10
	ds_swizzle_b32 v10, v0 offset:swizzle(SWAP,2)
	s_waitcnt lgkmcnt(0)
	v_add_f32_e32 v0, v0, v10
	ds_swizzle_b32 v10, v0 offset:swizzle(SWAP,4)
	s_waitcnt lgkmcnt(0)
	v_add_f32_e32 v0, v0, v10
	ds_swizzle_b32 v10, v0 offset:swizzle(SWAP,8)
	s_waitcnt lgkmcnt(0)
	v_add_f32_e32 v0, v0, v10
	ds_swizzle_b32 v10, v0 offset:swizzle(SWAP,16)
	s_waitcnt lgkmcnt(0)
	v_add_f32_e32 v0, v0, v10
	v_mov_b32_e32 v10, v0
	s_nop 1
	v_permlane32_swap_b32_e32 v0, v10
	s_cbranch_scc1 .LBB0_761
	v_add_f32_e32 v0, v0, v10
	v_fmamk_f32 v0, v0, 0x3b800000, v202
	v_mul_f32_e32 v10, 0x4f800000, v0
	v_cmp_gt_f32_e32 vcc, s60, v0
	s_ashr_i32 s1, s0, 31
	s_lshl_b64 s[0:1], s[0:1], 9
	v_cndmask_b32_e32 v0, v0, v10, vcc
	v_sqrt_f32_e32 v10, v0
	s_nop 0
	v_add_u32_e32 v11, -1, v10
	v_fma_f32 v13, -v11, v10, v0
	v_add_u32_e32 v12, 1, v10
	v_cmp_ge_f32_e64 s[38:39], 0, v13
	s_nop 1
	v_cndmask_b32_e64 v11, v10, v11, s[38:39]
	v_fma_f32 v10, -v12, v10, v0
	v_cmp_lt_f32_e64 s[38:39], 0, v10
	s_nop 1
	v_cndmask_b32_e64 v10, v11, v12, s[38:39]
	v_mul_f32_e32 v11, 0x37800000, v10
	v_cndmask_b32_e32 v10, v10, v11, vcc
	v_cmp_class_f32_e32 vcc, v0, v203
	s_nop 1
	v_cndmask_b32_e32 v0, v10, v0, vcc
	v_div_scale_f32 v10, s[8:9], v0, v0, 1.0
	v_rcp_f32_e32 v11, v10
	s_nop 0
	v_fma_f32 v12, -v10, v11, 1.0
	v_fmac_f32_e32 v11, v12, v11
	v_div_scale_f32 v12, vcc, 1.0, v0, 1.0
	v_mul_f32_e32 v13, v12, v11
	v_fma_f32 v14, -v10, v13, v12
	v_fmac_f32_e32 v13, v14, v11
	v_fma_f32 v10, -v10, v13, v12
	v_div_fmas_f32 v10, v10, v11, v13
	v_div_fixup_f32 v0, v10, v0, 1.0
	v_mul_f32_e32 v6, v6, v0
	v_mul_f32_e32 v7, v7, v0
	v_mul_f32_e32 v8, v8, v0
	v_mul_f32_e32 v9, v9, v0
	v_mul_f32_e32 v6, v2, v6
	v_mul_f32_e32 v7, v3, v7
	v_mul_f32_e32 v8, v4, v8
	v_mul_f32_e32 v9, v5, v9
	v_bfe_u32 v0, v6, 16, 1
	v_add3_u32 v0, v6, v0, s94
	v_bfe_u32 v6, v7, 16, 1
	v_lshrrev_b32_e32 v0, 16, v0
	v_add3_u32 v6, v7, v6, s94
	v_and_or_b32 v6, v6, s95, v0
	v_bfe_u32 v0, v8, 16, 1
	v_add3_u32 v0, v8, v0, s94
	v_bfe_u32 v7, v9, 16, 1
	v_lshrrev_b32_e32 v0, 16, v0
	v_add3_u32 v7, v9, v7, s94
	v_and_or_b32 v7, v7, s95, v0
	v_lshl_add_u64 v[8:9], v[20:21], 0, s[0:1]
	global_store_dwordx2 v[8:9], v[6:7], off
	s_branch .LBB0_761

; #define LAS __attribute__((address_space(3)))
; #define MFMA32(a, b, c) __builtin_amdgcn_mfma_f32_32x32x16_bf16((a), (b), (c), 0, 0, 0)
; #define NSA_LOAD(Kp, Vp, jb) do { kr = *(const GAS v4u*)((const GAS char*)((Kp) + (size_t)(jb) * 4096) + toff); vr = *(const GAS v4u*)((const GAS char*)((Vp) + (size_t)(jb) * 4096) + toff); } while (0)
; #define NSA_STAGE() do { nsa_stage_store(lds, itc & 1, tid, kr, vr); } while (0)
; #define NSA_BAR() asm volatile("s_waitcnt lgkmcnt(0)\n\ts_barrier" ::: "memory")
; __device__ __forceinline__ void nsa_scores(f32x16& p0, f32x16& p1, LAS const unsigned char* Kt, const bf16x8 (&qr)[4], float cin, int r32, int hi) {
; #pragma unroll
;     for (int r = 0; r < 16; ++r) { p0[r] = cin; p1[r] = cin; }
;     const int sw = (r32 >> 1) & 7;
;     LAS const unsigned char* k0 = Kt + r32 * 128; LAS const unsigned char* k1 = k0 + 32 * 128;
; #pragma unroll
;     for (int d0 = 0; d0 < 4; ++d0) {
;         const int ch = ((2 * d0 + hi) ^ sw) << 4;
;         const bf16x8 a0 = *(LAS const bf16x8*)(k0 + ch), a1 = *(LAS const bf16x8*)(k1 + ch);
;         p0 = MFMA32(a0, qr[d0], p0); p1 = MFMA32(a1, qr[d0], p1);
;     }
; }
; __device__ __forceinline__ void nsa_near(f32x16& p0, f32x16& p1, int dbase, int stride, int lim, LAS const float* lut, int hi) {
;     int db = dbase - stride * 4 * hi; asm volatile("" : "+v"(db));
; #pragma unroll
;     for (int r = 0; r < 16; ++r) {
;         const int d0 = db - stride * ((r & 3) + 8 * (r >> 2)), d1 = d0 - stride * 32;
;         const float b0 = lut[min(max(d0, 0), 127)], b1 = lut[min(max(d1, 0), 127)];
;         p0[r] = (d0 >= 0 && d0 < lim) ? p0[r] + b0 : -INFINITY; p1[r] = (d1 >= 0 && d1 < lim) ? p1[r] + b1 : -INFINITY;
;     }
; }
; __device__ __forceinline__ void nsa_unit(Frame& F, int b, int g, int i, const bf16* QN, const bf16* KV, const bf16* KCMP, const float* GN, bf16* ON, int& itc) {
;     ...
;     for (int jb = 0; jb < ncb; ++jb) {
;         NSA_STAGE(); if (jb + 1 < ncb) NSA_LOAD(Kc, Vc, jb + 1); else NSA_LOAD(Kc, Vc, 0);
;         NSA_BAR();
;         f32x16 p0, p1;
;         const int dmin = tw0 - 31 - 16 * (64 * jb + 63);
;         nsa_scores(p0, p1, NSA_KT, qr, 0.f, r32, hi);
;         float cin = b31;
;         if (dmin < 113) { nsa_near(p0, p1, t - 31 - 1024 * jb, 16, 1 << 30, lut, hi); cin = 0.f; }
.LBB0_892:
	s_add_i32 s34, s26, s14
	s_and_b32 s42, s34, 0x2000
	s_cmp_lt_u32 s16, s22
	v_add_u32_e32 v2, s42, v120
	s_cselect_b64 vcc, -1, 0
	s_add_u32 s34, s0, s14
	s_waitcnt vmcnt(0)
	ds_write_b128 v2, v[96:99]
	v_add_u32_e32 v2, s42, v121
	s_addc_u32 s35, s1, s15
	ds_write_b128 v2, v[100:103] offset:16384
	v_lshl_add_u64 v[2:3], s[34:35], 0, v[110:111]
	s_mov_b64 s[34:35], 0x2000
	v_lshl_add_u64 v[4:5], v[2:3], 0, s[34:35]
	s_mov_b64 s[34:35], 0x82000
	v_lshl_add_u64 v[2:3], v[2:3], 0, s[34:35]
	v_cndmask_b32_e32 v5, v35, v5, vcc
	v_cndmask_b32_e32 v4, v34, v4, vcc
	v_cndmask_b32_e32 v3, v37, v3, vcc
	v_cndmask_b32_e32 v2, v36, v2, vcc
	global_load_dwordx4 v[96:99], v[4:5], off
	global_load_dwordx4 v[100:103], v[2:3], off
	v_add_u32_e32 v43, s42, v122
	s_waitcnt lgkmcnt(0)
	s_barrier
	v_add_u32_e32 v18, v43, v123
	ds_read_b128 v[2:5], v18
	v_add_u32_e32 v44, v43, v124
	ds_read_b128 v[38:41], v44
	s_waitcnt lgkmcnt(0)
	v_mfma_f32_32x32x16_bf16 v[2:17], v[2:5], v[80:83], 0
	ds_read_b128 v[18:21], v18 offset:4096
	s_add_i32 s34, s33, 0xfffffbf1
	s_cmpk_gt_i32 s34, 0x70
	v_mfma_f32_32x32x16_bf16 v[2:17], v[38:41], v[84:87], v[2:17]
	ds_read_b128 v[38:41], v44 offset:4096
	v_add_u32_e32 v44, v43, v125
	v_add_u32_e32 v43, v43, v126
	s_waitcnt lgkmcnt(1)
	v_mfma_f32_32x32x16_bf16 v[18:33], v[18:21], v[80:83], 0
	s_waitcnt lgkmcnt(0)
	v_mfma_f32_32x32x16_bf16 v[18:33], v[38:41], v[84:87], v[18:33]
	ds_read_b128 v[38:41], v44
	s_waitcnt lgkmcnt(0)
	v_mfma_f32_32x32x16_bf16 v[2:17], v[38:41], v[88:91], v[2:17]
	ds_read_b128 v[38:41], v44 offset:4096
	s_waitcnt lgkmcnt(0)
	v_mfma_f32_32x32x16_bf16 v[18:33], v[38:41], v[88:91], v[18:33]
	ds_read_b128 v[38:41], v43
	s_waitcnt lgkmcnt(0)
	v_mfma_f32_32x32x16_bf16 v[2:17], v[38:41], v[92:95], v[2:17]
	ds_read_b128 v[38:41], v43 offset:4096
	s_waitcnt lgkmcnt(0)
	v_mfma_f32_32x32x16_bf16 v[18:33], v[38:41], v[92:95], v[18:33]
	s_cbranch_scc1 .LBB0_894
	v_add_u32_e32 v43, s33, v132
	s_nop 0
	v_subrev_u32_e32 v68, 32, v43
	v_subrev_u32_e32 v67, 48, v43
	v_med3_i32 v44, v68, 0, v205
	v_lshl_add_u32 v46, v44, 2, s21
	v_med3_i32 v44, v67, 0, v205
	v_add_u32_e32 v70, 0xfffffde0, v43
	v_add_u32_e32 v64, -16, v43
	v_add_u32_e32 v65, 0xfffffdf0, v43
	v_add_u32_e32 v66, 0xfffffe00, v43
	v_lshl_add_u32 v47, v44, 2, s21
	v_add_u32_e32 v69, 0xfffffdd0, v43
	v_med3_i32 v44, v70, 0, v205
	v_med3_i32 v38, v43, 0, v205
	v_med3_i32 v39, v64, 0, v205
	v_med3_i32 v40, v66, 0, v205
	v_med3_i32 v41, v65, 0, v205
	v_lshl_add_u32 v48, v44, 2, s21
	v_med3_i32 v44, v69, 0, v205
	v_lshl_add_u32 v38, v38, 2, s21
	v_lshl_add_u32 v39, v39, 2, s21
	v_lshl_add_u32 v40, v40, 2, s21
	v_lshl_add_u32 v41, v41, 2, s21
	v_lshl_add_u32 v49, v44, 2, s21
	v_add_u32_e32 v71, 0xffffff70, v43
	v_add_u32_e32 v72, 0xffffff80, v43
	v_add_u32_e32 v73, 0xfffffd70, v43
	v_add_u32_e32 v74, 0xfffffd80, v43
	v_add_u32_e32 v75, 0xffffff50, v43
	v_add_u32_e32 v76, 0xffffff60, v43
	v_add_u32_e32 v77, 0xfffffd50, v43
	v_add_u32_e32 v78, 0xfffffd60, v43
	v_add_u32_e32 v79, 0xfffffef0, v43
	v_add_u32_e32 v116, 0xffffff00, v43
	v_add_u32_e32 v117, 0xfffffcf0, v43
	v_add_u32_e32 v137, 0xfffffd00, v43
	v_add_u32_e32 v138, 0xfffffed0, v43
	v_add_u32_e32 v139, 0xfffffee0, v43
	v_add_u32_e32 v140, 0xfffffcd0, v43
	v_add_u32_e32 v141, 0xfffffce0, v43
	ds_read_b32 v44, v38
	ds_read_b32 v45, v39
	ds_read_b32 v40, v40
	ds_read_b32 v41, v41
	ds_read_b32 v46, v46
	ds_read_b32 v47, v47
	ds_read_b32 v38, v48
	ds_read_b32 v39, v49
	v_med3_i32 v48, v72, 0, v205
	v_med3_i32 v49, v71, 0, v205
	v_med3_i32 v50, v74, 0, v205
	v_med3_i32 v51, v73, 0, v205
	v_med3_i32 v52, v76, 0, v205
	v_med3_i32 v53, v75, 0, v205
	v_med3_i32 v54, v78, 0, v205
	v_med3_i32 v55, v77, 0, v205
	v_med3_i32 v56, v116, 0, v205
	v_med3_i32 v57, v79, 0, v205
	v_med3_i32 v58, v137, 0, v205
	v_med3_i32 v59, v117, 0, v205
	v_med3_i32 v60, v139, 0, v205
	v_med3_i32 v61, v138, 0, v205
	v_med3_i32 v62, v141, 0, v205
	v_med3_i32 v63, v140, 0, v205
	v_lshl_add_u32 v48, v48, 2, s21
	v_lshl_add_u32 v49, v49, 2, s21
	v_lshl_add_u32 v50, v50, 2, s21
	v_lshl_add_u32 v51, v51, 2, s21
	v_lshl_add_u32 v52, v52, 2, s21
	v_lshl_add_u32 v53, v53, 2, s21
	v_lshl_add_u32 v54, v54, 2, s21
	v_lshl_add_u32 v55, v55, 2, s21
	v_lshl_add_u32 v56, v56, 2, s21
	v_lshl_add_u32 v57, v57, 2, s21
	v_lshl_add_u32 v58, v58, 2, s21
	v_lshl_add_u32 v59, v59, 2, s21
	v_lshl_add_u32 v60, v60, 2, s21
	v_lshl_add_u32 v61, v61, 2, s21
	v_lshl_add_u32 v62, v62, 2, s21
	v_lshl_add_u32 v63, v63, 2, s21
	ds_read_b32 v48, v48
	ds_read_b32 v49, v49
	ds_read_b32 v50, v50
	ds_read_b32 v51, v51
	ds_read_b32 v52, v52
	ds_read_b32 v53, v53
	ds_read_b32 v54, v54
	ds_read_b32 v55, v55
	ds_read_b32 v56, v56
	ds_read_b32 v57, v57
	ds_read_b32 v58, v58
	ds_read_b32 v59, v59
	ds_read_b32 v60, v60
	ds_read_b32 v61, v61
	ds_read_b32 v62, v62
	ds_read_b32 v63, v63
	s_waitcnt lgkmcnt(6)
; #define LAS __attribute__((address_space(3)))
; __device__ __forceinline__ void nsa_near(f32x16& p0, f32x16& p1, int dbase, int stride, int lim, LAS const float* lut, int hi) {
;     int db = dbase - stride * 4 * hi; asm volatile("" : "+v"(db));
; #pragma unroll
;     for (int r = 0; r < 16; ++r) {
;         const int d0 = db - stride * ((r & 3) + 8 * (r >> 2)), d1 = d0 - stride * 32;
;         const float b0 = lut[min(max(d0, 0), 127)], b1 = lut[min(max(d1, 0), 127)];
;         p0[r] = (d0 >= 0 && d0 < lim) ? p0[r] + b0 : -INFINITY; p1[r] = (d1 >= 0 && d1 < lim) ? p1[r] + b1 : -INFINITY;
;     }
	v_add_f32_e32 v10, v10, v56
	v_add_f32_e32 v11, v11, v57
	v_add_u32_e32 v57, 0xfffffc60, v43
	v_add_u32_e32 v143, 0xfffffe80, v43
	v_add_f32_e32 v2, v2, v44
	v_add_f32_e32 v3, v3, v45
	v_add_u32_e32 v56, 0xfffffc50, v43
	v_med3_i32 v44, v57, 0, v205
	v_add_u32_e32 v142, 0xfffffe70, v43
	v_med3_i32 v144, v143, 0, v205
	v_add_u32_e32 v146, 0xfffffc70, v43
	v_add_u32_e32 v147, 0xfffffc80, v43
	v_add_u32_e32 v150, 0xfffffe50, v43
	v_add_u32_e32 v151, 0xfffffe60, v43
	v_add_f32_e32 v4, v4, v46
	v_add_f32_e32 v5, v5, v47
	v_lshl_add_u32 v47, v44, 2, s21
	v_med3_i32 v44, v56, 0, v205
	v_lshl_add_u32 v144, v144, 2, s21
	v_med3_i32 v145, v142, 0, v205
	v_med3_i32 v148, v147, 0, v205
	v_med3_i32 v149, v146, 0, v205
	v_med3_i32 v152, v151, 0, v205
	v_med3_i32 v153, v150, 0, v205
	v_add_f32_e32 v8, v8, v52
	v_add_f32_e32 v9, v9, v53
	v_lshl_add_u32 v53, v44, 2, s21
	v_lshl_add_u32 v145, v145, 2, s21
	v_lshl_add_u32 v148, v148, 2, s21
	v_lshl_add_u32 v149, v149, 2, s21
	v_lshl_add_u32 v152, v152, 2, s21
	v_lshl_add_u32 v153, v153, 2, s21
	v_add_f32_e32 v6, v6, v48
	v_add_f32_e32 v7, v7, v49
	ds_read_b32 v44, v144
	ds_read_b32 v45, v145
	ds_read_b32 v46, v148
	ds_read_b32 v48, v152
	ds_read_b32 v49, v153
	ds_read_b32 v52, v47
	ds_read_b32 v53, v53
	ds_read_b32 v47, v149
	v_cmp_gt_u32_e32 vcc, 2.0, v150
	s_waitcnt lgkmcnt(3)
	v_add_f32_e32 v16, v16, v48
	v_add_f32_e32 v17, v17, v49
	v_add_f32_e32 v14, v14, v44
	v_add_f32_e32 v15, v15, v45
	v_cndmask_b32_e32 v17, v206, v17, vcc
	v_cmp_gt_u32_e32 vcc, 2.0, v151
	v_add_f32_e32 v12, v12, v60
	v_add_f32_e32 v13, v13, v61
	s_waitcnt lgkmcnt(1)
	v_add_f32_e32 v32, v32, v52
	v_add_f32_e32 v33, v33, v53
	v_cndmask_b32_e32 v16, v206, v16, vcc
	v_cmp_gt_u32_e32 vcc, 2.0, v142
	s_waitcnt lgkmcnt(0)
	v_add_f32_e32 v30, v30, v46
	v_add_f32_e32 v31, v31, v47
	v_add_f32_e32 v28, v28, v62
	v_add_f32_e32 v29, v29, v63
	v_cndmask_b32_e32 v15, v206, v15, vcc
	v_cmp_gt_u32_e32 vcc, 2.0, v143
	v_add_f32_e32 v26, v26, v58
	v_add_f32_e32 v27, v27, v59
	v_add_f32_e32 v24, v24, v54
	v_add_f32_e32 v25, v25, v55
	v_cndmask_b32_e32 v14, v206, v14, vcc
	v_cmp_gt_u32_e32 vcc, 2.0, v138
	v_add_f32_e32 v22, v22, v50
	v_add_f32_e32 v23, v23, v51
	v_add_f32_e32 v20, v20, v38
	v_add_f32_e32 v21, v21, v39
	v_cndmask_b32_e32 v13, v206, v13, vcc
	v_cmp_gt_u32_e32 vcc, 2.0, v139
	v_add_f32_e32 v18, v18, v40
	v_add_f32_e32 v19, v19, v41
	v_mov_b32_e32 v38, 0
	v_cndmask_b32_e32 v12, v206, v12, vcc
	v_cmp_gt_u32_e32 vcc, 2.0, v79
	s_nop 1
	v_cndmask_b32_e32 v11, v206, v11, vcc
	v_cmp_gt_u32_e32 vcc, 2.0, v116
	s_nop 1
	v_cndmask_b32_e32 v10, v206, v10, vcc
	v_cmp_gt_u32_e32 vcc, 2.0, v75
	s_nop 1
	v_cndmask_b32_e32 v9, v206, v9, vcc
	v_cmp_gt_u32_e32 vcc, 2.0, v76
	s_nop 1
	v_cndmask_b32_e32 v8, v206, v8, vcc
	v_cmp_gt_u32_e32 vcc, 2.0, v71
	s_nop 1
	v_cndmask_b32_e32 v7, v206, v7, vcc
	v_cmp_gt_u32_e32 vcc, 2.0, v72
	s_nop 1
	v_cndmask_b32_e32 v6, v206, v6, vcc
	v_cmp_gt_u32_e32 vcc, 2.0, v67
	s_nop 1
	v_cndmask_b32_e32 v5, v206, v5, vcc
	v_cmp_gt_u32_e32 vcc, 2.0, v68
	s_nop 1
	v_cndmask_b32_e32 v4, v206, v4, vcc
	v_cmp_gt_u32_e32 vcc, 2.0, v64
	s_nop 1
	v_cndmask_b32_e32 v3, v206, v3, vcc
	v_cmp_gt_u32_e32 vcc, 2.0, v43
	s_nop 1
	v_cndmask_b32_e32 v2, v206, v2, vcc
	v_cmp_gt_u32_e32 vcc, 2.0, v56
	s_nop 1
	v_cndmask_b32_e32 v33, v206, v33, vcc
	v_cmp_gt_u32_e32 vcc, 2.0, v57
	s_nop 1
	v_cndmask_b32_e32 v32, v206, v32, vcc
	v_cmp_gt_u32_e32 vcc, 2.0, v146
	s_nop 1
	v_cndmask_b32_e32 v31, v206, v31, vcc
	v_cmp_gt_u32_e32 vcc, 2.0, v147
	s_nop 1
	v_cndmask_b32_e32 v30, v206, v30, vcc
	v_cmp_gt_u32_e32 vcc, 2.0, v140
	s_nop 1
	v_cndmask_b32_e32 v29, v206, v29, vcc
	v_cmp_gt_u32_e32 vcc, 2.0, v141
	s_nop 1
	v_cndmask_b32_e32 v28, v206, v28, vcc
	v_cmp_gt_u32_e32 vcc, 2.0, v117
	s_nop 1
	v_cndmask_b32_e32 v27, v206, v27, vcc
	v_cmp_gt_u32_e32 vcc, 2.0, v137
	s_nop 1
	v_cndmask_b32_e32 v26, v206, v26, vcc
	v_cmp_gt_u32_e32 vcc, 2.0, v77
	s_nop 1
	v_cndmask_b32_e32 v25, v206, v25, vcc
	v_cmp_gt_u32_e32 vcc, 2.0, v78
	s_nop 1
	v_cndmask_b32_e32 v24, v206, v24, vcc
	v_cmp_gt_u32_e32 vcc, 2.0, v73
	s_nop 1
	v_cndmask_b32_e32 v23, v206, v23, vcc
	v_cmp_gt_u32_e32 vcc, 2.0, v74
	s_nop 1
	v_cndmask_b32_e32 v22, v206, v22, vcc
	v_cmp_gt_u32_e32 vcc, 2.0, v69
	s_nop 1
	v_cndmask_b32_e32 v21, v206, v21, vcc
	v_cmp_gt_u32_e32 vcc, 2.0, v70
	s_nop 1
	v_cndmask_b32_e32 v20, v206, v20, vcc
	v_cmp_gt_u32_e32 vcc, 2.0, v65
	s_nop 1
	v_cndmask_b32_e32 v19, v206, v19, vcc
	v_cmp_gt_u32_e32 vcc, 2.0, v66
	s_nop 1
	v_cndmask_b32_e32 v18, v206, v18, vcc
	s_branch .LBB0_895

; __device__ __forceinline__ void nsa_unit(Frame& F, int b, int g, int i, const bf16* QN, const bf16* KV, const bf16* KCMP, const float* GN, bf16* ON, int& itc) {
;     ...
;         const float mx = nsa_rowmax(p0, p1) + cin, mn = fmaxf(sc.m, mx), alpha = __builtin_amdgcn_exp2f(sc.m - mn), off = mn - cin;
;         sc.m = mn; float sum = 0.f;
; #pragma unroll
;         for (int r = 0; r < 16; ++r) sum += __builtin_amdgcn_exp2f(p0[r] - off) + __builtin_amdgcn_exp2f(p1[r] - off);
;         sc.l = sc.l * alpha + sum;
;         ++itc;
.LBB0_895:
	s_nop 9
	v_maximum3_f32 v39, v3, v19, v19
	v_maximum3_f32 v39, v2, v18, v39
	v_maximum3_f32 v40, v4, v20, v20
	v_maximum3_f32 v41, v5, v21, v21
	v_maximum3_f32 v39, v39, v40, v41
	v_maximum3_f32 v40, v6, v22, v22
	v_maximum3_f32 v41, v7, v23, v23
	v_maximum3_f32 v39, v39, v40, v41
	v_maximum3_f32 v40, v8, v24, v24
	v_maximum3_f32 v41, v9, v25, v25
	v_maximum3_f32 v39, v39, v40, v41
	v_maximum3_f32 v40, v10, v26, v26
	v_maximum3_f32 v41, v11, v27, v27
	v_maximum3_f32 v39, v39, v40, v41
	v_maximum3_f32 v40, v12, v28, v28
	v_maximum3_f32 v41, v13, v29, v29
	v_maximum3_f32 v39, v39, v40, v41
	v_maximum3_f32 v40, v14, v30, v30
	v_maximum3_f32 v41, v15, v31, v31
	v_maximum3_f32 v39, v39, v40, v41
	v_maximum3_f32 v40, v16, v32, v32
	v_maximum3_f32 v41, v17, v33, v33
	v_maximum3_f32 v39, v39, v40, v41
	v_mov_b32_e32 v40, v39
	s_add_u32 s14, s14, 0x2000
	s_nop 0
	v_permlane32_swap_b32_e32 v39, v40
	v_max_f32_e32 v40, v40, v40
	v_max_f32_e32 v39, v39, v39
	v_max_f32_e32 v39, v39, v40
	v_add_f32_e32 v39, v38, v39
	v_max_f32_e32 v40, v42, v42
	v_max_f32_e32 v137, v40, v39
	v_sub_f32_e32 v38, v137, v38
	v_sub_f32_e32 v2, v2, v38
	v_sub_f32_e32 v18, v18, v38
	v_exp_f32_e32 v2, v2
	v_exp_f32_e32 v18, v18
	v_sub_f32_e32 v3, v3, v38
	v_exp_f32_e32 v3, v3
	v_sub_f32_e32 v4, v4, v38
	v_add_f32_e32 v2, v2, v18
	v_sub_f32_e32 v18, v19, v38
	v_exp_f32_e32 v18, v18
	v_sub_f32_e32 v19, v20, v38
	v_exp_f32_e32 v4, v4
	v_exp_f32_e32 v19, v19
	v_add_f32_e32 v2, 0, v2
	v_add_f32_e32 v3, v3, v18
	v_add_f32_e32 v2, v3, v2
	v_add_f32_e32 v3, v4, v19
	v_add_f32_e32 v3, v3, v2
	v_sub_f32_e32 v2, v5, v38
	v_exp_f32_e32 v5, v2
	v_sub_f32_e32 v2, v21, v38
	v_exp_f32_e32 v18, v2
	v_sub_f32_e32 v2, v6, v38
	v_exp_f32_e32 v6, v2
	v_sub_f32_e32 v2, v22, v38
	v_exp_f32_e32 v19, v2
	v_sub_f32_e32 v2, v7, v38
	v_sub_f32_e32 v4, v23, v38
	v_exp_f32_e32 v2, v2
	v_exp_f32_e32 v4, v4
	v_add_f32_e32 v5, v5, v18
	v_add_f32_e32 v5, v5, v3
	v_add_f32_e32 v3, v6, v19
	v_add_f32_e32 v2, v2, v4
	v_add_f32_e32 v3, v3, v5
	v_sub_f32_e32 v7, v42, v137
	v_add_f32_e32 v3, v2, v3
	v_add_f32_e32 v2, v2, v2
	v_sub_f32_e32 v2, v8, v38
	v_exp_f32_e32 v5, v2
	v_sub_f32_e32 v2, v24, v38
	v_exp_f32_e32 v6, v2
	v_sub_f32_e32 v2, v9, v38
	v_exp_f32_e32 v4, v2
	v_sub_f32_e32 v2, v25, v38
	v_exp_f32_e32 v2, v2
	v_add_f32_e32 v5, v5, v6
	s_addc_u32 s15, s15, 0
	s_addk_i32 s33, 0xfc00
	v_add_f32_e32 v2, v4, v2
	v_add_f32_e32 v3, v5, v3
	s_add_i32 s16, s16, 1
	v_add_f32_e32 v3, v2, v3
	v_add_f32_e32 v2, v2, v2
	v_sub_f32_e32 v2, v10, v38
	v_exp_f32_e32 v5, v2
	v_sub_f32_e32 v2, v26, v38
	v_exp_f32_e32 v6, v2
	v_sub_f32_e32 v2, v11, v38
	v_exp_f32_e32 v4, v2
	v_sub_f32_e32 v2, v27, v38
	v_exp_f32_e32 v2, v2
	v_add_f32_e32 v5, v5, v6
	s_cmp_eq_u32 s27, s14
	v_add_f32_e32 v2, v4, v2
	v_add_f32_e32 v3, v5, v3
	s_nop 0
	v_add_f32_e32 v3, v2, v3
	v_add_f32_e32 v2, v2, v2
	v_sub_f32_e32 v2, v12, v38
	v_exp_f32_e32 v5, v2
	v_sub_f32_e32 v2, v28, v38
	v_exp_f32_e32 v6, v2
	v_sub_f32_e32 v2, v13, v38
	v_exp_f32_e32 v4, v2
	v_sub_f32_e32 v2, v29, v38
	v_exp_f32_e32 v2, v2
	v_add_f32_e32 v5, v5, v6
	v_add_f32_e32 v2, v4, v2
	v_add_f32_e32 v3, v5, v3
	s_nop 0
	v_add_f32_e32 v3, v2, v3
	v_add_f32_e32 v2, v2, v2
	v_sub_f32_e32 v2, v14, v38
	v_exp_f32_e32 v5, v2
	v_sub_f32_e32 v2, v30, v38
	v_exp_f32_e32 v6, v2
	v_sub_f32_e32 v2, v15, v38
	v_exp_f32_e32 v4, v2
	v_sub_f32_e32 v2, v31, v38
	v_exp_f32_e32 v2, v2
	v_add_f32_e32 v5, v5, v6
	v_add_f32_e32 v2, v4, v2
	v_add_f32_e32 v3, v5, v3
	s_nop 0
	v_add_f32_e32 v3, v2, v3
	v_add_f32_e32 v2, v2, v2
	v_sub_f32_e32 v2, v16, v38
	v_exp_f32_e32 v5, v2
	v_sub_f32_e32 v2, v32, v38
	v_exp_f32_e32 v6, v2
	v_sub_f32_e32 v2, v17, v38
	v_exp_f32_e32 v4, v2
	v_sub_f32_e32 v2, v33, v38
	v_exp_f32_e32 v2, v2
	v_add_f32_e32 v5, v5, v6
	v_add_f32_e32 v2, v4, v2
	v_add_f32_e32 v3, v5, v3
	s_nop 0
	v_add_f32_e32 v2, v2, v3
	v_exp_f32_e32 v3, v7
	s_nop 0
	v_fmac_f32_e32 v2, v0, v3
	s_cbranch_scc1 .LBB0_897
	v_mov_b32_e32 v0, v2
	v_mov_b32_e32 v42, v137
	s_branch .LBB0_892

; #define NSA_LOAD(Kp, Vp, jb) do { kr = *(const GAS v4u*)((const GAS char*)((Kp) + (size_t)(jb) * 4096) + toff); vr = *(const GAS v4u*)((const GAS char*)((Vp) + (size_t)(jb) * 4096) + toff); } while (0)
; #define NSA_STAGE() do { nsa_stage_store(lds, itc & 1, tid, kr, vr); } while (0)
; #define NSA_BAR() asm volatile("s_waitcnt lgkmcnt(0)\n\ts_barrier" ::: "memory")
; __device__ __forceinline__ void nsa_unit(Frame& F, int b, int g, int i, const bf16* QN, const bf16* KV, const bf16* KCMP, const float* GN, bf16* ON, int& itc) {
;     ...
;             if (jb < ncb) {
;                 NSA_STAGE(); if (jb + 1 < ncb) NSA_LOAD(Kc, Vc, jb + 1);
;                 NSA_BAR();
;                 f32x16 p0, p1;
;                 const int dmin = tw0 - 31 - 16 * (64 * jb + 63);
;                 nsa_scores(p0, p1, NSA_KT, qr, 0.f, r32, hi);
;                 float off = sc.m - b31;
;                 if (dmin < 113) { nsa_near(p0, p1, t - 31 - 1024 * jb, 16, 1 << 30, lut, hi); off = sc.m; }
.LBB0_903:
	v_add_u32_e32 v0, s26, v122
	s_waitcnt lgkmcnt(0)
	s_barrier
	v_add_u32_e32 v6, v0, v123
	ds_read_b128 v[2:5], v6
	s_add_i32 s27, s17, 0xfffffbf1
	s_cmpk_gt_i32 s27, 0x70
	s_waitcnt lgkmcnt(0)
	v_mfma_f32_32x32x16_bf16 v[48:63], v[2:5], v[80:83], 0
	ds_read_b128 v[2:5], v6 offset:4096
	v_add_u32_e32 v6, v0, v124
	s_waitcnt lgkmcnt(0)
	v_mfma_f32_32x32x16_bf16 v[64:79], v[2:5], v[80:83], 0
	ds_read_b128 v[2:5], v6
	s_waitcnt lgkmcnt(0)
	v_mfma_f32_32x32x16_bf16 v[48:63], v[2:5], v[84:87], v[48:63]
	ds_read_b128 v[2:5], v6 offset:4096
	v_add_u32_e32 v6, v0, v125
	v_add_u32_e32 v0, v0, v126
	s_waitcnt lgkmcnt(0)
	v_mfma_f32_32x32x16_bf16 v[64:79], v[2:5], v[84:87], v[64:79]
	ds_read_b128 v[2:5], v6
	s_waitcnt lgkmcnt(0)
	v_mfma_f32_32x32x16_bf16 v[48:63], v[2:5], v[88:91], v[48:63]
	ds_read_b128 v[2:5], v6 offset:4096
	s_waitcnt lgkmcnt(0)
	v_mfma_f32_32x32x16_bf16 v[64:79], v[2:5], v[88:91], v[64:79]
	ds_read_b128 v[2:5], v0
	s_waitcnt lgkmcnt(0)
	v_mfma_f32_32x32x16_bf16 v[48:63], v[2:5], v[92:95], v[48:63]
	ds_read_b128 v[2:5], v0 offset:4096
	s_waitcnt lgkmcnt(0)
	v_mfma_f32_32x32x16_bf16 v[64:79], v[2:5], v[92:95], v[64:79]
	s_cbranch_scc1 .LBB0_905
	v_add_u32_e32 v0, s17, v132
	s_nop 0
	v_subrev_u32_e32 v155, 32, v0
	v_subrev_u32_e32 v154, 48, v0
	v_med3_i32 v6, v155, 0, v205
	v_lshl_add_u32 v8, v6, 2, s21
	v_med3_i32 v6, v154, 0, v205
	v_add_u32_e32 v157, 0xfffffde0, v0
	v_add_u32_e32 v141, -16, v0
	v_add_u32_e32 v152, 0xfffffdf0, v0
	v_add_u32_e32 v153, 0xfffffe00, v0
	v_lshl_add_u32 v9, v6, 2, s21
	v_add_u32_e32 v156, 0xfffffdd0, v0
	v_med3_i32 v6, v157, 0, v205
	v_med3_i32 v2, v0, 0, v205
	v_med3_i32 v3, v141, 0, v205
	v_med3_i32 v4, v153, 0, v205
	v_med3_i32 v5, v152, 0, v205
	v_lshl_add_u32 v10, v6, 2, s21
	v_med3_i32 v6, v156, 0, v205
	v_lshl_add_u32 v2, v2, 2, s21
	v_lshl_add_u32 v3, v3, 2, s21
	v_lshl_add_u32 v4, v4, 2, s21
	v_lshl_add_u32 v5, v5, 2, s21
	v_lshl_add_u32 v11, v6, 2, s21
	v_add_u32_e32 v158, 0xffffff70, v0
	v_add_u32_e32 v159, 0xffffff80, v0
	v_add_u32_e32 v160, 0xfffffd70, v0
	v_add_u32_e32 v161, 0xfffffd80, v0
	v_add_u32_e32 v162, 0xffffff50, v0
	v_add_u32_e32 v163, 0xffffff60, v0
	v_add_u32_e32 v164, 0xfffffd50, v0
	v_add_u32_e32 v165, 0xfffffd60, v0
	v_add_u32_e32 v166, 0xfffffef0, v0
	v_add_u32_e32 v167, 0xffffff00, v0
	v_add_u32_e32 v168, 0xfffffcf0, v0
	v_add_u32_e32 v169, 0xfffffd00, v0
	v_add_u32_e32 v170, 0xfffffed0, v0
	v_add_u32_e32 v171, 0xfffffee0, v0
	v_add_u32_e32 v177, 0xfffffcd0, v0
	v_add_u32_e32 v178, 0xfffffce0, v0
	ds_read_b32 v6, v2
	ds_read_b32 v7, v3
	ds_read_b32 v4, v4
	ds_read_b32 v5, v5
	ds_read_b32 v8, v8
	ds_read_b32 v9, v9
	ds_read_b32 v2, v10
	ds_read_b32 v3, v11
	v_med3_i32 v10, v159, 0, v205
	v_med3_i32 v11, v158, 0, v205
	v_med3_i32 v12, v161, 0, v205
	v_med3_i32 v13, v160, 0, v205
	v_med3_i32 v14, v163, 0, v205
	v_med3_i32 v15, v162, 0, v205
	v_med3_i32 v142, v165, 0, v205
	v_med3_i32 v143, v164, 0, v205
	v_med3_i32 v144, v167, 0, v205
	v_med3_i32 v145, v166, 0, v205
	v_med3_i32 v146, v169, 0, v205
	v_med3_i32 v147, v168, 0, v205
	v_med3_i32 v148, v171, 0, v205
	v_med3_i32 v149, v170, 0, v205
	v_med3_i32 v150, v178, 0, v205
	v_med3_i32 v151, v177, 0, v205
	v_lshl_add_u32 v10, v10, 2, s21
	v_lshl_add_u32 v11, v11, 2, s21
	v_lshl_add_u32 v12, v12, 2, s21
	v_lshl_add_u32 v13, v13, 2, s21
	v_lshl_add_u32 v14, v14, 2, s21
	v_lshl_add_u32 v15, v15, 2, s21
	v_lshl_add_u32 v142, v142, 2, s21
	v_lshl_add_u32 v143, v143, 2, s21
	v_lshl_add_u32 v144, v144, 2, s21
	v_lshl_add_u32 v145, v145, 2, s21
	v_lshl_add_u32 v146, v146, 2, s21
	v_lshl_add_u32 v147, v147, 2, s21
	v_lshl_add_u32 v148, v148, 2, s21
	v_lshl_add_u32 v149, v149, 2, s21
	v_lshl_add_u32 v150, v150, 2, s21
	v_lshl_add_u32 v151, v151, 2, s21
	ds_read_b32 v10, v10
	ds_read_b32 v11, v11
	ds_read_b32 v12, v12
	ds_read_b32 v13, v13
	ds_read_b32 v14, v14
	ds_read_b32 v15, v15
	ds_read_b32 v142, v142
	ds_read_b32 v143, v143
	ds_read_b32 v144, v144
	ds_read_b32 v145, v145
	ds_read_b32 v146, v146
	ds_read_b32 v147, v147
	ds_read_b32 v148, v148
	ds_read_b32 v149, v149
	ds_read_b32 v150, v150
	ds_read_b32 v151, v151
	v_add_u32_e32 v180, 0xfffffe80, v0
	v_add_u32_e32 v192, 0xfffffc60, v0
	v_add_u32_e32 v179, 0xfffffe70, v0
	v_med3_i32 v181, v180, 0, v205
	v_add_u32_e32 v183, 0xfffffc70, v0
	v_add_u32_e32 v184, 0xfffffc80, v0
	v_add_u32_e32 v187, 0xfffffe50, v0
	v_add_u32_e32 v188, 0xfffffe60, v0
	s_waitcnt lgkmcnt(14)
; #define LAS __attribute__((address_space(3)))
; __device__ __forceinline__ void nsa_near(f32x16& p0, f32x16& p1, int dbase, int stride, int lim, LAS const float* lut, int hi) {
;     int db = dbase - stride * 4 * hi; asm volatile("" : "+v"(db));
; #pragma unroll
;     for (int r = 0; r < 16; ++r) {
;         const int d0 = db - stride * ((r & 3) + 8 * (r >> 2)), d1 = d0 - stride * 32;
;         const float b0 = lut[min(max(d0, 0), 127)], b1 = lut[min(max(d1, 0), 127)];
;         p0[r] = (d0 >= 0 && d0 < lim) ? p0[r] + b0 : -INFINITY; p1[r] = (d1 >= 0 && d1 < lim) ? p1[r] + b1 : -INFINITY;
;     }
	v_add_f32_e32 v10, v52, v10
	v_add_f32_e32 v11, v53, v11
	v_add_u32_e32 v191, 0xfffffc50, v0
	v_med3_i32 v52, v192, 0, v205
	v_lshl_add_u32 v181, v181, 2, s21
	v_med3_i32 v182, v179, 0, v205
	v_med3_i32 v185, v184, 0, v205
	v_med3_i32 v186, v183, 0, v205
	v_med3_i32 v189, v188, 0, v205
	v_med3_i32 v190, v187, 0, v205
	v_add_f32_e32 v6, v48, v6
	v_add_f32_e32 v7, v49, v7
	s_waitcnt lgkmcnt(6)
	v_add_f32_e32 v48, v56, v144
	v_add_f32_e32 v49, v57, v145
	v_lshl_add_u32 v56, v52, 2, s21
	v_med3_i32 v52, v191, 0, v205
	v_lshl_add_u32 v182, v182, 2, s21
	v_lshl_add_u32 v185, v185, 2, s21
	v_lshl_add_u32 v186, v186, 2, s21
	v_lshl_add_u32 v189, v189, 2, s21
	v_lshl_add_u32 v190, v190, 2, s21
	v_add_f32_e32 v8, v50, v8
	v_add_f32_e32 v9, v51, v9
	v_add_f32_e32 v14, v54, v14
	v_add_f32_e32 v15, v55, v15
	s_waitcnt lgkmcnt(2)
	v_add_f32_e32 v50, v58, v148
	v_add_f32_e32 v51, v59, v149
	v_lshl_add_u32 v57, v52, 2, s21
	ds_read_b32 v52, v181
	ds_read_b32 v53, v182
	ds_read_b32 v144, v185
	ds_read_b32 v54, v189
	ds_read_b32 v55, v190
	ds_read_b32 v148, v56
	ds_read_b32 v149, v57
	ds_read_b32 v145, v186
	v_cmp_gt_u32_e32 vcc, 2.0, v187
	s_waitcnt lgkmcnt(3)
	v_add_f32_e32 v54, v62, v54
	v_add_f32_e32 v55, v63, v55
	v_add_f32_e32 v52, v60, v52
	v_add_f32_e32 v53, v61, v53
	v_cndmask_b32_e32 v63, v206, v55, vcc
	v_cmp_gt_u32_e32 vcc, 2.0, v188
	v_add_f32_e32 v4, v64, v4
	v_add_f32_e32 v5, v65, v5
	s_waitcnt lgkmcnt(1)
	v_add_f32_e32 v64, v78, v148
	v_add_f32_e32 v65, v79, v149
	v_cndmask_b32_e32 v62, v206, v54, vcc
	v_cmp_gt_u32_e32 vcc, 2.0, v179
	v_add_f32_e32 v2, v66, v2
	v_add_f32_e32 v3, v67, v3
	s_nop 0
	v_cndmask_b32_e32 v61, v206, v53, vcc
	v_cmp_gt_u32_e32 vcc, 2.0, v180
	s_nop 1
	v_cndmask_b32_e32 v60, v206, v52, vcc
	v_cmp_gt_u32_e32 vcc, 2.0, v170
	s_nop 1
	v_cndmask_b32_e32 v59, v206, v51, vcc
	v_cmp_gt_u32_e32 vcc, 2.0, v171
	s_nop 1
	v_cndmask_b32_e32 v58, v206, v50, vcc
	v_cmp_gt_u32_e32 vcc, 2.0, v166
	s_nop 1
	v_cndmask_b32_e32 v57, v206, v49, vcc
	v_cmp_gt_u32_e32 vcc, 2.0, v167
	s_nop 1
	v_cndmask_b32_e32 v56, v206, v48, vcc
	v_cmp_gt_u32_e32 vcc, 2.0, v162
	s_nop 1
	v_cndmask_b32_e32 v55, v206, v15, vcc
	v_cmp_gt_u32_e32 vcc, 2.0, v163
	s_nop 1
	v_cndmask_b32_e32 v54, v206, v14, vcc
	v_cmp_gt_u32_e32 vcc, 2.0, v158
	s_waitcnt lgkmcnt(0)
	v_add_f32_e32 v14, v76, v144
	v_add_f32_e32 v15, v77, v145
	v_cndmask_b32_e32 v53, v206, v11, vcc
	v_cmp_gt_u32_e32 vcc, 2.0, v159
	s_nop 1
	v_cndmask_b32_e32 v52, v206, v10, vcc
	v_cmp_gt_u32_e32 vcc, 2.0, v154
	v_add_f32_e32 v10, v72, v146
	v_add_f32_e32 v11, v73, v147
	s_nop 0
	v_cndmask_b32_e32 v51, v206, v9, vcc
	v_cmp_gt_u32_e32 vcc, 2.0, v155
	s_nop 1
	v_cndmask_b32_e32 v50, v206, v8, vcc
	v_cmp_gt_u32_e32 vcc, 2.0, v141
	v_add_f32_e32 v8, v70, v142
	v_add_f32_e32 v9, v71, v143
	s_nop 0
	v_cndmask_b32_e32 v49, v206, v7, vcc
	v_cmp_gt_u32_e32 vcc, 2.0, v0
	v_mov_b32_e32 v0, v137
	s_nop 0
	v_cndmask_b32_e32 v48, v206, v6, vcc
	v_cmp_gt_u32_e32 vcc, 2.0, v191
	v_add_f32_e32 v6, v68, v12
	v_add_f32_e32 v7, v69, v13
	v_add_f32_e32 v12, v74, v150
	v_add_f32_e32 v13, v75, v151
	v_cndmask_b32_e32 v79, v206, v65, vcc
	v_cmp_gt_u32_e32 vcc, 2.0, v192
	s_nop 1
	v_cndmask_b32_e32 v78, v206, v64, vcc
	v_cmp_gt_u32_e32 vcc, 2.0, v183
	s_nop 1
	v_cndmask_b32_e32 v77, v206, v15, vcc
	v_cmp_gt_u32_e32 vcc, 2.0, v184
	s_nop 1
	v_cndmask_b32_e32 v76, v206, v14, vcc
	v_cmp_gt_u32_e32 vcc, 2.0, v177
	s_nop 1
	v_cndmask_b32_e32 v75, v206, v13, vcc
	v_cmp_gt_u32_e32 vcc, 2.0, v178
	s_nop 1
	v_cndmask_b32_e32 v74, v206, v12, vcc
	v_cmp_gt_u32_e32 vcc, 2.0, v168
	s_nop 1
	v_cndmask_b32_e32 v73, v206, v11, vcc
	v_cmp_gt_u32_e32 vcc, 2.0, v169
	s_nop 1
	v_cndmask_b32_e32 v72, v206, v10, vcc
	v_cmp_gt_u32_e32 vcc, 2.0, v164
	s_nop 1
	v_cndmask_b32_e32 v71, v206, v9, vcc
	v_cmp_gt_u32_e32 vcc, 2.0, v165
	s_nop 1
	v_cndmask_b32_e32 v70, v206, v8, vcc
	v_cmp_gt_u32_e32 vcc, 2.0, v160
	s_nop 1
	v_cndmask_b32_e32 v69, v206, v7, vcc
	v_cmp_gt_u32_e32 vcc, 2.0, v161
	s_nop 1
	v_cndmask_b32_e32 v68, v206, v6, vcc
	v_cmp_gt_u32_e32 vcc, 2.0, v156
	s_nop 1
	v_cndmask_b32_e32 v67, v206, v3, vcc
	v_cmp_gt_u32_e32 vcc, 2.0, v157
	s_nop 1
	v_cndmask_b32_e32 v66, v206, v2, vcc
	v_cmp_gt_u32_e32 vcc, 2.0, v152
	s_nop 1
	v_cndmask_b32_e32 v65, v206, v5, vcc
	v_cmp_gt_u32_e32 vcc, 2.0, v153
	s_nop 1
	v_cndmask_b32_e32 v64, v206, v4, vcc
	s_branch .LBB0_906

; __device__ __forceinline__ float xget32(float v, bool upper) { const SwapPair r = swap32(v); return __builtin_bit_cast(float, upper ? r.a : r.b); }
; __device__ __forceinline__ void nsa_unit(Frame& F, int b, int g, int i, const bf16* QN, const bf16* KV, const bf16* KCMP, const float* GN, bf16* ON, int& itc) {
;     ...
; #pragma unroll
;                 for (int r = 0; r < 16; ++r) { p0[r] = __builtin_amdgcn_exp2f(p0[r] - off) * inv; p1[r] = __builtin_amdgcn_exp2f(p1[r] - off) * inv; }
;                 X[0] = hi ? 0.f : carry;
; #pragma unroll
;                 for (int a = 0; a < 8; ++a) {
;                     const int ra = 4 * (a & 3);
;                     const float e0 = a < 4 ? p0[ra] : p1[ra], e1 = a < 4 ? p0[ra + 1] : p1[ra + 1], e2 = a < 4 ? p0[ra + 2] : p1[ra + 2], e3 = a < 4 ? p0[ra + 3] : p1[ra + 3];
;                     const float other = xget32(e3, hi != 0);
;                     X[a] += (e0 + e1) + (e2 + e3);
;                     if (hi) X[a] += other; else { if (a < 7) X[a + 1] += other; else carry = other; }
;                 }
;                 bf16x8 pk[4]; nsa_pack(pk, p0, p1);
;                 nsa_pv(o0, o1, NSA_VT, pk, lane);
.LBB0_906:
	s_nop 6
	v_sub_f32_e32 v2, v48, v0
	v_exp_f32_e32 v3, v2
	s_nop 0
	v_sub_f32_e32 v2, v64, v0
	v_exp_f32_e32 v5, v2
	v_sub_f32_e32 v2, v49, v0
	v_exp_f32_e32 v7, v2
	v_sub_f32_e32 v2, v65, v0
	v_exp_f32_e32 v9, v2
	v_sub_f32_e32 v2, v50, v0
	v_exp_f32_e32 v11, v2
	v_sub_f32_e32 v2, v66, v0
	v_sub_f32_e32 v50, v56, v0
	v_exp_f32_e32 v15, v2
	v_sub_f32_e32 v2, v51, v0
	v_exp_f32_e32 v51, v50
	v_sub_f32_e32 v50, v72, v0
	v_sub_f32_e32 v6, v53, v0
	v_sub_f32_e32 v12, v70, v0
	v_exp_f32_e32 v53, v50
	v_sub_f32_e32 v50, v57, v0
	v_exp_f32_e32 v14, v12
	v_sub_f32_e32 v12, v55, v0
	v_exp_f32_e32 v55, v50
	v_sub_f32_e32 v50, v73, v0
	v_exp_f32_e32 v13, v2
	v_exp_f32_e32 v12, v12
	v_exp_f32_e32 v57, v50
	v_sub_f32_e32 v50, v58, v0
	v_exp_f32_e32 v65, v50
	v_sub_f32_e32 v50, v74, v0
	v_sub_f32_e32 v2, v67, v0
	v_exp_f32_e32 v67, v50
	v_sub_f32_e32 v50, v59, v0
	v_sub_f32_e32 v58, v62, v0
	v_exp_f32_e32 v59, v50
	v_sub_f32_e32 v50, v75, v0
	v_exp_f32_e32 v64, v58
	v_sub_f32_e32 v58, v78, v0
	v_exp_f32_e32 v49, v2
	v_sub_f32_e32 v2, v52, v0
	v_sub_f32_e32 v4, v68, v0
	v_sub_f32_e32 v8, v69, v0
	v_sub_f32_e32 v10, v54, v0
	v_sub_f32_e32 v48, v71, v0
	v_exp_f32_e32 v69, v50
	v_sub_f32_e32 v50, v60, v0
	v_sub_f32_e32 v52, v76, v0
	v_sub_f32_e32 v54, v61, v0
	v_sub_f32_e32 v56, v77, v0
	v_exp_f32_e32 v66, v58
	v_sub_f32_e32 v58, v63, v0
	v_sub_f32_e32 v0, v79, v0
	v_mul_f32_e32 v146, v116, v12
	v_mul_f32_e32 v147, v117, v13
	v_exp_f32_e32 v68, v0
	v_mov_b32_e32 v0, v147
	v_exp_f32_e32 v6, v6
	v_exp_f32_e32 v48, v48
	v_mov_b32_e32 v12, v147
	v_exp_f32_e32 v2, v2
	v_exp_f32_e32 v10, v10
	v_exp_f32_e32 v54, v54
	v_exp_f32_e32 v58, v58
	v_permlane32_swap_b32_e32 v12, v0
	v_cndmask_b32_e64 v13, v0, v12, s[38:39]
	v_add_f32_e32 v0, 0, v13
	v_mul_f32_e32 v74, v116, v48
	v_mul_f32_e32 v75, v117, v49
	v_mul_f32_e32 v6, v116, v6
	v_mul_f32_e32 v7, v117, v7
	v_cndmask_b32_e64 v48, v0, 0, s[38:39]
	v_mov_b32_e32 v0, v146
	v_mul_f32_e32 v78, v116, v54
	v_mul_f32_e32 v79, v117, v55
	v_mul_f32_e32 v58, v116, v58
	v_mul_f32_e32 v59, v117, v59
	v_mul_f32_e32 v54, v116, v2
	v_mul_f32_e32 v55, v117, v3
	v_mul_f32_e32 v144, v116, v10
	v_mul_f32_e32 v145, v117, v11
	v_mov_b32_e32 v12, v146
	v_fma_f32 v2, v116, v2, v6
	v_fma_f32 v3, v117, v3, v7
	v_fma_f32 v10, v116, v10, v146
	v_fma_f32 v11, v117, v11, v147
	v_exp_f32_e32 v50, v50
	v_cndmask_b32_e64 v49, v139, 0, s[38:39]
	v_permlane32_swap_b32_e32 v12, v0
	v_add_f32_e32 v2, v2, v10
	v_add_f32_e32 v3, v3, v11
	v_mov_b32_e32 v10, v59
	v_add_f32_e32 v2, v2, v48
	v_add_f32_e32 v3, v3, v49
	v_mov_b32_e32 v11, v59
	v_cndmask_b32_e64 v49, v0, v12, s[38:39]
	s_nop 0
	v_permlane32_swap_b32_e32 v11, v10
	v_mov_b32_e32 v12, v49
	v_cndmask_b32_e64 v48, v10, v11, s[38:39]
	v_add_f32_e32 v10, v2, v12
	v_add_f32_e32 v11, v3, v13
	v_mul_f32_e32 v76, v116, v50
	v_mul_f32_e32 v77, v117, v51
	v_cndmask_b32_e64 v10, v2, v10, s[38:39]
	v_cndmask_b32_e64 v0, v3, v11, s[38:39]
	v_add_f32_e32 v2, 0, v48
	v_add_f32_e32 v3, 0, v49
	v_fma_f32 v12, v116, v50, v78
	v_fma_f32 v13, v117, v51, v79
	v_fma_f32 v50, v116, v64, v58
	v_fma_f32 v51, v117, v65, v59
	v_cndmask_b32_e64 v3, v3, 0, s[38:39]
	v_cndmask_b32_e64 v2, v2, 0, s[38:39]
	v_add_f32_e32 v12, v12, v50
	v_add_f32_e32 v13, v13, v51
	v_mov_b32_e32 v11, v58
	v_add_f32_e32 v2, v12, v2
	v_add_f32_e32 v3, v13, v3
	v_mov_b32_e32 v12, v75
	v_exp_f32_e32 v8, v8
	v_mov_b32_e32 v49, v58
	v_mov_b32_e32 v13, v75
	v_exp_f32_e32 v4, v4
	v_exp_f32_e32 v56, v56
	v_permlane32_swap_b32_e32 v49, v11
	v_permlane32_swap_b32_e32 v13, v12
	v_cndmask_b32_e64 v51, v11, v49, s[38:39]
	v_cndmask_b32_e64 v50, v12, v13, s[38:39]
	v_pk_mov_b32 v[12:13], v[50:51], v[48:49] op_sel:[1,0]
	v_mul_f32_e32 v8, v116, v8
	v_mul_f32_e32 v9, v117, v9
	v_add_f32_e32 v12, v2, v12
	v_add_f32_e32 v13, v3, v13
	v_mul_f32_e32 v62, v116, v56
	v_mul_f32_e32 v63, v117, v57
	v_mul_f32_e32 v56, v116, v4
	v_mul_f32_e32 v57, v117, v5
	v_mul_f32_e32 v72, v116, v14
	v_mul_f32_e32 v73, v117, v15
	v_cndmask_b32_e64 v12, v2, v12, s[38:39]
	v_cndmask_b32_e64 v11, v3, v13, s[38:39]
	v_add_f32_e32 v2, 0, v50
	v_add_f32_e32 v3, 0, v51
	v_fma_f32 v4, v116, v4, v8
	v_fma_f32 v5, v117, v5, v9
	v_fma_f32 v14, v116, v14, v74
	v_fma_f32 v15, v117, v15, v75
	v_mul_f32_e32 v68, v116, v68
	v_mul_f32_e32 v69, v117, v69
	v_cndmask_b32_e64 v3, v3, 0, s[38:39]
	v_cndmask_b32_e64 v2, v2, 0, s[38:39]
	v_add_f32_e32 v4, v4, v14
	v_add_f32_e32 v5, v5, v15
	v_mov_b32_e32 v13, v74
	v_add_f32_e32 v2, v4, v2
	v_add_f32_e32 v3, v5, v3
	v_mov_b32_e32 v4, v69
	v_mov_b32_e32 v48, v74
	v_mov_b32_e32 v14, v69
	v_exp_f32_e32 v52, v52
	v_permlane32_swap_b32_e32 v48, v13
	v_permlane32_swap_b32_e32 v14, v4
	v_cndmask_b32_e64 v5, v13, v48, s[38:39]
	v_cndmask_b32_e64 v4, v4, v14, s[38:39]
	v_mov_b32_e32 v13, v68
	v_pk_mov_b32 v[14:15], v[4:5], v[50:51] op_sel:[1,0]
	v_mov_b32_e32 v48, v68
	v_add_f32_e32 v14, v2, v14
	v_add_f32_e32 v15, v3, v15
	s_nop 0
	v_permlane32_swap_b32_e32 v48, v13
	v_cndmask_b32_e64 v50, v13, v48, s[38:39]
	v_cndmask_b32_e64 v14, v2, v14, s[38:39]
	v_cndmask_b32_e64 v13, v3, v15, s[38:39]
	v_mov_b32_e32 v51, v4
	v_add_f32_e32 v2, 0, v4
	v_add_f32_e32 v3, 0, v5
	v_fma_f32 v4, v116, v52, v62
	v_fma_f32 v5, v117, v53, v63
	v_fma_f32 v48, v116, v66, v68
	v_fma_f32 v49, v117, v67, v69
	v_cndmask_b32_e64 v3, v3, 0, s[38:39]
	v_cndmask_b32_e64 v2, v2, 0, s[38:39]
	v_add_f32_e32 v4, v4, v48
	v_add_f32_e32 v5, v5, v49
	v_add_u32_e32 v49, s26, v129
	v_add_f32_e32 v2, v4, v2
	v_add_f32_e32 v3, v5, v3
	v_mul_f32_e32 v60, v116, v52
	v_mul_f32_e32 v61, v117, v53
	v_mul_f32_e32 v142, v116, v64
	v_mul_f32_e32 v143, v117, v65
	v_add_f32_e32 v4, v2, v50
	v_add_f32_e32 v5, v3, v51
	v_cvt_pk_bf16_f32 v52, v54, v6
	v_cvt_pk_bf16_f32 v6, v57, v9
	v_cvt_pk_bf16_f32 v9, v72, v74
	v_add_u32_e32 v74, v49, v127
	v_cndmask_b32_e64 v48, v2, v4, s[38:39]
	v_cndmask_b32_e64 v139, v50, v139, s[38:39]
	v_cvt_pk_bf16_f32 v50, v55, v7
	v_cvt_pk_bf16_f32 v55, v143, v59
	v_cvt_pk_bf16_f32 v57, v142, v58
	v_cvt_pk_bf16_f32 v2, v61, v63
	v_cvt_pk_bf16_f32 v4, v60, v62
	ds_read_b64_tr_b16 v[58:59], v74 offset:16384
	ds_read_b64_tr_b16 v[60:61], v74 offset:17408
	v_mul_f32_e32 v70, v116, v66
	v_mul_f32_e32 v71, v117, v67
	v_add_u32_e32 v49, v49, v128
	v_cndmask_b32_e64 v15, v3, v5, s[38:39]
	v_cvt_pk_bf16_f32 v51, v145, v147
	v_cvt_pk_bf16_f32 v53, v144, v146
	v_cvt_pk_bf16_f32 v7, v73, v75
	v_cvt_pk_bf16_f32 v3, v71, v69
	v_cvt_pk_bf16_f32 v5, v70, v68
	ds_read_b64_tr_b16 v[62:63], v49 offset:16384
	ds_read_b64_tr_b16 v[64:65], v49 offset:17408
	ds_read_b64_tr_b16 v[66:67], v74 offset:18432
	ds_read_b64_tr_b16 v[68:69], v74 offset:19456
	ds_read_b64_tr_b16 v[70:71], v49 offset:18432
	ds_read_b64_tr_b16 v[72:73], v49 offset:19456
	s_waitcnt lgkmcnt(6)
; #define LAS __attribute__((address_space(3)))
; #define MFMA32(a, b, c) __builtin_amdgcn_mfma_f32_32x32x16_bf16((a), (b), (c), 0, 0, 0)
; __device__ __forceinline__ void nsa_pv(f32x16& o0, f32x16& o1, LAS const unsigned char* Vt, const bf16x8 (&pk)[4], int lane) {
;     ...
; #pragma unroll
;     for (int sb = 0; sb < 2; ++sb) {
;         s16x4 al[2][2], ah[2][2];
; #pragma unroll
;         for (int s2 = 0; s2 < 2; ++s2) { LAS const unsigned char* base = Vt + (2 * sb + s2) * 16 * 128 + rowoff;
;             al[s2][0] = __builtin_bit_cast(s16x4, __builtin_amdgcn_ds_read_tr16_b64_v4i16((LAS s16x4*)(base + c0)));
;             ah[s2][0] = __builtin_bit_cast(s16x4, __builtin_amdgcn_ds_read_tr16_b64_v4i16((LAS s16x4*)(base + c0 + 8 * 128)));
;             al[s2][1] = __builtin_bit_cast(s16x4, __builtin_amdgcn_ds_read_tr16_b64_v4i16((LAS s16x4*)(base + c1)));
;             ah[s2][1] = __builtin_bit_cast(s16x4, __builtin_amdgcn_ds_read_tr16_b64_v4i16((LAS s16x4*)(base + c1 + 8 * 128))); }
; #pragma unroll
;         for (int s2 = 0; s2 < 2; ++s2) {
;             const bf16x8 v0 = {al[s2][0][0], al[s2][0][1], al[s2][0][2], al[s2][0][3], ah[s2][0][0], ah[s2][0][1], ah[s2][0][2], ah[s2][0][3]};
;             const bf16x8 v1 = {al[s2][1][0], al[s2][1][1], al[s2][1][2], al[s2][1][3], ah[s2][1][0], ah[s2][1][1], ah[s2][1][2], ah[s2][1][3]};
;             o0 = MFMA32(v0, pk[2 * sb + s2], o0); o1 = MFMA32(v1, pk[2 * sb + s2], o1); }
;     }
	v_mfma_f32_32x32x16_bf16 v[32:47], v[58:61], v[50:53], v[32:47]
	v_cvt_pk_bf16_f32 v8, v56, v8
	v_cvt_pk_bf16_f32 v54, v77, v79
	v_cvt_pk_bf16_f32 v56, v76, v78
	s_add_i32 s49, s49, 1
	s_waitcnt lgkmcnt(4)
	v_mfma_f32_32x32x16_bf16 v[16:31], v[62:65], v[50:53], v[16:31]
	s_waitcnt lgkmcnt(2)
	v_mfma_f32_32x32x16_bf16 v[32:47], v[66:69], v[54:57], v[32:47]
	s_waitcnt lgkmcnt(0)
	v_mfma_f32_32x32x16_bf16 v[16:31], v[70:73], v[54:57], v[16:31]
	ds_read_b64_tr_b16 v[50:51], v74 offset:20480
	ds_read_b64_tr_b16 v[52:53], v74 offset:21504
	ds_read_b64_tr_b16 v[54:55], v49 offset:20480
	ds_read_b64_tr_b16 v[56:57], v49 offset:21504
	ds_read_b64_tr_b16 v[58:59], v74 offset:22528
	ds_read_b64_tr_b16 v[60:61], v74 offset:23552
	ds_read_b64_tr_b16 v[62:63], v49 offset:22528
	ds_read_b64_tr_b16 v[64:65], v49 offset:23552
	s_waitcnt lgkmcnt(6)
	v_mfma_f32_32x32x16_bf16 v[32:47], v[50:53], v[6:9], v[32:47]
	s_waitcnt lgkmcnt(4)
	v_mfma_f32_32x32x16_bf16 v[16:31], v[54:57], v[6:9], v[16:31]
	s_waitcnt lgkmcnt(2)
	v_mfma_f32_32x32x16_bf16 v[32:47], v[58:61], v[2:5], v[32:47]
	s_waitcnt lgkmcnt(0)
	v_mfma_f32_32x32x16_bf16 v[16:31], v[62:65], v[2:5], v[16:31]
	s_branch .LBB0_899

; #define NSA_LOAD(Kp, Vp, jb) do { kr = *(const GAS v4u*)((const GAS char*)((Kp) + (size_t)(jb) * 4096) + toff); vr = *(const GAS v4u*)((const GAS char*)((Vp) + (size_t)(jb) * 4096) + toff); } while (0)
; #define NSA_STAGE() do { nsa_stage_store(lds, itc & 1, tid, kr, vr); } while (0)
; #define NSA_BAR() asm volatile("s_waitcnt lgkmcnt(0)\n\ts_barrier" ::: "memory")
; __device__ __forceinline__ void nsa_unit(Frame& F, int b, int g, int i, const bf16* QN, const bf16* KV, const bf16* KCMP, const float* GN, bf16* ON, int& itc) {
;     ...
;         for (int jb = 0; jb <= i; ++jb) {
;             NSA_STAGE(); if (jb < i) NSA_LOAD(Ks, Vs, jb + 1);
;             NSA_BAR();
;             const bool att = (mymask >> jb) & 1ull;
;             f32x16 p0, p1;
;             const int dmin = tw0 - 64 * jb - 63;
;             nsa_scores(p0, p1, NSA_KT, qr, 0.f, r32, hi);
;             float cin = att ? b31 : -INFINITY;
;             if (dmin < 113) { nsa_near(p0, p1, t - 64 * jb, 1, 1 << 30, lut, hi); cin = att ? 0.f : -INFINITY; }
.LBB0_924:
	v_add_u32_e32 v0, s26, v122
	s_waitcnt lgkmcnt(0)
	s_barrier
	v_add_u32_e32 v64, v0, v123
	ds_read_b128 v[26:29], v64
	v_add_u32_e32 v98, v0, v124
	s_waitcnt lgkmcnt(14)
	v_lshrrev_b64 v[100:101], s14, v[30:31]
	s_cmp_le_i32 s17, s22
	s_waitcnt lgkmcnt(0)
	v_mfma_f32_32x32x16_bf16 v[48:63], v[26:29], v[80:83], 0
	ds_read_b128 v[26:29], v64 offset:4096
	s_waitcnt lgkmcnt(0)
	v_mfma_f32_32x32x16_bf16 v[64:79], v[26:29], v[80:83], 0
	ds_read_b128 v[26:29], v98
	s_waitcnt lgkmcnt(0)
	v_mfma_f32_32x32x16_bf16 v[48:63], v[26:29], v[84:87], v[48:63]
	ds_read_b128 v[26:29], v98 offset:4096
	v_add_u32_e32 v98, v0, v125
	v_add_u32_e32 v0, v0, v126
	s_waitcnt lgkmcnt(0)
	v_mfma_f32_32x32x16_bf16 v[64:79], v[26:29], v[84:87], v[64:79]
	ds_read_b128 v[26:29], v98
	s_waitcnt lgkmcnt(0)
	v_mfma_f32_32x32x16_bf16 v[48:63], v[26:29], v[88:91], v[48:63]
	ds_read_b128 v[26:29], v98 offset:4096
	s_waitcnt lgkmcnt(0)
	v_mfma_f32_32x32x16_bf16 v[64:79], v[26:29], v[88:91], v[64:79]
	ds_read_b128 v[26:29], v0
	s_waitcnt lgkmcnt(0)
	v_mfma_f32_32x32x16_bf16 v[48:63], v[26:29], v[92:95], v[48:63]
	ds_read_b128 v[26:29], v0 offset:4096
	v_and_b32_e32 v0, 1, v100
	v_cmp_eq_u64_e32 vcc, 0, v[0:1]
	s_waitcnt lgkmcnt(0)
	v_mfma_f32_32x32x16_bf16 v[64:79], v[26:29], v[92:95], v[64:79]
	s_cbranch_scc1 .LBB0_926
	v_mov_b32_e32 v0, v96
	s_nop 0
	v_add_u32_e32 v159, -2, v0
	v_add_u32_e32 v158, -3, v0
	v_med3_i32 v100, v159, 0, v205
	v_lshl_add_u32 v102, v100, 2, s21
	v_med3_i32 v100, v158, 0, v205
	v_subrev_u32_e32 v161, 34, v0
	v_add_u32_e32 v98, -1, v0
	v_subrev_u32_e32 v104, 33, v0
	v_subrev_u32_e32 v137, 32, v0
	v_lshl_add_u32 v103, v100, 2, s21
	v_subrev_u32_e32 v160, 35, v0
	v_med3_i32 v100, v161, 0, v205
	v_med3_i32 v26, v0, 0, v205
	v_med3_i32 v27, v98, 0, v205
	v_med3_i32 v28, v137, 0, v205
	v_med3_i32 v29, v104, 0, v205
	v_lshl_add_u32 v116, v100, 2, s21
	v_med3_i32 v100, v160, 0, v205
	v_lshl_add_u32 v26, v26, 2, s21
	v_lshl_add_u32 v27, v27, 2, s21
	v_lshl_add_u32 v28, v28, 2, s21
	v_lshl_add_u32 v29, v29, 2, s21
	v_lshl_add_u32 v117, v100, 2, s21
	v_add_u32_e32 v162, -9, v0
	v_add_u32_e32 v163, -8, v0
	v_subrev_u32_e32 v164, 41, v0
	v_subrev_u32_e32 v165, 40, v0
	v_add_u32_e32 v166, -11, v0
	v_add_u32_e32 v167, -10, v0
	v_subrev_u32_e32 v168, 43, v0
	v_subrev_u32_e32 v169, 42, v0
	v_add_u32_e32 v170, -16, v0
	v_subrev_u32_e32 v171, 17, v0
	v_subrev_u32_e32 v177, 49, v0
	v_subrev_u32_e32 v178, 48, v0
	v_subrev_u32_e32 v179, 19, v0
	v_subrev_u32_e32 v180, 18, v0
	v_subrev_u32_e32 v181, 51, v0
	v_subrev_u32_e32 v182, 50, v0
	ds_read_b32 v100, v26
	ds_read_b32 v101, v27
	ds_read_b32 v28, v28
	ds_read_b32 v29, v29
	ds_read_b32 v102, v102
	ds_read_b32 v103, v103
	ds_read_b32 v26, v116
	ds_read_b32 v27, v117
	v_med3_i32 v116, v163, 0, v205
	v_med3_i32 v117, v162, 0, v205
	v_med3_i32 v138, v165, 0, v205
	v_med3_i32 v139, v164, 0, v205
	v_med3_i32 v140, v167, 0, v205
	v_med3_i32 v141, v166, 0, v205
	v_med3_i32 v142, v169, 0, v205
	v_med3_i32 v143, v168, 0, v205
	v_med3_i32 v144, v170, 0, v205
	v_med3_i32 v145, v171, 0, v205
	v_med3_i32 v146, v178, 0, v205
	v_med3_i32 v147, v177, 0, v205
	v_med3_i32 v148, v180, 0, v205
	v_med3_i32 v149, v179, 0, v205
	v_med3_i32 v150, v182, 0, v205
	v_med3_i32 v151, v181, 0, v205
	v_lshl_add_u32 v116, v116, 2, s21
	v_lshl_add_u32 v117, v117, 2, s21
	v_lshl_add_u32 v138, v138, 2, s21
	v_lshl_add_u32 v139, v139, 2, s21
	v_lshl_add_u32 v140, v140, 2, s21
	v_lshl_add_u32 v141, v141, 2, s21
	v_lshl_add_u32 v142, v142, 2, s21
	v_lshl_add_u32 v143, v143, 2, s21
	v_lshl_add_u32 v144, v144, 2, s21
	v_lshl_add_u32 v145, v145, 2, s21
	v_lshl_add_u32 v146, v146, 2, s21
	v_lshl_add_u32 v147, v147, 2, s21
	v_lshl_add_u32 v148, v148, 2, s21
	v_lshl_add_u32 v149, v149, 2, s21
	v_lshl_add_u32 v150, v150, 2, s21
	v_lshl_add_u32 v151, v151, 2, s21
	ds_read_b32 v116, v116
	ds_read_b32 v117, v117
	ds_read_b32 v138, v138
	ds_read_b32 v139, v139
	ds_read_b32 v140, v140
	ds_read_b32 v141, v141
	ds_read_b32 v142, v142
	ds_read_b32 v143, v143
	ds_read_b32 v144, v144
	ds_read_b32 v145, v145
	ds_read_b32 v146, v146
	ds_read_b32 v147, v147
	ds_read_b32 v148, v148
	ds_read_b32 v149, v149
	ds_read_b32 v150, v150
	ds_read_b32 v151, v151
	v_subrev_u32_e32 v185, 57, v0
	v_subrev_u32_e32 v183, 25, v0
	v_subrev_u32_e32 v184, 24, v0
	v_subrev_u32_e32 v186, 56, v0
	v_med3_i32 v155, v185, 0, v205
	v_subrev_u32_e32 v188, 27, v0
	v_subrev_u32_e32 v189, 26, v0
	v_subrev_u32_e32 v191, 58, v0
	v_med3_i32 v152, v184, 0, v205
	v_med3_i32 v153, v183, 0, v205
	v_med3_i32 v154, v186, 0, v205
	v_lshl_add_u32 v187, v155, 2, s21
	v_med3_i32 v155, v189, 0, v205
	v_med3_i32 v156, v188, 0, v205
	s_waitcnt lgkmcnt(2)
; #define LAS __attribute__((address_space(3)))
; __device__ __forceinline__ void nsa_near(f32x16& p0, f32x16& p1, int dbase, int stride, int lim, LAS const float* lut, int hi) {
;     int db = dbase - stride * 4 * hi; asm volatile("" : "+v"(db));
; #pragma unroll
;     for (int r = 0; r < 16; ++r) {
;         const int d0 = db - stride * ((r & 3) + 8 * (r >> 2)), d1 = d0 - stride * 32;
;         const float b0 = lut[min(max(d0, 0), 127)], b1 = lut[min(max(d1, 0), 127)];
;         p0[r] = (d0 >= 0 && d0 < lim) ? p0[r] + b0 : -INFINITY; p1[r] = (d1 >= 0 && d1 < lim) ? p1[r] + b1 : -INFINITY;
;     }
; __device__ __forceinline__ void nsa_unit(Frame& F, int b, int g, int i, const bf16* QN, const bf16* KV, const bf16* KCMP, const float* GN, bf16* ON, int& itc) {
;     ...
;             if (dmin < 113) { nsa_near(p0, p1, t - 64 * jb, 1, 1 << 30, lut, hi); cin = att ? 0.f : -INFINITY; }
	v_add_f32_e32 v58, v58, v148
	v_add_f32_e32 v59, v59, v149
	v_subrev_u32_e32 v190, 59, v0
	v_med3_i32 v148, v191, 0, v205
	v_lshl_add_u32 v152, v152, 2, s21
	v_lshl_add_u32 v153, v153, 2, s21
	v_lshl_add_u32 v154, v154, 2, s21
	v_lshl_add_u32 v155, v155, 2, s21
	v_lshl_add_u32 v156, v156, 2, s21
	v_lshl_add_u32 v157, v148, 2, s21
	v_med3_i32 v148, v190, 0, v205
	v_lshl_add_u32 v192, v148, 2, s21
	ds_read_b32 v148, v152
	ds_read_b32 v149, v153
	ds_read_b32 v152, v154
	ds_read_b32 v154, v155
	ds_read_b32 v155, v156
	ds_read_b32 v156, v157
	ds_read_b32 v157, v192
	ds_read_b32 v153, v187
	v_cmp_gt_u32_e64 s[42:43], 2.0, v188
	s_waitcnt lgkmcnt(3)
	v_add_f32_e32 v62, v62, v154
	v_add_f32_e32 v63, v63, v155
	v_add_f32_e32 v60, v60, v148
	v_add_f32_e32 v61, v61, v149
	v_cndmask_b32_e64 v63, v206, v63, s[42:43]
	v_cmp_gt_u32_e64 s[42:43], 2.0, v189
	v_add_f32_e32 v56, v56, v144
	v_add_f32_e32 v57, v57, v145
	v_add_f32_e32 v54, v54, v140
	v_add_f32_e32 v55, v55, v141
	v_cndmask_b32_e64 v62, v206, v62, s[42:43]
	v_cmp_gt_u32_e64 s[42:43], 2.0, v183
	v_add_f32_e32 v52, v52, v116
	v_add_f32_e32 v53, v53, v117
	v_add_f32_e32 v50, v50, v102
	v_add_f32_e32 v51, v51, v103
	v_cndmask_b32_e64 v61, v206, v61, s[42:43]
	v_cmp_gt_u32_e64 s[42:43], 2.0, v184
	v_add_f32_e32 v48, v48, v100
	v_add_f32_e32 v49, v49, v101
	v_add_f32_e32 v26, v66, v26
	v_add_f32_e32 v27, v67, v27
	v_cndmask_b32_e64 v60, v206, v60, s[42:43]
	v_cmp_gt_u32_e64 s[42:43], 2.0, v179
	v_add_f32_e32 v66, v70, v142
	v_add_f32_e32 v67, v71, v143
	v_add_f32_e32 v70, v74, v150
	v_add_f32_e32 v71, v75, v151
	v_cndmask_b32_e64 v59, v206, v59, s[42:43]
	v_cmp_gt_u32_e64 s[42:43], 2.0, v180
	s_waitcnt lgkmcnt(1)
	v_add_f32_e32 v74, v78, v156
	v_add_f32_e32 v75, v79, v157
	v_add_f32_e32 v28, v64, v28
	v_add_f32_e32 v29, v65, v29
	v_cndmask_b32_e64 v58, v206, v58, s[42:43]
	v_cmp_gt_u32_e64 s[42:43], 2.0, v171
	v_add_f32_e32 v64, v68, v138
	v_add_f32_e32 v65, v69, v139
	v_add_f32_e32 v68, v72, v146
	v_add_f32_e32 v69, v73, v147
	v_cndmask_b32_e64 v57, v206, v57, s[42:43]
	v_cmp_gt_u32_e64 s[42:43], 2.0, v170
	s_waitcnt lgkmcnt(0)
	v_add_f32_e32 v72, v76, v152
	v_add_f32_e32 v73, v77, v153
	v_cndmask_b32_e64 v56, v206, v56, s[42:43]
	v_cmp_gt_u32_e64 s[42:43], 2.0, v166
	s_nop 1
	v_cndmask_b32_e64 v55, v206, v55, s[42:43]
	v_cmp_gt_u32_e64 s[42:43], 2.0, v167
	s_nop 1
	v_cndmask_b32_e64 v54, v206, v54, s[42:43]
	v_cmp_gt_u32_e64 s[42:43], 2.0, v162
	s_nop 1
	v_cndmask_b32_e64 v53, v206, v53, s[42:43]
	v_cmp_gt_u32_e64 s[42:43], 2.0, v163
	s_nop 1
	v_cndmask_b32_e64 v52, v206, v52, s[42:43]
	v_cmp_gt_u32_e64 s[42:43], 2.0, v158
	s_nop 1
	v_cndmask_b32_e64 v51, v206, v51, s[42:43]
	v_cmp_gt_u32_e64 s[42:43], 2.0, v159
	s_nop 1
	v_cndmask_b32_e64 v50, v206, v50, s[42:43]
	v_cmp_gt_u32_e64 s[42:43], 2.0, v98
	s_nop 1
	v_cndmask_b32_e64 v49, v206, v49, s[42:43]
	v_cmp_gt_u32_e64 s[42:43], 2.0, v0
	s_nop 1
	v_cndmask_b32_e64 v48, v206, v48, s[42:43]
	v_cmp_gt_u32_e64 s[42:43], 2.0, v190
	s_nop 1
	v_cndmask_b32_e64 v79, v206, v75, s[42:43]
	v_cmp_gt_u32_e64 s[42:43], 2.0, v191
	s_nop 1
	v_cndmask_b32_e64 v78, v206, v74, s[42:43]
	v_cmp_gt_u32_e64 s[42:43], 2.0, v185
	s_nop 1
	v_cndmask_b32_e64 v77, v206, v73, s[42:43]
	v_cmp_gt_u32_e64 s[42:43], 2.0, v186
	s_nop 1
	v_cndmask_b32_e64 v76, v206, v72, s[42:43]
	v_cmp_gt_u32_e64 s[42:43], 2.0, v181
	s_nop 1
	v_cndmask_b32_e64 v75, v206, v71, s[42:43]
	v_cmp_gt_u32_e64 s[42:43], 2.0, v182
	s_nop 1
	v_cndmask_b32_e64 v74, v206, v70, s[42:43]
	v_cmp_gt_u32_e64 s[42:43], 2.0, v177
	s_nop 1
	v_cndmask_b32_e64 v73, v206, v69, s[42:43]
	v_cmp_gt_u32_e64 s[42:43], 2.0, v178
	s_nop 1
	v_cndmask_b32_e64 v72, v206, v68, s[42:43]
	v_cmp_gt_u32_e64 s[42:43], 2.0, v168
	s_nop 1
	v_cndmask_b32_e64 v71, v206, v67, s[42:43]
	v_cmp_gt_u32_e64 s[42:43], 2.0, v169
	s_nop 1
	v_cndmask_b32_e64 v70, v206, v66, s[42:43]
	v_cmp_gt_u32_e64 s[42:43], 2.0, v164
	s_nop 1
	v_cndmask_b32_e64 v69, v206, v65, s[42:43]
	v_cmp_gt_u32_e64 s[42:43], 2.0, v165
	s_nop 1
	v_cndmask_b32_e64 v68, v206, v64, s[42:43]
	v_cmp_gt_u32_e64 s[42:43], 2.0, v160
	s_nop 1
	v_cndmask_b32_e64 v67, v206, v27, s[42:43]
	v_cmp_gt_u32_e64 s[42:43], 2.0, v161
	s_nop 1
	v_cndmask_b32_e64 v66, v206, v26, s[42:43]
	v_cmp_gt_u32_e64 s[42:43], 2.0, v104
	v_cndmask_b32_e32 v26, 0, v206, vcc
	s_nop 0
	v_cndmask_b32_e64 v65, v206, v29, s[42:43]
	v_cmp_gt_u32_e64 s[42:43], 2.0, v137
	s_nop 1
	v_cndmask_b32_e64 v64, v206, v28, s[42:43]
	s_branch .LBB0_927

; __device__ __forceinline__ void nsa_online(f32x16& p0, f32x16& p1, NsaSm& st, f32x16& o0, f32x16& o1, LAS const unsigned char* Vt, int lane, float cin) {
;     const float mx = nsa_rowmax(p0, p1) + cin, mn = fmaxf(st.m, mx), alpha = __builtin_amdgcn_exp2f(st.m - mn), off = mn - cin;
;     st.m = mn; float sum = 0.f;
; #pragma unroll
;     for (int r = 0; r < 16; ++r) { p0[r] = __builtin_amdgcn_exp2f(p0[r] - off); p1[r] = __builtin_amdgcn_exp2f(p1[r] - off); sum += p0[r] + p1[r]; }
;     st.l = st.l * alpha + sum;
;     if (__any(alpha != 1.0f)) {
; #pragma unroll
;         for (int r = 0; r < 16; ++r) { o0[r] *= alpha; o1[r] *= alpha; } }
.LBB0_927:
	s_nop 9
	v_maximum3_f32 v0, v49, v65, v65
	v_maximum3_f32 v0, v48, v64, v0
	v_maximum3_f32 v27, v50, v66, v66
	v_maximum3_f32 v28, v51, v67, v67
	v_maximum3_f32 v0, v0, v27, v28
	v_maximum3_f32 v27, v52, v68, v68
	v_maximum3_f32 v28, v53, v69, v69
	v_maximum3_f32 v0, v0, v27, v28
	v_maximum3_f32 v27, v54, v70, v70
	v_maximum3_f32 v28, v55, v71, v71
	v_maximum3_f32 v0, v0, v27, v28
	v_maximum3_f32 v27, v56, v72, v72
	v_maximum3_f32 v28, v57, v73, v73
	v_maximum3_f32 v0, v0, v27, v28
	v_maximum3_f32 v27, v58, v74, v74
	v_maximum3_f32 v28, v59, v75, v75
	v_maximum3_f32 v0, v0, v27, v28
	v_maximum3_f32 v27, v60, v76, v76
	v_maximum3_f32 v28, v61, v77, v77
	v_maximum3_f32 v0, v0, v27, v28
	v_maximum3_f32 v27, v62, v78, v78
	v_maximum3_f32 v28, v63, v79, v79
	v_maximum3_f32 v0, v0, v27, v28
	v_mov_b32_e32 v27, v0
	s_nop 1
	v_permlane32_swap_b32_e32 v0, v27
	v_max_f32_e32 v27, v27, v27
	v_max_f32_e32 v0, v0, v0
	v_max_f32_e32 v0, v0, v27
	v_add_f32_e32 v0, v26, v0
	v_max_f32_e32 v27, v99, v99
	v_max_f32_e32 v98, v27, v0
	v_sub_f32_e32 v0, v99, v98
	v_exp_f32_e32 v0, v0
	s_nop 0
	v_cmp_neq_f32_e32 vcc, 1.0, v0
	s_cbranch_vccz .LBB0_929
	v_mul_f32_e32 v16, v16, v0
	v_mul_f32_e32 v17, v17, v0
	v_mul_f32_e32 v14, v14, v0
	v_mul_f32_e32 v15, v15, v0
	v_mul_f32_e32 v12, v12, v0
	v_mul_f32_e32 v13, v13, v0
	v_mul_f32_e32 v10, v10, v0
	v_mul_f32_e32 v11, v11, v0
	v_mul_f32_e32 v8, v8, v0
	v_mul_f32_e32 v9, v9, v0
	v_mul_f32_e32 v6, v6, v0
	v_mul_f32_e32 v7, v7, v0
	v_mul_f32_e32 v4, v4, v0
	v_mul_f32_e32 v5, v5, v0
	v_mul_f32_e32 v2, v2, v0
	v_mul_f32_e32 v3, v3, v0
	v_mul_f32_e32 v46, v46, v0
	v_mul_f32_e32 v47, v47, v0
	v_mul_f32_e32 v44, v44, v0
	v_mul_f32_e32 v45, v45, v0
	v_mul_f32_e32 v42, v42, v0
	v_mul_f32_e32 v43, v43, v0
	v_mul_f32_e32 v40, v40, v0
	v_mul_f32_e32 v41, v41, v0
	v_mul_f32_e32 v38, v38, v0
	v_mul_f32_e32 v39, v39, v0
	v_mul_f32_e32 v36, v36, v0
	v_mul_f32_e32 v37, v37, v0
	v_mul_f32_e32 v34, v34, v0
	v_mul_f32_e32 v35, v35, v0
	v_mul_f32_e32 v32, v32, v0
	v_mul_f32_e32 v33, v33, v0

; #define NSA_LOAD(Kp, Vp, jb) do { kr = *(const GAS v4u*)((const GAS char*)((Kp) + (size_t)(jb) * 4096) + toff); vr = *(const GAS v4u*)((const GAS char*)((Vp) + (size_t)(jb) * 4096) + toff); } while (0)
; #define NSA_STAGE() do { nsa_stage_store(lds, itc & 1, tid, kr, vr); } while (0)
; #define NSA_BAR() asm volatile("s_waitcnt lgkmcnt(0)\n\ts_barrier" ::: "memory")
; __device__ __forceinline__ void nsa_unit(Frame& F, int b, int g, int i, const bf16* QN, const bf16* KV, const bf16* KCMP, const float* GN, bf16* ON, int& itc) {
;     ...
;         for (int jb = j0; jb <= i; ++jb) {
;             NSA_STAGE(); if (jb < i) NSA_LOAD(Kw, Vw, jb + 1);
;             NSA_BAR();
;             f32x16 p0, p1;
;             const int dmin = tw0 - 64 * jb - 63, dmax = tw0 + 31 - 64 * jb;
;     ...
;             nsa_scores(p0, p1, NSA_KT, qr, 0.f, r32, hi);
;             float cin = b31;
;             if (dmin < 113) { nsa_near(p0, p1, t - 64 * jb, 1, 1 << 30, lut, hi); cin = 0.f; }
;     ...
;             nsa_scores(p0, p1, NSA_KT, qr, 0.f, r32, hi);
;             float cin = b31;
;             if (!(dmin >= 113 && dmax < 512)) { nsa_near(p0, p1, t - 64 * jb, 1, 512, lut, hi); cin = 0.f; }
.LBB0_935:
	v_add_u32_e32 v0, s26, v122
	s_waitcnt lgkmcnt(0)
	s_barrier
	v_add_u32_e32 v6, v0, v123
	ds_read_b128 v[2:5], v6
	s_add_i32 s27, s22, 31
	s_cmp_lt_i32 s33, s48
	s_cselect_b64 s[34:35], -1, 0
	s_cmpk_lt_i32 s27, 0x200
	s_cselect_b64 s[42:43], -1, 0
	s_and_b64 s[34:35], s[34:35], s[42:43]
	s_and_b64 vcc, exec, s[34:35]
	s_waitcnt lgkmcnt(0)
	v_mfma_f32_32x32x16_bf16 v[48:63], v[2:5], v[80:83], 0
	ds_read_b128 v[2:5], v6 offset:4096
	v_add_u32_e32 v6, v0, v124
	s_waitcnt lgkmcnt(0)
	v_mfma_f32_32x32x16_bf16 v[64:79], v[2:5], v[80:83], 0
	ds_read_b128 v[2:5], v6
	s_waitcnt lgkmcnt(0)
	v_mfma_f32_32x32x16_bf16 v[48:63], v[2:5], v[84:87], v[48:63]
	ds_read_b128 v[2:5], v6 offset:4096
	v_add_u32_e32 v6, v0, v125
	v_add_u32_e32 v0, v0, v126
	s_waitcnt lgkmcnt(0)
	v_mfma_f32_32x32x16_bf16 v[64:79], v[2:5], v[84:87], v[64:79]
	ds_read_b128 v[2:5], v6
	s_waitcnt lgkmcnt(0)
	v_mfma_f32_32x32x16_bf16 v[48:63], v[2:5], v[88:91], v[48:63]
	ds_read_b128 v[2:5], v6 offset:4096
	s_waitcnt lgkmcnt(0)
	v_mfma_f32_32x32x16_bf16 v[64:79], v[2:5], v[88:91], v[64:79]
	ds_read_b128 v[2:5], v0
	ds_read_b128 v[6:9], v0 offset:4096
	s_waitcnt lgkmcnt(1)
	v_mfma_f32_32x32x16_bf16 v[48:63], v[2:5], v[92:95], v[48:63]
	s_waitcnt lgkmcnt(0)
	v_mfma_f32_32x32x16_bf16 v[64:79], v[6:9], v[92:95], v[64:79]
	s_cbranch_vccnz .LBB0_937
	v_add_u32_e32 v0, s22, v135
	s_nop 0
	v_add_u32_e32 v149, -2, v0
	v_add_u32_e32 v148, -3, v0
	v_med3_i32 v6, v149, 0, v205
	v_lshl_add_u32 v8, v6, 2, s21
	v_med3_i32 v6, v148, 0, v205
	v_subrev_u32_e32 v151, 34, v0
	v_add_u32_e32 v137, -1, v0
	v_subrev_u32_e32 v146, 33, v0
	v_subrev_u32_e32 v147, 32, v0
	v_lshl_add_u32 v9, v6, 2, s21
	v_subrev_u32_e32 v150, 35, v0
	v_med3_i32 v6, v151, 0, v205
	v_med3_i32 v2, v0, 0, v205
	v_med3_i32 v3, v137, 0, v205
	v_med3_i32 v4, v147, 0, v205
	v_med3_i32 v5, v146, 0, v205
	v_lshl_add_u32 v10, v6, 2, s21
	v_med3_i32 v6, v150, 0, v205
	v_lshl_add_u32 v2, v2, 2, s21
	v_lshl_add_u32 v3, v3, 2, s21
	v_lshl_add_u32 v4, v4, 2, s21
	v_lshl_add_u32 v5, v5, 2, s21
	v_lshl_add_u32 v11, v6, 2, s21
	v_add_u32_e32 v152, -9, v0
	v_add_u32_e32 v153, -8, v0
	v_subrev_u32_e32 v154, 41, v0
	v_subrev_u32_e32 v155, 40, v0
	v_add_u32_e32 v156, -11, v0
	v_add_u32_e32 v157, -10, v0
	v_subrev_u32_e32 v158, 43, v0
	v_subrev_u32_e32 v159, 42, v0
	v_subrev_u32_e32 v160, 17, v0
	v_add_u32_e32 v161, -16, v0
	v_subrev_u32_e32 v162, 49, v0
	v_subrev_u32_e32 v163, 48, v0
	v_subrev_u32_e32 v164, 19, v0
	v_subrev_u32_e32 v165, 18, v0
	v_subrev_u32_e32 v166, 51, v0
	v_subrev_u32_e32 v167, 50, v0
	ds_read_b32 v6, v2
	ds_read_b32 v7, v3
	ds_read_b32 v4, v4
	ds_read_b32 v5, v5
	ds_read_b32 v8, v8
	ds_read_b32 v9, v9
	ds_read_b32 v2, v10
	ds_read_b32 v3, v11
	v_med3_i32 v10, v153, 0, v205
	v_med3_i32 v11, v152, 0, v205
	v_med3_i32 v12, v155, 0, v205
	v_med3_i32 v13, v154, 0, v205
	v_med3_i32 v14, v157, 0, v205
	v_med3_i32 v15, v156, 0, v205
	v_med3_i32 v116, v159, 0, v205
	v_med3_i32 v117, v158, 0, v205
	v_med3_i32 v138, v161, 0, v205
	v_med3_i32 v139, v160, 0, v205
	v_med3_i32 v140, v163, 0, v205
	v_med3_i32 v141, v162, 0, v205
	v_med3_i32 v142, v165, 0, v205
	v_med3_i32 v143, v164, 0, v205
	v_med3_i32 v144, v167, 0, v205
	v_med3_i32 v145, v166, 0, v205
	v_lshl_add_u32 v10, v10, 2, s21
	v_lshl_add_u32 v11, v11, 2, s21
	v_lshl_add_u32 v12, v12, 2, s21
	v_lshl_add_u32 v13, v13, 2, s21
	v_lshl_add_u32 v14, v14, 2, s21
	v_lshl_add_u32 v15, v15, 2, s21
	v_lshl_add_u32 v116, v116, 2, s21
	v_lshl_add_u32 v117, v117, 2, s21
	v_lshl_add_u32 v138, v138, 2, s21
	v_lshl_add_u32 v139, v139, 2, s21
	v_lshl_add_u32 v140, v140, 2, s21
	v_lshl_add_u32 v141, v141, 2, s21
	v_lshl_add_u32 v142, v142, 2, s21
	v_lshl_add_u32 v143, v143, 2, s21
	v_lshl_add_u32 v144, v144, 2, s21
	v_lshl_add_u32 v145, v145, 2, s21
	ds_read_b32 v10, v10
	ds_read_b32 v11, v11
	ds_read_b32 v12, v12
	ds_read_b32 v13, v13
	ds_read_b32 v14, v14
	ds_read_b32 v15, v15
	ds_read_b32 v116, v116
	ds_read_b32 v117, v117
	ds_read_b32 v138, v138
	ds_read_b32 v139, v139
	ds_read_b32 v140, v140
	ds_read_b32 v141, v141
	ds_read_b32 v142, v142
	ds_read_b32 v143, v143
	ds_read_b32 v144, v144
	ds_read_b32 v145, v145
	v_subrev_u32_e32 v169, 24, v0
	v_subrev_u32_e32 v186, 58, v0
	v_subrev_u32_e32 v168, 25, v0
	v_med3_i32 v170, v169, 0, v205
	v_subrev_u32_e32 v177, 57, v0
	v_subrev_u32_e32 v178, 56, v0
	v_subrev_u32_e32 v181, 27, v0
	v_subrev_u32_e32 v182, 26, v0
	s_waitcnt lgkmcnt(14)
; #define LAS __attribute__((address_space(3)))
; __device__ __forceinline__ void nsa_near(f32x16& p0, f32x16& p1, int dbase, int stride, int lim, LAS const float* lut, int hi) {
;     int db = dbase - stride * 4 * hi; asm volatile("" : "+v"(db));
; #pragma unroll
;     for (int r = 0; r < 16; ++r) {
;         const int d0 = db - stride * ((r & 3) + 8 * (r >> 2)), d1 = d0 - stride * 32;
;         const float b0 = lut[min(max(d0, 0), 127)], b1 = lut[min(max(d1, 0), 127)];
;         p0[r] = (d0 >= 0 && d0 < lim) ? p0[r] + b0 : -INFINITY; p1[r] = (d1 >= 0 && d1 < lim) ? p1[r] + b1 : -INFINITY;
;     }
; __device__ __forceinline__ void nsa_unit(Frame& F, int b, int g, int i, const bf16* QN, const bf16* KV, const bf16* KCMP, const float* GN, bf16* ON, int& itc) {
;     ...
;             if (!(dmin >= 113 && dmax < 512)) { nsa_near(p0, p1, t - 64 * jb, 1, 512, lut, hi); cin = 0.f; }
	v_add_f32_e32 v10, v52, v10
	v_add_f32_e32 v11, v53, v11
	v_subrev_u32_e32 v185, 59, v0
	v_med3_i32 v52, v186, 0, v205
	v_lshl_add_u32 v170, v170, 2, s21
	v_med3_i32 v171, v168, 0, v205
	v_med3_i32 v179, v178, 0, v205
	v_med3_i32 v180, v177, 0, v205
	v_med3_i32 v183, v182, 0, v205
	v_med3_i32 v184, v181, 0, v205
	v_add_f32_e32 v6, v48, v6
	v_add_f32_e32 v7, v49, v7
	s_waitcnt lgkmcnt(6)
	v_add_f32_e32 v48, v56, v138
	v_add_f32_e32 v49, v57, v139
	v_lshl_add_u32 v56, v52, 2, s21
	v_med3_i32 v52, v185, 0, v205
	v_lshl_add_u32 v171, v171, 2, s21
	v_lshl_add_u32 v179, v179, 2, s21
	v_lshl_add_u32 v180, v180, 2, s21
	v_lshl_add_u32 v183, v183, 2, s21
	v_lshl_add_u32 v184, v184, 2, s21
	v_add_f32_e32 v8, v50, v8
	v_add_f32_e32 v9, v51, v9
	v_add_f32_e32 v14, v54, v14
	v_add_f32_e32 v15, v55, v15
	s_waitcnt lgkmcnt(2)
	v_add_f32_e32 v50, v58, v142
	v_add_f32_e32 v51, v59, v143
	v_lshl_add_u32 v57, v52, 2, s21
	ds_read_b32 v52, v170
	ds_read_b32 v53, v171
	ds_read_b32 v138, v179
	ds_read_b32 v54, v183
	ds_read_b32 v55, v184
	ds_read_b32 v142, v56
	ds_read_b32 v143, v57
	ds_read_b32 v139, v180
	v_cmp_gt_u32_e32 vcc, s75, v181
	s_waitcnt lgkmcnt(3)
	v_add_f32_e32 v54, v62, v54
	v_add_f32_e32 v55, v63, v55
	v_add_f32_e32 v52, v60, v52
	v_add_f32_e32 v53, v61, v53
	v_cndmask_b32_e32 v63, v206, v55, vcc
	v_cmp_gt_u32_e32 vcc, s75, v182
	v_add_f32_e32 v4, v64, v4
	v_add_f32_e32 v5, v65, v5
	s_waitcnt lgkmcnt(1)
	v_add_f32_e32 v64, v78, v142
	v_add_f32_e32 v65, v79, v143
	v_cndmask_b32_e32 v62, v206, v54, vcc
	v_cmp_gt_u32_e32 vcc, s75, v168
	v_add_f32_e32 v2, v66, v2
	v_add_f32_e32 v3, v67, v3
	s_nop 0
	v_cndmask_b32_e32 v61, v206, v53, vcc
	v_cmp_gt_u32_e32 vcc, s75, v169
	s_nop 1
	v_cndmask_b32_e32 v60, v206, v52, vcc
	v_cmp_gt_u32_e32 vcc, s75, v164
	s_nop 1
	v_cndmask_b32_e32 v59, v206, v51, vcc
	v_cmp_gt_u32_e32 vcc, s75, v165
	s_nop 1
	v_cndmask_b32_e32 v58, v206, v50, vcc
	v_cmp_gt_u32_e32 vcc, s75, v160
	s_nop 1
	v_cndmask_b32_e32 v57, v206, v49, vcc
	v_cmp_gt_u32_e32 vcc, s75, v161
	s_nop 1
	v_cndmask_b32_e32 v56, v206, v48, vcc
	v_cmp_gt_u32_e32 vcc, s75, v156
	s_nop 1
	v_cndmask_b32_e32 v55, v206, v15, vcc
	v_cmp_gt_u32_e32 vcc, s75, v157
	s_nop 1
	v_cndmask_b32_e32 v54, v206, v14, vcc
	v_cmp_gt_u32_e32 vcc, s75, v152
	s_waitcnt lgkmcnt(0)
	v_add_f32_e32 v14, v76, v138
	v_add_f32_e32 v15, v77, v139
	v_cndmask_b32_e32 v53, v206, v11, vcc
	v_cmp_gt_u32_e32 vcc, s75, v153
	s_nop 1
	v_cndmask_b32_e32 v52, v206, v10, vcc
	v_cmp_gt_u32_e32 vcc, s75, v148
	v_add_f32_e32 v10, v72, v140
	v_add_f32_e32 v11, v73, v141
	s_nop 0
	v_cndmask_b32_e32 v51, v206, v9, vcc
	v_cmp_gt_u32_e32 vcc, s75, v149
	s_nop 1
	v_cndmask_b32_e32 v50, v206, v8, vcc
	v_cmp_gt_u32_e32 vcc, s75, v137
	v_add_f32_e32 v8, v70, v116
	v_add_f32_e32 v9, v71, v117
	s_nop 0
	v_cndmask_b32_e32 v49, v206, v7, vcc
	v_cmp_gt_u32_e32 vcc, s75, v0
	s_nop 1
	v_cndmask_b32_e32 v48, v206, v6, vcc
	v_cmp_gt_u32_e32 vcc, s75, v185
	v_add_f32_e32 v6, v68, v12
	v_add_f32_e32 v7, v69, v13
	v_add_f32_e32 v12, v74, v144
	v_add_f32_e32 v13, v75, v145
	v_cndmask_b32_e32 v79, v206, v65, vcc
	v_cmp_gt_u32_e32 vcc, s75, v186
	s_nop 1
	v_cndmask_b32_e32 v78, v206, v64, vcc
	v_cmp_gt_u32_e32 vcc, s75, v177
	s_nop 1
	v_cndmask_b32_e32 v77, v206, v15, vcc
	v_cmp_gt_u32_e32 vcc, s75, v178
	s_nop 1
	v_cndmask_b32_e32 v76, v206, v14, vcc
	v_cmp_gt_u32_e32 vcc, s75, v166
	s_nop 1
	v_cndmask_b32_e32 v75, v206, v13, vcc
	v_cmp_gt_u32_e32 vcc, s75, v167
	s_nop 1
	v_cndmask_b32_e32 v74, v206, v12, vcc
	v_cmp_gt_u32_e32 vcc, s75, v162
	s_nop 1
	v_cndmask_b32_e32 v73, v206, v11, vcc
	v_cmp_gt_u32_e32 vcc, s75, v163
	s_nop 1
	v_cndmask_b32_e32 v72, v206, v10, vcc
	v_cmp_gt_u32_e32 vcc, s75, v158
	s_nop 1
	v_cndmask_b32_e32 v71, v206, v9, vcc
	v_cmp_gt_u32_e32 vcc, s75, v159
	s_nop 1
	v_cndmask_b32_e32 v70, v206, v8, vcc
	v_cmp_gt_u32_e32 vcc, s75, v154
	s_nop 1
	v_cndmask_b32_e32 v69, v206, v7, vcc
	v_cmp_gt_u32_e32 vcc, s75, v155
	s_nop 1
	v_cndmask_b32_e32 v68, v206, v6, vcc
	v_cmp_gt_u32_e32 vcc, s75, v150
	s_nop 1
	v_cndmask_b32_e32 v67, v206, v3, vcc
	v_cmp_gt_u32_e32 vcc, s75, v151
	s_nop 1
	v_cndmask_b32_e32 v66, v206, v2, vcc
	v_cmp_gt_u32_e32 vcc, s75, v146
	v_mov_b32_e32 v2, 0
	s_nop 0
	v_cndmask_b32_e32 v65, v206, v5, vcc
	v_cmp_gt_u32_e32 vcc, s75, v147
	s_nop 1
	v_cndmask_b32_e32 v64, v206, v4, vcc
	s_branch .LBB0_938

; __device__ __forceinline__ void nsa_online(f32x16& p0, f32x16& p1, NsaSm& st, f32x16& o0, f32x16& o1, LAS const unsigned char* Vt, int lane, float cin) {
;     const float mx = nsa_rowmax(p0, p1) + cin, mn = fmaxf(st.m, mx), alpha = __builtin_amdgcn_exp2f(st.m - mn), off = mn - cin;
;     st.m = mn; float sum = 0.f;
; #pragma unroll
;     for (int r = 0; r < 16; ++r) { p0[r] = __builtin_amdgcn_exp2f(p0[r] - off); p1[r] = __builtin_amdgcn_exp2f(p1[r] - off); sum += p0[r] + p1[r]; }
;     st.l = st.l * alpha + sum;
;     if (__any(alpha != 1.0f)) {
; #pragma unroll
;         for (int r = 0; r < 16; ++r) { o0[r] *= alpha; o1[r] *= alpha; } }
.LBB0_938:
	s_nop 9
	v_maximum3_f32 v0, v49, v65, v65
	v_maximum3_f32 v0, v48, v64, v0
	v_maximum3_f32 v3, v50, v66, v66
	v_maximum3_f32 v4, v51, v67, v67
	v_maximum3_f32 v0, v0, v3, v4
	v_maximum3_f32 v3, v52, v68, v68
	v_maximum3_f32 v4, v53, v69, v69
	v_maximum3_f32 v0, v0, v3, v4
	v_maximum3_f32 v3, v54, v70, v70
	v_maximum3_f32 v4, v55, v71, v71
	v_maximum3_f32 v0, v0, v3, v4
	v_maximum3_f32 v3, v56, v72, v72
	v_maximum3_f32 v4, v57, v73, v73
	v_maximum3_f32 v0, v0, v3, v4
	v_maximum3_f32 v3, v58, v74, v74
	v_maximum3_f32 v4, v59, v75, v75
	v_maximum3_f32 v0, v0, v3, v4
	v_maximum3_f32 v3, v60, v76, v76
	v_maximum3_f32 v4, v61, v77, v77
	v_maximum3_f32 v0, v0, v3, v4
	v_maximum3_f32 v3, v62, v78, v78
	v_maximum3_f32 v4, v63, v79, v79
	v_maximum3_f32 v0, v0, v3, v4
	v_mov_b32_e32 v3, v0
	s_nop 1
	v_permlane32_swap_b32_e32 v0, v3
	v_max_f32_e32 v3, v3, v3
	v_max_f32_e32 v0, v0, v0
	v_max_f32_e32 v0, v0, v3
	v_add_f32_e32 v0, v2, v0
	v_max_f32_e32 v3, v105, v105
	v_max_f32_e32 v10, v3, v0
	v_sub_f32_e32 v0, v105, v10
	v_exp_f32_e32 v0, v0
	s_nop 0
	v_cmp_neq_f32_e32 vcc, 1.0, v0
	s_cbranch_vccz .LBB0_940
	v_mul_f32_e32 v46, v46, v0
	v_mul_f32_e32 v47, v47, v0
	v_mul_f32_e32 v44, v44, v0
	v_mul_f32_e32 v45, v45, v0
	v_mul_f32_e32 v42, v42, v0
	v_mul_f32_e32 v43, v43, v0
	v_mul_f32_e32 v40, v40, v0
	v_mul_f32_e32 v41, v41, v0
	v_mul_f32_e32 v38, v38, v0
	v_mul_f32_e32 v39, v39, v0
	v_mul_f32_e32 v36, v36, v0
	v_mul_f32_e32 v37, v37, v0
	v_mul_f32_e32 v34, v34, v0
	v_mul_f32_e32 v35, v35, v0
	v_mul_f32_e32 v32, v32, v0
	v_mul_f32_e32 v33, v33, v0
	v_mul_f32_e32 v30, v30, v0
	v_mul_f32_e32 v31, v31, v0
	v_mul_f32_e32 v28, v28, v0
	v_mul_f32_e32 v29, v29, v0
	v_mul_f32_e32 v26, v26, v0
	v_mul_f32_e32 v27, v27, v0
	v_mul_f32_e32 v24, v24, v0
	v_mul_f32_e32 v25, v25, v0
	v_mul_f32_e32 v22, v22, v0
	v_mul_f32_e32 v23, v23, v0
	v_mul_f32_e32 v20, v20, v0
	v_mul_f32_e32 v21, v21, v0
	v_mul_f32_e32 v18, v18, v0
	v_mul_f32_e32 v19, v19, v0
	v_mul_f32_e32 v16, v16, v0
	v_mul_f32_e32 v17, v17, v0

; __device__ __forceinline__ SwapPair swap32p(float x, float y) { unsigned a = __builtin_bit_cast(unsigned, x), b = __builtin_bit_cast(unsigned, y); asm volatile("" : "+v"(a), "+v"(b)); auto r = __builtin_amdgcn_permlane32_swap(a, b, false, false); return SwapPair{r[0], r[1]}; }
; __device__ __forceinline__ SwapPair swap16p(float x, float y) { unsigned a = __builtin_bit_cast(unsigned, x), b = __builtin_bit_cast(unsigned, y); asm volatile("" : "+v"(a), "+v"(b)); auto r = __builtin_amdgcn_permlane16_swap(a, b, false, false); return SwapPair{r[0], r[1]}; }
; #define MFMA16(a, b, c) __builtin_amdgcn_mfma_f32_16x16x32_bf16((a), (b), (c), 0, 0, 0)
; #define DSA_KLOAD(c, ahead) do { _Pragma("unroll") for (int tau = 0; tau < 4; ++tau) kbuf[(c) % 3][tau] = *(const GAS bf16x8*)(kp + ((ahead) * 64 + 16 * tau) * 32); } while (0)
; __device__ __forceinline__ void dsa_token(Frame& F, int b, int t, const bf16* QI, const bf16* KI, const float* WI, const bf16* CKVN, const bf16* QLAT, bf16* OLAT) {
;     ...
;                 for (int c = 4 * g4; c < 4 * g4 + 4; ++c) {
;                     asm volatile("" : "+v"(kp));
;                     if (c + 2 < 64) { if (c + 2 <= cmax4) DSA_KLOAD(c + 2, 2); }
;                     float v[4];
; #pragma unroll
;                     for (int tau = 0; tau < 4; ++tau) {
;                         const f32x4 d = MFMA16(qa, kbuf[c % 3][tau], ((f32x4){0.f, 0.f, 0.f, 0.f}));
;                         typedef int i32x4_ __attribute__((ext_vector_type(4)));
;                         const f32x4 rl = __builtin_bit_cast(f32x4, __builtin_elementwise_max(__builtin_bit_cast(i32x4_, d), ((i32x4_){0, 0, 0, 0})));
;                         v[tau] = fmaf(w4.w, rl[3], fmaf(w4.z, rl[2], fmaf(w4.y, rl[1], w4.x * rl[0])));
;                     }
;                     const SwapPair r0 = swap32p(v[0], v[2]), r1 = swap32p(v[1], v[3]);
;                     const float a0 = __builtin_bit_cast(float, r0.a) + __builtin_bit_cast(float, r0.b), a1 = __builtin_bit_cast(float, r1.a) + __builtin_bit_cast(float, r1.b);
;                     const SwapPair r2 = swap16p(a0, a1);
;                     const float keep = __builtin_bit_cast(float, r2.a) + __builtin_bit_cast(float, r2.b);
;                     const bool cand = 64 * c + lane <= t;
;                     sc[c] = cand ? keep : -INFINITY; vmax = fmaxf(vmax, sc[c]); vmin = fminf(vmin, cand ? keep : INFINITY);
.LBB0_950:
	v_add_f32_e32 v58, v58, v60
	v_add_f32_e32 v59, v59, v61
	v_cmp_lt_i32_e32 vcc, s2, v176
	v_cmp_lt_i32_e64 s[44:45], s2, v177
	v_add_f32_e32 v0, v0, v64
	v_cndmask_b32_e32 v74, v58, v206, vcc
	v_min_f32_e32 v58, 0x7f800000, v58
	v_cndmask_b32_e64 v72, v59, v206, s[44:45]
	v_cndmask_b32_e32 v58, v58, v207, vcc
	v_cndmask_b32_e64 v59, v59, v207, s[44:45]
	v_min_f32_e32 v66, v58, v59
	s_waitcnt vmcnt(3)
	v_mfma_f32_16x16x32_bf16 v[58:61], v[6:9], v[22:25], 0
	v_cmp_lt_i32_e32 vcc, s2, v209
	s_mov_b32 s0, 0xff800000
	v_max3_f32 v65, v74, s0, v72
	v_cndmask_b32_e32 v71, v0, v206, vcc
	v_cndmask_b32_e32 v0, v0, v207, vcc
	s_nop 2
	v_max_i32_e32 v58, 0, v58
	v_max_i32_e32 v59, 0, v59
	v_mul_f32_e32 v64, v2, v58
	v_max_i32_e32 v60, 0, v60
	v_fmac_f32_e32 v64, v3, v59
	v_max_i32_e32 v61, 0, v61
	v_fmac_f32_e32 v64, v4, v60
	v_fmac_f32_e32 v64, v5, v61
	s_waitcnt vmcnt(2)
	v_mfma_f32_16x16x32_bf16 v[58:61], v[6:9], v[18:21], 0
	v_cmp_lt_i32_e32 vcc, s2, v210
	s_nop 6
	v_max_i32_e32 v58, 0, v58
	v_max_i32_e32 v59, 0, v59
	v_mul_f32_e32 v67, v2, v58
	v_max_i32_e32 v60, 0, v60
	v_fmac_f32_e32 v67, v3, v59
	v_max_i32_e32 v61, 0, v61
	v_fmac_f32_e32 v67, v4, v60
	v_fmac_f32_e32 v67, v5, v61
	s_waitcnt vmcnt(1)
	v_mfma_f32_16x16x32_bf16 v[58:61], v[6:9], v[14:17], 0
	s_nop 7
	v_max_i32_e32 v58, 0, v58
	v_max_i32_e32 v59, 0, v59
	v_mul_f32_e32 v68, v2, v58
	v_max_i32_e32 v60, 0, v60
	v_fmac_f32_e32 v68, v3, v59
	v_max_i32_e32 v61, 0, v61
	v_fmac_f32_e32 v68, v4, v60
	v_fmac_f32_e32 v68, v5, v61
	s_waitcnt vmcnt(0)
	v_mfma_f32_16x16x32_bf16 v[58:61], v[6:9], v[10:13], 0
	s_nop 0
	v_permlane32_swap_b32_e32 v64, v68
	s_nop 5
	v_max_i32_e32 v58, 0, v58
	v_max_i32_e32 v59, 0, v59
	v_mul_f32_e32 v58, v2, v58
	v_max_i32_e32 v60, 0, v60
	v_fmac_f32_e32 v58, v3, v59
	v_max_i32_e32 v61, 0, v61
	v_fmac_f32_e32 v58, v4, v60
	v_fmac_f32_e32 v58, v5, v61
	v_add_f32_e32 v59, v64, v68
	s_nop 0
	v_permlane32_swap_b32_e32 v67, v58
	v_add_f32_e32 v58, v67, v58
	s_nop 1
	v_permlane16_swap_b32_e32 v59, v58
	v_add_f32_e32 v58, v59, v58
	v_cndmask_b32_e32 v73, v58, v206, vcc
	v_cndmask_b32_e32 v58, v58, v207, vcc
	v_max3_f32 v107, v65, v71, v73
	v_min3_f32 v108, v66, v0, v58
	v_lshl_add_u64 v[58:59], v[62:63], 0, s[28:29]
	s_branch .LBB0_952

; __device__ __forceinline__ SwapPair swap32p(float x, float y) { unsigned a = __builtin_bit_cast(unsigned, x), b = __builtin_bit_cast(unsigned, y); asm volatile("" : "+v"(a), "+v"(b)); auto r = __builtin_amdgcn_permlane32_swap(a, b, false, false); return SwapPair{r[0], r[1]}; }
; __device__ __forceinline__ SwapPair swap16p(float x, float y) { unsigned a = __builtin_bit_cast(unsigned, x), b = __builtin_bit_cast(unsigned, y); asm volatile("" : "+v"(a), "+v"(b)); auto r = __builtin_amdgcn_permlane16_swap(a, b, false, false); return SwapPair{r[0], r[1]}; }
; #define MFMA16(a, b, c) __builtin_amdgcn_mfma_f32_16x16x32_bf16((a), (b), (c), 0, 0, 0)
; #define DSA_KLOAD(c, ahead) do { _Pragma("unroll") for (int tau = 0; tau < 4; ++tau) kbuf[(c) % 3][tau] = *(const GAS bf16x8*)(kp + ((ahead) * 64 + 16 * tau) * 32); } while (0)
; __device__ __forceinline__ void dsa_token(Frame& F, int b, int t, const bf16* QI, const bf16* KI, const float* WI, const bf16* CKVN, const bf16* QLAT, bf16* OLAT) {
;     ...
;                 for (int c = 4 * g4; c < 4 * g4 + 4; ++c) {
;                     asm volatile("" : "+v"(kp));
;                     if (c + 2 < 64) { if (c + 2 <= cmax4) DSA_KLOAD(c + 2, 2); }
;                     float v[4];
; #pragma unroll
;                     for (int tau = 0; tau < 4; ++tau) {
;                         const f32x4 d = MFMA16(qa, kbuf[c % 3][tau], ((f32x4){0.f, 0.f, 0.f, 0.f}));
;                         typedef int i32x4_ __attribute__((ext_vector_type(4)));
;                         const f32x4 rl = __builtin_bit_cast(f32x4, __builtin_elementwise_max(__builtin_bit_cast(i32x4_, d), ((i32x4_){0, 0, 0, 0})));
;                         v[tau] = fmaf(w4.w, rl[3], fmaf(w4.z, rl[2], fmaf(w4.y, rl[1], w4.x * rl[0])));
;                     }
;                     const SwapPair r0 = swap32p(v[0], v[2]), r1 = swap32p(v[1], v[3]);
;                     const float a0 = __builtin_bit_cast(float, r0.a) + __builtin_bit_cast(float, r0.b), a1 = __builtin_bit_cast(float, r1.a) + __builtin_bit_cast(float, r1.b);
;                     const SwapPair r2 = swap16p(a0, a1);
;                     const float keep = __builtin_bit_cast(float, r2.a) + __builtin_bit_cast(float, r2.b);
;                     const bool cand = 64 * c + lane <= t;
;                     sc[c] = cand ? keep : -INFINITY; vmax = fmaxf(vmax, sc[c]); vmin = fminf(vmin, cand ? keep : INFINITY);
.LBB0_1111:
	s_waitcnt vmcnt(3)
	v_mfma_f32_16x16x32_bf16 v[42:45], v[6:9], v[42:45], 0
	v_add_f32_e32 v122, v121, v122
	v_cmp_lt_i32_e32 vcc, s2, v220
	v_mfma_f32_16x16x32_bf16 v[26:29], v[6:9], v[26:29], 0
	s_nop 0
	v_cndmask_b32_e32 v121, v122, v206, vcc
	s_nop 2
	v_max_i32_e32 v42, 0, v42
	v_max_i32_e32 v43, 0, v43
	v_mul_f32_e32 v123, v2, v42
	v_max_i32_e32 v44, 0, v44
	v_fmac_f32_e32 v123, v3, v43
	v_max_i32_e32 v45, 0, v45
	v_fmac_f32_e32 v123, v4, v44
	v_fmac_f32_e32 v123, v5, v45
	s_waitcnt vmcnt(2)
	v_mfma_f32_16x16x32_bf16 v[42:45], v[6:9], v[46:49], 0
	v_max_i32_e32 v26, 0, v26
	v_max_i32_e32 v27, 0, v27
	v_max_i32_e32 v28, 0, v28
	v_max_i32_e32 v29, 0, v29
	v_mfma_f32_16x16x32_bf16 v[22:25], v[6:9], v[22:25], 0
	s_nop 2
	v_max_i32_e32 v42, 0, v42
	v_max_i32_e32 v43, 0, v43
	v_mul_f32_e32 v46, v2, v42
	v_max_i32_e32 v44, 0, v44
	v_fmac_f32_e32 v46, v3, v43
	v_max_i32_e32 v45, 0, v45
	v_fmac_f32_e32 v46, v4, v44
	v_fmac_f32_e32 v46, v5, v45
	s_waitcnt vmcnt(1)
	v_mfma_f32_16x16x32_bf16 v[42:45], v[6:9], v[50:53], 0
	v_max_i32_e32 v22, 0, v22
	v_max_i32_e32 v23, 0, v23
	v_mul_f32_e32 v22, v2, v22
	v_mfma_f32_16x16x32_bf16 v[18:21], v[6:9], v[18:21], 0
	v_max_i32_e32 v24, 0, v24
	s_nop 2
	v_max_i32_e32 v42, 0, v42
	v_max_i32_e32 v43, 0, v43
	v_mul_f32_e32 v47, v2, v42
	v_max_i32_e32 v44, 0, v44
	v_fmac_f32_e32 v47, v3, v43
	v_max_i32_e32 v45, 0, v45
	v_fmac_f32_e32 v47, v4, v44
	v_fmac_f32_e32 v47, v5, v45
	s_waitcnt vmcnt(0)
	v_mfma_f32_16x16x32_bf16 v[42:45], v[6:9], v[54:57], 0
	v_max_i32_e32 v18, 0, v18
	v_permlane32_swap_b32_e32 v123, v47
	v_mfma_f32_16x16x32_bf16 v[14:17], v[6:9], v[14:17], 0
	s_nop 4
	v_max_i32_e32 v42, 0, v42
	v_max_i32_e32 v43, 0, v43
	v_mul_f32_e32 v42, v2, v42
	v_max_i32_e32 v44, 0, v44
	v_fmac_f32_e32 v42, v3, v43
	v_max_i32_e32 v45, 0, v45
	v_fmac_f32_e32 v42, v4, v44
	v_fmac_f32_e32 v42, v5, v45
	v_max_i32_e32 v14, 0, v14
	s_nop 0
	v_permlane32_swap_b32_e32 v46, v42
	v_add_f32_e32 v42, v46, v42
	v_mul_f32_e32 v46, v2, v26
	v_fmac_f32_e32 v46, v3, v27
	v_fmac_f32_e32 v46, v4, v28
	v_fmac_f32_e32 v46, v5, v29
	v_mfma_f32_16x16x32_bf16 v[26:29], v[6:9], v[30:33], 0
	v_add_f32_e32 v43, v123, v47
	v_lshl_add_u64 v[44:45], v[58:59], 0, s[28:29]
	v_max_i32_e32 v19, 0, v19
	v_mul_f32_e32 v18, v2, v18
	v_max_i32_e32 v15, 0, v15
	s_nop 2
	v_max_i32_e32 v26, 0, v26
	v_max_i32_e32 v27, 0, v27
	v_mul_f32_e32 v30, v2, v26
	v_max_i32_e32 v28, 0, v28
	v_fmac_f32_e32 v30, v3, v27
	v_max_i32_e32 v29, 0, v29
	v_fmac_f32_e32 v30, v4, v28
	v_fmac_f32_e32 v30, v5, v29
	v_mfma_f32_16x16x32_bf16 v[26:29], v[6:9], v[34:37], 0
	v_mul_f32_e32 v14, v2, v14
	v_fmac_f32_e32 v22, v3, v23
	v_max_i32_e32 v20, 0, v20
	s_nop 4
	v_max_i32_e32 v26, 0, v26
	v_max_i32_e32 v27, 0, v27
	v_mul_f32_e32 v31, v2, v26
	v_max_i32_e32 v28, 0, v28
	v_fmac_f32_e32 v31, v3, v27
	v_max_i32_e32 v29, 0, v29
	v_fmac_f32_e32 v31, v4, v28
	v_fmac_f32_e32 v31, v5, v29
	v_mfma_f32_16x16x32_bf16 v[26:29], v[6:9], v[38:41], 0
	v_fmac_f32_e32 v18, v3, v19
	v_max_i32_e32 v16, 0, v16
	v_mfma_f32_16x16x32_bf16 v[6:9], v[6:9], v[10:13], 0
	v_fmac_f32_e32 v14, v3, v15
	s_nop 3
	v_max_i32_e32 v26, 0, v26
	v_max_i32_e32 v27, 0, v27
	v_mul_f32_e32 v26, v2, v26
	v_max_i32_e32 v28, 0, v28
	v_fmac_f32_e32 v26, v3, v27
	v_max_i32_e32 v29, 0, v29
	v_fmac_f32_e32 v26, v4, v28
	v_max_i32_e32 v6, 0, v6
	v_fmac_f32_e32 v26, v5, v29
	v_max_i32_e32 v7, 0, v7
	v_mul_f32_e32 v2, v2, v6
	v_max_i32_e32 v8, 0, v8
	v_fmac_f32_e32 v2, v3, v7
	v_permlane32_swap_b32_e32 v46, v31
	v_permlane32_swap_b32_e32 v30, v26
	v_max_i32_e32 v25, 0, v25
	v_fmac_f32_e32 v22, v4, v24
	v_max_i32_e32 v21, 0, v21
	v_fmac_f32_e32 v18, v4, v20
	v_max_i32_e32 v17, 0, v17
	v_fmac_f32_e32 v14, v4, v16
	v_max_i32_e32 v9, 0, v9
	v_fmac_f32_e32 v2, v4, v8
	v_permlane16_swap_b32_e32 v43, v42
	v_add_f32_e32 v27, v46, v31
	v_add_f32_e32 v29, v30, v26
	v_lshl_add_u64 v[30:31], v[44:45], 0, s[28:29]
	v_fmac_f32_e32 v22, v5, v25
	v_fmac_f32_e32 v18, v5, v21
	v_fmac_f32_e32 v14, v5, v17
	v_fmac_f32_e32 v2, v5, v9
	v_cndmask_b32_e32 v122, v122, v207, vcc
	v_add_f32_e32 v43, v43, v42
	v_cmp_lt_i32_e32 vcc, s2, v221
	s_nop 0
	v_permlane32_swap_b32_e32 v22, v14
	v_cndmask_b32_e32 v26, v43, v207, vcc
	v_permlane32_swap_b32_e32 v18, v2
	v_min3_f32 v30, v108, v122, v26
	v_add_f32_e32 v26, v22, v14
	v_add_f32_e32 v28, v18, v2
	v_permlane16_swap_b32_e32 v27, v29
	s_nop 0
	v_permlane16_swap_b32_e32 v26, v28
	v_cndmask_b32_e32 v42, v43, v206, vcc
	v_add_f32_e32 v4, v26, v28
	v_add_f32_e32 v5, v27, v29
	v_cmp_lt_i32_e32 vcc, s2, v195
	v_max3_f32 v31, v107, v121, v42
	s_nop 0
	v_cndmask_b32_e32 v3, v5, v207, vcc
	v_cndmask_b32_e32 v122, v5, v206, vcc
	v_cmp_lt_i32_e32 vcc, s2, v194
	s_nop 1
	v_cndmask_b32_e32 v2, v4, v206, vcc
	v_cndmask_b32_e32 v4, v4, v207, vcc
	v_max3_f32 v107, v31, v122, v2
	v_min3_f32 v108, v30, v3, v4
	s_cmpk_lt_i32 s2, 0x100
	s_mov_b64 s[16:17], -1
	s_cbranch_scc0 .LBB0_1113
	s_branch .LBB0_1447

.LBB0_1457:
	s_waitcnt lgkmcnt(8)
	v_sub_u32_sdwa v0, s2, v2 dst_sel:DWORD dst_unused:UNUSED_PAD src0_sel:DWORD src1_sel:WORD_0
	v_sub_u32_sdwa v2, s2, v2 dst_sel:DWORD dst_unused:UNUSED_PAD src0_sel:DWORD src1_sel:WORD_1
	v_med3_i32 v0, v0, 0, v205
	v_med3_i32 v2, v2, 0, v205
	v_sub_u32_sdwa v228, s2, v3 dst_sel:DWORD dst_unused:UNUSED_PAD src0_sel:DWORD src1_sel:WORD_0
	v_sub_u32_sdwa v3, s2, v3 dst_sel:DWORD dst_unused:UNUSED_PAD src0_sel:DWORD src1_sel:WORD_1
	v_lshl_add_u32 v0, v0, 2, v208
	v_lshl_add_u32 v2, v2, 2, v208
	v_med3_i32 v228, v228, 0, v205
	v_med3_i32 v3, v3, 0, v205
	v_lshl_add_u32 v228, v228, 2, v208
	v_lshl_add_u32 v3, v3, 2, v208
	ds_read_b32 v0, v0
	ds_read_b32 v2, v2
	ds_read_b32 v229, v228
	ds_read_b32 v233, v3
	v_add_u32_e32 v3, -16, v179
	s_waitcnt lgkmcnt(3)
	v_fmac_f32_e32 v0, 0x3e38aa3b, v164
	v_cmp_gt_i32_e32 vcc, s0, v3
	s_waitcnt lgkmcnt(2)
	v_fmac_f32_e32 v2, 0x3e38aa3b, v165
	s_waitcnt lgkmcnt(1)
	v_fmac_f32_e32 v229, 0x3e38aa3b, v166
	v_cndmask_b32_e32 v228, v206, v0, vcc
	v_add_u32_e32 v0, -15, v179
	v_cmp_gt_i32_e32 vcc, s0, v0
	v_add_u32_e32 v0, -14, v179
	s_waitcnt lgkmcnt(0)
	v_fmac_f32_e32 v233, 0x3e38aa3b, v167
	v_cndmask_b32_e32 v164, v206, v2, vcc
	v_cmp_gt_i32_e32 vcc, s0, v0
	v_add_u32_e32 v0, -13, v179
	s_nop 0
	v_cndmask_b32_e32 v3, v206, v229, vcc
	v_cmp_gt_i32_e32 vcc, s0, v0
	s_nop 1
	v_cndmask_b32_e32 v2, v206, v233, vcc
	v_max_f32_e32 v0, v3, v2
	v_max3_f32 v0, v228, v164, v0
	v_mov_b32_e32 v165, v0
	s_nop 1
	v_permlane16_swap_b32_e32 v0, v165
	v_max_f32_e32 v165, v165, v165
	v_max_f32_e32 v0, v0, v0
	v_max_f32_e32 v0, v0, v165
	v_mov_b32_e32 v165, v0
	s_nop 1
	v_permlane32_swap_b32_e32 v0, v165
	v_max3_f32 v229, v231, v0, v165
	v_sub_f32_e32 v0, v231, v229
	v_exp_f32_e32 v0, v0
	s_nop 0
	v_cmp_neq_f32_e32 vcc, 1.0, v0
	s_cbranch_vccz .LBB0_1459
	v_mul_f32_e32 v82, v82, v0
	v_mul_f32_e32 v83, v83, v0
	v_mul_f32_e32 v80, v80, v0
	v_mul_f32_e32 v81, v81, v0
	v_mul_f32_e32 v62, v62, v0
	v_mul_f32_e32 v63, v63, v0
	v_mul_f32_e32 v60, v60, v0
	v_mul_f32_e32 v61, v61, v0
	v_mul_f32_e32 v58, v58, v0
	v_mul_f32_e32 v59, v59, v0
	v_mul_f32_e32 v56, v56, v0
	v_mul_f32_e32 v57, v57, v0
	v_mul_f32_e32 v54, v54, v0
	v_mul_f32_e32 v55, v55, v0
	v_mul_f32_e32 v52, v52, v0
	v_mul_f32_e32 v53, v53, v0
	v_mul_f32_e32 v50, v50, v0
	v_mul_f32_e32 v51, v51, v0
	v_mul_f32_e32 v48, v48, v0
	v_mul_f32_e32 v49, v49, v0
	v_mul_f32_e32 v46, v46, v0
	v_mul_f32_e32 v47, v47, v0
	v_mul_f32_e32 v44, v44, v0
	v_mul_f32_e32 v45, v45, v0
	v_mul_f32_e32 v42, v42, v0
	v_mul_f32_e32 v43, v43, v0
	v_mul_f32_e32 v40, v40, v0
	v_mul_f32_e32 v41, v41, v0
	v_mul_f32_e32 v38, v38, v0
	v_mul_f32_e32 v39, v39, v0
	v_mul_f32_e32 v36, v36, v0
	v_mul_f32_e32 v37, v37, v0
	v_mul_f32_e32 v34, v34, v0
	v_mul_f32_e32 v35, v35, v0
	v_mul_f32_e32 v32, v32, v0
	v_mul_f32_e32 v33, v33, v0
	v_mul_f32_e32 v30, v30, v0
	v_mul_f32_e32 v31, v31, v0
	v_mul_f32_e32 v28, v28, v0
	v_mul_f32_e32 v29, v29, v0
	v_mul_f32_e32 v26, v26, v0
	v_mul_f32_e32 v27, v27, v0
	v_mul_f32_e32 v24, v24, v0
	v_mul_f32_e32 v25, v25, v0
	v_mul_f32_e32 v22, v22, v0
	v_mul_f32_e32 v23, v23, v0
	v_mul_f32_e32 v20, v20, v0
	v_mul_f32_e32 v21, v21, v0
	v_mul_f32_e32 v18, v18, v0
	v_mul_f32_e32 v19, v19, v0
	v_mul_f32_e32 v16, v16, v0
	v_mul_f32_e32 v17, v17, v0
	v_mul_f32_e32 v14, v14, v0
	v_mul_f32_e32 v15, v15, v0
	v_mul_f32_e32 v12, v12, v0
	v_mul_f32_e32 v13, v13, v0
	v_mul_f32_e32 v10, v10, v0
	v_mul_f32_e32 v11, v11, v0
	v_mul_f32_e32 v8, v8, v0
	v_mul_f32_e32 v9, v9, v0
	v_mul_f32_e32 v6, v6, v0
	v_mul_f32_e32 v7, v7, v0
	v_mul_f32_e32 v4, v4, v0
	v_mul_f32_e32 v5, v5, v0

.LBB0_1462:
	s_waitcnt lgkmcnt(8)
	v_sub_u32_sdwa v0, s2, v2 dst_sel:DWORD dst_unused:UNUSED_PAD src0_sel:DWORD src1_sel:WORD_0
	v_med3_i32 v0, v0, 0, v205
	v_lshl_add_u32 v0, v0, 2, v208
	ds_read_b32 v0, v0
	v_sub_u32_sdwa v2, s2, v2 dst_sel:DWORD dst_unused:UNUSED_PAD src0_sel:DWORD src1_sel:WORD_1
	v_med3_i32 v2, v2, 0, v205
	v_sub_u32_sdwa v230, s2, v3 dst_sel:DWORD dst_unused:UNUSED_PAD src0_sel:DWORD src1_sel:WORD_0
	v_sub_u32_sdwa v3, s2, v3 dst_sel:DWORD dst_unused:UNUSED_PAD src0_sel:DWORD src1_sel:WORD_1
	v_lshl_add_u32 v2, v2, 2, v208
	v_med3_i32 v230, v230, 0, v205
	v_med3_i32 v3, v3, 0, v205
	v_lshl_add_u32 v230, v230, 2, v208
	v_lshl_add_u32 v3, v3, 2, v208
	ds_read_b32 v2, v2
	ds_read_b32 v231, v230
	ds_read_b32 v232, v3
	s_waitcnt lgkmcnt(3)
	v_fmac_f32_e32 v0, 0x3e38aa3b, v164
	v_cmp_gt_i32_e32 vcc, s0, v179
	s_waitcnt lgkmcnt(2)
	v_fmac_f32_e32 v2, 0x3e38aa3b, v165
	s_waitcnt lgkmcnt(1)
	v_fmac_f32_e32 v231, 0x3e38aa3b, v166
	v_cndmask_b32_e32 v230, v206, v0, vcc
	v_add_u32_e32 v0, 1, v179
	v_cmp_gt_i32_e32 vcc, s0, v0
	v_add_u32_e32 v0, 2, v179
	s_waitcnt lgkmcnt(0)
	v_fmac_f32_e32 v232, 0x3e38aa3b, v167
	v_cndmask_b32_e32 v164, v206, v2, vcc
	v_cmp_gt_i32_e32 vcc, s0, v0
	v_add_u32_e32 v0, 3, v179
	s_nop 0
	v_cndmask_b32_e32 v3, v206, v231, vcc
	v_cmp_gt_i32_e32 vcc, s0, v0
	s_nop 1
	v_cndmask_b32_e32 v2, v206, v232, vcc
	v_max_f32_e32 v0, v3, v2
	v_max3_f32 v0, v230, v164, v0
	v_mov_b32_e32 v165, v0
	s_nop 1
	v_permlane16_swap_b32_e32 v0, v165
	v_max_f32_e32 v165, v165, v165
	v_max_f32_e32 v0, v0, v0
	v_max_f32_e32 v0, v0, v165
	v_mov_b32_e32 v165, v0
	s_nop 1
	v_permlane32_swap_b32_e32 v0, v165
	v_max3_f32 v231, v229, v0, v165
	v_sub_f32_e32 v0, v229, v231
	v_exp_f32_e32 v0, v0
	s_nop 0
	v_cmp_neq_f32_e32 vcc, 1.0, v0
	s_cbranch_vccz .LBB0_1464
	v_mul_f32_e32 v82, v82, v0
	v_mul_f32_e32 v83, v83, v0
	v_mul_f32_e32 v80, v80, v0
	v_mul_f32_e32 v81, v81, v0
	v_mul_f32_e32 v62, v62, v0
	v_mul_f32_e32 v63, v63, v0
	v_mul_f32_e32 v60, v60, v0
	v_mul_f32_e32 v61, v61, v0
	v_mul_f32_e32 v58, v58, v0
	v_mul_f32_e32 v59, v59, v0
	v_mul_f32_e32 v56, v56, v0
	v_mul_f32_e32 v57, v57, v0
	v_mul_f32_e32 v54, v54, v0
	v_mul_f32_e32 v55, v55, v0
	v_mul_f32_e32 v52, v52, v0
	v_mul_f32_e32 v53, v53, v0
	v_mul_f32_e32 v50, v50, v0
	v_mul_f32_e32 v51, v51, v0
	v_mul_f32_e32 v48, v48, v0
	v_mul_f32_e32 v49, v49, v0
	v_mul_f32_e32 v46, v46, v0
	v_mul_f32_e32 v47, v47, v0
	v_mul_f32_e32 v44, v44, v0
	v_mul_f32_e32 v45, v45, v0
	v_mul_f32_e32 v42, v42, v0
	v_mul_f32_e32 v43, v43, v0
	v_mul_f32_e32 v40, v40, v0
	v_mul_f32_e32 v41, v41, v0
	v_mul_f32_e32 v38, v38, v0
	v_mul_f32_e32 v39, v39, v0
	v_mul_f32_e32 v36, v36, v0
	v_mul_f32_e32 v37, v37, v0
	v_mul_f32_e32 v34, v34, v0
	v_mul_f32_e32 v35, v35, v0
	v_mul_f32_e32 v32, v32, v0
	v_mul_f32_e32 v33, v33, v0
	v_mul_f32_e32 v30, v30, v0
	v_mul_f32_e32 v31, v31, v0
	v_mul_f32_e32 v28, v28, v0
	v_mul_f32_e32 v29, v29, v0
	v_mul_f32_e32 v26, v26, v0
	v_mul_f32_e32 v27, v27, v0
	v_mul_f32_e32 v24, v24, v0
	v_mul_f32_e32 v25, v25, v0
	v_mul_f32_e32 v22, v22, v0
	v_mul_f32_e32 v23, v23, v0
	v_mul_f32_e32 v20, v20, v0
	v_mul_f32_e32 v21, v21, v0
	v_mul_f32_e32 v18, v18, v0
	v_mul_f32_e32 v19, v19, v0
	v_mul_f32_e32 v16, v16, v0
	v_mul_f32_e32 v17, v17, v0
	v_mul_f32_e32 v14, v14, v0
	v_mul_f32_e32 v15, v15, v0
	v_mul_f32_e32 v12, v12, v0
	v_mul_f32_e32 v13, v13, v0
	v_mul_f32_e32 v10, v10, v0
	v_mul_f32_e32 v11, v11, v0
	v_mul_f32_e32 v8, v8, v0
	v_mul_f32_e32 v9, v9, v0
	v_mul_f32_e32 v6, v6, v0
	v_mul_f32_e32 v7, v7, v0
	v_mul_f32_e32 v4, v4, v0
	v_mul_f32_e32 v5, v5, v0

; #define GAS __attribute__((address_space(1)))
; __device__ __forceinline__ unsigned pk2(float lo, float hi) { return f2bf(lo) | (f2bf(hi) << 16); }
; __device__ __forceinline__ void modulate_phase(Frame& F, const float* x, bf16* H, const float* gnorm, const float* modsub) {
;     ...
;         float s = 0.f;
; #pragma unroll
;         for (int j = 0; j < 8; ++j) s += (v[j].x * v[j].x + v[j].y * v[j].y) + (v[j].z * v[j].z + v[j].w * v[j].w);
;         const float rstd = 1.0f / sqrtf(wave_sum(s) * (1.0f / D) + RMS_EPS);
;         GAS unsigned long long* o8 = (GAS unsigned long long*)(H + (size_t)r * D) + F.lane;
; #pragma unroll
;         for (int j = 0; j < 8; ++j) { const f32x4 y = v[j] * rstd * gs[j] + sh[j];
;             o8[64 * j] = (unsigned long long)pk2(y.x, y.y) | ((unsigned long long)pk2(y.z, y.w) << 32); }
.LBB0_1734:
	s_waitcnt vmcnt(15)
	v_mul_f32_e32 v0, v95, v95
	v_mul_f32_e32 v155, v97, v97
	v_fmac_f32_e32 v0, v94, v94
	v_fmac_f32_e32 v155, v96, v96
	v_add_f32_e32 v0, v0, v155
	s_waitcnt vmcnt(14)
	v_mul_f32_e32 v155, v83, v83
	v_mul_f32_e32 v156, v85, v85
	v_fmac_f32_e32 v155, v82, v82
	v_fmac_f32_e32 v156, v84, v84
	v_add_f32_e32 v155, v155, v156
	v_add_f32_e32 v0, v0, v155
	s_waitcnt vmcnt(13)
	v_mul_f32_e32 v155, v47, v47
	v_mul_f32_e32 v156, v49, v49
	v_fmac_f32_e32 v155, v46, v46
	v_fmac_f32_e32 v156, v48, v48
	v_add_f32_e32 v155, v155, v156
	v_add_f32_e32 v0, v155, v0
	s_waitcnt vmcnt(12)
	v_mul_f32_e32 v155, v35, v35
	v_mul_f32_e32 v156, v37, v37
	v_fmac_f32_e32 v155, v34, v34
	v_fmac_f32_e32 v156, v36, v36
	v_add_f32_e32 v155, v155, v156
	v_add_f32_e32 v0, v155, v0
	s_waitcnt vmcnt(11)
	v_mul_f32_e32 v155, v31, v31
	v_mul_f32_e32 v156, v33, v33
	v_fmac_f32_e32 v155, v30, v30
	v_fmac_f32_e32 v156, v32, v32
	v_add_f32_e32 v155, v155, v156
	v_add_f32_e32 v0, v155, v0
	s_waitcnt vmcnt(10)
	v_mul_f32_e32 v155, v19, v19
	v_mul_f32_e32 v156, v21, v21
	v_fmac_f32_e32 v155, v18, v18
	v_fmac_f32_e32 v156, v20, v20
	v_add_f32_e32 v155, v155, v156
	v_add_f32_e32 v0, v155, v0
	s_waitcnt vmcnt(9)
	v_mul_f32_e32 v155, v15, v15
	v_mul_f32_e32 v156, v17, v17
	v_fmac_f32_e32 v155, v14, v14
	v_fmac_f32_e32 v156, v16, v16
	v_add_f32_e32 v155, v155, v156
	v_add_f32_e32 v0, v155, v0
	s_waitcnt vmcnt(8)
	v_mul_f32_e32 v155, v3, v3
	v_mul_f32_e32 v156, v5, v5
	v_fmac_f32_e32 v155, v2, v2
	v_fmac_f32_e32 v156, v4, v4
	v_add_f32_e32 v155, v155, v156
	v_add_f32_e32 v0, v155, v0
	ds_swizzle_b32 v155, v0 offset:swizzle(SWAP,1)
	s_waitcnt lgkmcnt(0)
	v_add_f32_e32 v0, v0, v155
	ds_swizzle_b32 v155, v0 offset:swizzle(SWAP,2)
	s_waitcnt lgkmcnt(0)
	v_add_f32_e32 v0, v0, v155
	ds_swizzle_b32 v155, v0 offset:swizzle(SWAP,4)
	s_waitcnt lgkmcnt(0)
	v_add_f32_e32 v0, v0, v155
	ds_swizzle_b32 v155, v0 offset:swizzle(SWAP,8)
	s_waitcnt lgkmcnt(0)
	v_add_f32_e32 v0, v0, v155
	ds_swizzle_b32 v155, v0 offset:swizzle(SWAP,16)
	s_waitcnt lgkmcnt(0)
	v_add_f32_e32 v0, v0, v155
	v_mov_b32_e32 v155, v0
	s_nop 1
	v_permlane32_swap_b32_e32 v0, v155
	v_add_f32_e32 v0, v0, v155
	v_fmamk_f32 v0, v0, 0x3a000000, v202
	v_mul_f32_e32 v155, 0x4f800000, v0
	v_cmp_gt_f32_e32 vcc, s60, v0
	s_nop 1
	v_cndmask_b32_e32 v0, v0, v155, vcc
	v_sqrt_f32_e32 v155, v0
	s_nop 0
	v_add_u32_e32 v156, -1, v155
	v_fma_f32 v157, -v156, v155, v0
	v_cmp_ge_f32_e64 s[40:41], 0, v157
	v_add_u32_e32 v157, 1, v155
	s_nop 0
	v_cndmask_b32_e64 v156, v155, v156, s[40:41]
	v_fma_f32 v155, -v157, v155, v0
	v_cmp_lt_f32_e64 s[40:41], 0, v155
	s_nop 1
	v_cndmask_b32_e64 v155, v156, v157, s[40:41]
	v_mul_f32_e32 v156, 0x37800000, v155
	v_cndmask_b32_e32 v155, v155, v156, vcc
	v_cmp_class_f32_e32 vcc, v0, v203
	s_nop 1
	v_cndmask_b32_e32 v0, v155, v0, vcc
	v_div_scale_f32 v155, s[10:11], v0, v0, 1.0
	v_rcp_f32_e32 v156, v155
	s_nop 0
	v_fma_f32 v157, -v155, v156, 1.0
	v_fmac_f32_e32 v156, v157, v156
	v_div_scale_f32 v157, vcc, 1.0, v0, 1.0
	v_mul_f32_e32 v158, v157, v156
	v_fma_f32 v159, -v155, v158, v157
	v_fmac_f32_e32 v158, v159, v156
	v_fma_f32 v155, -v155, v158, v157
	v_div_fmas_f32 v155, v155, v156, v158
	v_div_fixup_f32 v0, v155, v0, 1.0
	v_mul_f32_e32 v94, v94, v0
	v_mul_f32_e32 v95, v95, v0
	v_mul_f32_e32 v96, v96, v0
	v_mul_f32_e32 v97, v97, v0
	v_fma_f32 v94, v6, v94, v10
	v_fma_f32 v95, v7, v95, v11
	v_fma_f32 v96, v8, v96, v12
	v_fma_f32 v97, v9, v97, v13
	v_bfe_u32 v156, v94, 16, 1
	v_add3_u32 v94, v94, v156, s94
	v_bfe_u32 v156, v95, 16, 1
	v_lshrrev_b32_e32 v94, 16, v94
	v_add3_u32 v95, v95, v156, s94
	v_and_or_b32 v94, v95, s95, v94
	v_bfe_u32 v95, v96, 16, 1
	v_add3_u32 v95, v96, v95, s94
	v_bfe_u32 v96, v97, 16, 1
	v_lshrrev_b32_e32 v95, 16, v95
	v_add3_u32 v96, v97, v96, s94
	v_mul_f32_e32 v82, v82, v0
	v_mul_f32_e32 v83, v83, v0
	v_lshlrev_b32_e32 v155, 3, v130
	v_and_or_b32 v95, v96, s95, v95
	v_fma_f32 v82, v26, v82, v22
	v_fma_f32 v83, v27, v83, v23
	global_store_dwordx2 v155, v[94:95], s[6:7]
	v_bfe_u32 v94, v82, 16, 1
	v_mul_f32_e32 v84, v84, v0
	v_mul_f32_e32 v85, v85, v0
	v_add3_u32 v82, v82, v94, s94
	v_bfe_u32 v94, v83, 16, 1
	v_fma_f32 v84, v28, v84, v24
	v_fma_f32 v85, v29, v85, v25
	v_lshrrev_b32_e32 v82, 16, v82
	v_add3_u32 v83, v83, v94, s94
	v_and_or_b32 v82, v83, s95, v82
	v_bfe_u32 v83, v84, 16, 1
	v_add3_u32 v83, v84, v83, s94
	v_bfe_u32 v84, v85, 16, 1
	v_lshrrev_b32_e32 v83, 16, v83
	v_add3_u32 v84, v85, v84, s94
	v_mul_f32_e32 v46, v46, v0
	v_mul_f32_e32 v47, v47, v0
	v_and_or_b32 v83, v84, s95, v83
	v_fma_f32 v46, v42, v46, v38
	v_fma_f32 v47, v43, v47, v39
	global_store_dwordx2 v155, v[82:83], s[6:7] offset:512
	v_bfe_u32 v82, v46, 16, 1
	v_mul_f32_e32 v48, v48, v0
	v_mul_f32_e32 v49, v49, v0
	v_add3_u32 v46, v46, v82, s94
	v_bfe_u32 v82, v47, 16, 1
	v_fma_f32 v48, v44, v48, v40
	v_fma_f32 v49, v45, v49, v41
	v_lshrrev_b32_e32 v46, 16, v46
	v_add3_u32 v47, v47, v82, s94
	v_and_or_b32 v46, v47, s95, v46
	v_bfe_u32 v47, v48, 16, 1
	v_add3_u32 v47, v48, v47, s94
	v_bfe_u32 v48, v49, 16, 1
	v_lshrrev_b32_e32 v47, 16, v47
	v_add3_u32 v48, v49, v48, s94
	v_mul_f32_e32 v34, v34, v0
	v_mul_f32_e32 v35, v35, v0
	v_and_or_b32 v47, v48, s95, v47
	v_fma_f32 v34, v90, v34, v78
	v_fma_f32 v35, v91, v35, v79
	global_store_dwordx2 v155, v[46:47], s[6:7] offset:1024
	v_bfe_u32 v46, v34, 16, 1
	v_mul_f32_e32 v36, v36, v0
	v_mul_f32_e32 v37, v37, v0
	v_add3_u32 v34, v34, v46, s94
	v_bfe_u32 v46, v35, 16, 1
	v_fma_f32 v36, v92, v36, v80
	v_fma_f32 v37, v93, v37, v81
	v_lshrrev_b32_e32 v34, 16, v34
	v_add3_u32 v35, v35, v46, s94
	v_and_or_b32 v34, v35, s95, v34
	v_bfe_u32 v35, v36, 16, 1
; #define GAS __attribute__((address_space(1)))
; __device__ __forceinline__ unsigned pk2(float lo, float hi) { return f2bf(lo) | (f2bf(hi) << 16); }
; __device__ __forceinline__ void modulate_phase(Frame& F, const float* x, bf16* H, const float* gnorm, const float* modsub) {
;     ...
;         GAS unsigned long long* o8 = (GAS unsigned long long*)(H + (size_t)r * D) + F.lane;
; #pragma unroll
;         for (int j = 0; j < 8; ++j) { const f32x4 y = v[j] * rstd * gs[j] + sh[j];
;             o8[64 * j] = (unsigned long long)pk2(y.x, y.y) | ((unsigned long long)pk2(y.z, y.w) << 32); }
; #pragma unroll
;         for (int j = 0; j < 8; ++j) v[j] = nv[j];
	v_add3_u32 v35, v36, v35, s94
	v_bfe_u32 v36, v37, 16, 1
	v_lshrrev_b32_e32 v35, 16, v35
	v_add3_u32 v36, v37, v36, s94
	v_mul_f32_e32 v30, v30, v0
	v_mul_f32_e32 v31, v31, v0
	v_and_or_b32 v35, v36, s95, v35
	v_fma_f32 v30, v102, v30, v98
	v_fma_f32 v31, v103, v31, v99
	global_store_dwordx2 v155, v[34:35], s[6:7] offset:1536
	v_bfe_u32 v34, v30, 16, 1
	v_mul_f32_e32 v32, v32, v0
	v_mul_f32_e32 v33, v33, v0
	v_add3_u32 v30, v30, v34, s94
	v_bfe_u32 v34, v31, 16, 1
	v_fma_f32 v32, v104, v32, v100
	v_fma_f32 v33, v105, v33, v101
	v_lshrrev_b32_e32 v30, 16, v30
	v_add3_u32 v31, v31, v34, s94
	v_and_or_b32 v30, v31, s95, v30
	v_bfe_u32 v31, v32, 16, 1
	v_add3_u32 v31, v32, v31, s94
	v_bfe_u32 v32, v33, 16, 1
	v_lshrrev_b32_e32 v31, 16, v31
	v_add3_u32 v32, v33, v32, s94
	v_mul_f32_e32 v18, v18, v0
	v_mul_f32_e32 v19, v19, v0
	v_and_or_b32 v31, v32, s95, v31
	v_fma_f32 v18, v110, v18, v106
	v_fma_f32 v19, v111, v19, v107
	global_store_dwordx2 v155, v[30:31], s[6:7] offset:2048
	v_bfe_u32 v30, v18, 16, 1
	v_mul_f32_e32 v20, v20, v0
	v_mul_f32_e32 v21, v21, v0
	v_add3_u32 v18, v18, v30, s94
	v_bfe_u32 v30, v19, 16, 1
	v_fma_f32 v20, v112, v20, v108
	v_fma_f32 v21, v113, v21, v109
	v_lshrrev_b32_e32 v18, 16, v18
	v_add3_u32 v19, v19, v30, s94
	v_and_or_b32 v18, v19, s95, v18
	v_bfe_u32 v19, v20, 16, 1
	v_add3_u32 v19, v20, v19, s94
	v_bfe_u32 v20, v21, 16, 1
	v_lshrrev_b32_e32 v19, 16, v19
	v_add3_u32 v20, v21, v20, s94
	v_mul_f32_e32 v14, v14, v0
	v_mul_f32_e32 v15, v15, v0
	v_mul_f32_e32 v2, v2, v0
	v_mul_f32_e32 v3, v3, v0
	v_and_or_b32 v19, v20, s95, v19
	v_fma_f32 v14, v118, v14, v114
	v_fma_f32 v15, v119, v15, v115
	s_waitcnt vmcnt(5)
	v_fma_f32 v2, v122, v2, v126
	v_fma_f32 v3, v123, v3, v127
	global_store_dwordx2 v155, v[18:19], s[6:7] offset:2560
	v_mul_f32_e32 v16, v16, v0
	v_mul_f32_e32 v17, v17, v0
	v_bfe_u32 v18, v14, 16, 1
	v_mul_f32_e32 v4, v4, v0
	v_mul_f32_e32 v5, v5, v0
	v_bfe_u32 v0, v2, 16, 1
	v_add3_u32 v14, v14, v18, s94
	v_bfe_u32 v18, v15, 16, 1
	v_add3_u32 v0, v2, v0, s94
	v_bfe_u32 v2, v3, 16, 1
	v_fma_f32 v16, v120, v16, v116
	v_fma_f32 v17, v121, v17, v117
	v_lshrrev_b32_e32 v14, 16, v14
	v_add3_u32 v15, v15, v18, s94
	v_fma_f32 v4, v124, v4, v128
	v_fma_f32 v5, v125, v5, v129
	v_lshrrev_b32_e32 v0, 16, v0
	v_add3_u32 v2, v3, v2, s94
	v_and_or_b32 v14, v15, s95, v14
	v_bfe_u32 v15, v16, 16, 1
	v_and_or_b32 v2, v2, s95, v0
	v_bfe_u32 v0, v4, 16, 1
	v_add3_u32 v15, v16, v15, s94
	v_bfe_u32 v16, v17, 16, 1
	v_add3_u32 v0, v4, v0, s94
	v_bfe_u32 v3, v5, 16, 1
	v_lshrrev_b32_e32 v15, 16, v15
	v_add3_u32 v16, v17, v16, s94
	v_lshrrev_b32_e32 v0, 16, v0
	v_add3_u32 v3, v5, v3, s94
	v_and_or_b32 v15, v16, s95, v15
	v_and_or_b32 v3, v3, s95, v0
	global_store_dwordx2 v155, v[14:15], s[6:7] offset:3072
	global_store_dwordx2 v155, v[2:3], s[6:7] offset:3584
	s_add_u32 s6, s6, 0x1000
	s_addc_u32 s7, s7, 0
	s_cmp_lt_i32 s0, s2
	v_mov_b32_e32 v94, v86
	v_mov_b32_e32 v95, v87
	v_mov_b32_e32 v96, v88
	v_mov_b32_e32 v97, v89
	v_mov_b32_e32 v82, v74
	v_mov_b32_e32 v83, v75
	v_mov_b32_e32 v84, v76
	v_mov_b32_e32 v85, v77
	v_mov_b32_e32 v46, v66
	v_mov_b32_e32 v47, v67
	v_mov_b32_e32 v48, v68
	v_mov_b32_e32 v49, v69
	v_mov_b32_e32 v34, v58
	v_mov_b32_e32 v35, v59
	v_mov_b32_e32 v36, v60
	v_mov_b32_e32 v37, v61
	v_mov_b32_e32 v30, v70
	v_mov_b32_e32 v31, v71
	v_mov_b32_e32 v32, v72
	v_mov_b32_e32 v33, v73
	v_mov_b32_e32 v18, v62
	v_mov_b32_e32 v19, v63
	v_mov_b32_e32 v20, v64
	v_mov_b32_e32 v21, v65
	v_mov_b32_e32 v14, v54
	v_mov_b32_e32 v15, v55
	v_mov_b32_e32 v16, v56
	v_mov_b32_e32 v17, v57
	v_mov_b32_e32 v2, v50
	v_mov_b32_e32 v3, v51
	v_mov_b32_e32 v4, v52
	v_mov_b32_e32 v5, v53
	s_cbranch_scc0 .LBB0_1737
; #define GAS __attribute__((address_space(1)))
; __device__ __forceinline__ void modulate_phase(Frame& F, const float* x, bf16* H, const float* gnorm, const float* modsub) {
;     ...
;     for (int r = rbeg; r < rend; ++r) {
;         { const GAS f32x4* xn = (const GAS f32x4*)(x + (size_t)min(r + 1, rend - 1) * D) + F.lane;
; #pragma unroll
;           for (int j = 0; j < 8; ++j) nv[j] = xn[64 * j]; }
;         const int b = r >> 12;
;         if (b != curb) { curb = b;
; #pragma unroll
;             for (int j = 0; j < 8; ++j) { const int c = 4 * F.lane + 256 * j;
;                 const f32x4 g = *(const GAS f32x4*)(gnorm + c), sc = *(const GAS f32x4*)(modsub + (size_t)b * NMOD + D + c);
;                 gs[j] = g * (sc + 1.0f); sh[j] = *(const GAS f32x4*)(modsub + (size_t)b * NMOD + c); } }
.LBB0_1735:
	s_mov_b32 s1, s0
	s_add_i32 s0, s0, 1
	s_min_i32 s10, s0, s16
	s_ashr_i32 s11, s10, 31
	s_lshl_b64 s[10:11], s[10:11], 13
	s_add_u32 s10, s12, s10
	s_addc_u32 s11, s13, s11
	v_lshlrev_b32_e32 v0, 4, v130
	v_lshl_add_u64 v[50:51], s[10:11], 0, v[0:1]
	v_add_co_u32_e32 v50, vcc, 0x1000, v50
	global_load_dwordx4 v[86:89], v0, s[10:11]
	global_load_dwordx4 v[74:77], v0, s[10:11] offset:1024
	global_load_dwordx4 v[66:69], v0, s[10:11] offset:2048
	global_load_dwordx4 v[58:61], v0, s[10:11] offset:3072
	v_addc_co_u32_e32 v51, vcc, 0, v51, vcc
	global_load_dwordx4 v[70:73], v[50:51], off
	global_load_dwordx4 v[62:65], v[50:51], off offset:1024
	global_load_dwordx4 v[54:57], v[50:51], off offset:2048
	s_nop 0
	global_load_dwordx4 v[50:53], v[50:51], off offset:3072
	s_ashr_i32 s1, s1, 12
	s_cmp_eq_u32 s1, s8
	s_cbranch_scc1 .LBB0_1734
	s_mul_i32 s8, s1, 0x12000
	s_mul_hi_i32 s9, s1, 0x12000
	s_add_u32 s8, s14, s8
	s_addc_u32 s9, s15, s9
	s_add_u32 s10, s8, 0x2000
	s_addc_u32 s11, s9, 0
	global_load_dwordx4 v[6:9], v[132:133], off
	global_load_dwordx4 v[10:13], v131, s[10:11]
	s_waitcnt vmcnt(0)
	v_add_f32_e32 v12, 1.0, v12
	v_add_f32_e32 v13, 1.0, v13
	v_add_f32_e32 v10, 1.0, v10
	v_add_f32_e32 v11, 1.0, v11
	v_mul_f32_e32 v8, v8, v12
	v_mul_f32_e32 v9, v9, v13
	v_mul_f32_e32 v6, v6, v10
	v_mul_f32_e32 v7, v7, v11
	global_load_dwordx4 v[10:13], v131, s[8:9]
	global_load_dwordx4 v[22:25], v[134:135], off
	global_load_dwordx4 v[26:29], v148, s[10:11]
	s_waitcnt vmcnt(0)
	v_add_f32_e32 v28, 1.0, v28
	v_add_f32_e32 v29, 1.0, v29
	v_add_f32_e32 v26, 1.0, v26
	v_add_f32_e32 v27, 1.0, v27
	v_mul_f32_e32 v28, v24, v28
	v_mul_f32_e32 v29, v25, v29
	v_mul_f32_e32 v26, v22, v26
	v_mul_f32_e32 v27, v23, v27
	global_load_dwordx4 v[22:25], v131, s[8:9] offset:1024
	global_load_dwordx4 v[38:41], v[136:137], off
	global_load_dwordx4 v[42:45], v149, s[10:11]
	s_waitcnt vmcnt(0)
	v_add_f32_e32 v44, 1.0, v44
	v_add_f32_e32 v45, 1.0, v45
	v_add_f32_e32 v42, 1.0, v42
	v_add_f32_e32 v43, 1.0, v43
	v_mul_f32_e32 v44, v40, v44
	v_mul_f32_e32 v45, v41, v45
	v_mul_f32_e32 v42, v38, v42
	v_mul_f32_e32 v43, v39, v43
	global_load_dwordx4 v[38:41], v131, s[8:9] offset:2048
	global_load_dwordx4 v[78:81], v[138:139], off
	global_load_dwordx4 v[90:93], v150, s[10:11]
	s_waitcnt vmcnt(0)
	v_add_f32_e32 v92, 1.0, v92
	v_add_f32_e32 v93, 1.0, v93
	v_add_f32_e32 v90, 1.0, v90
	v_add_f32_e32 v91, 1.0, v91
	v_mul_f32_e32 v92, v80, v92
	v_mul_f32_e32 v93, v81, v93
	v_mul_f32_e32 v90, v78, v90
	v_mul_f32_e32 v91, v79, v91
	global_load_dwordx4 v[78:81], v131, s[8:9] offset:3072
	global_load_dwordx4 v[98:101], v[140:141], off
	global_load_dwordx4 v[102:105], v151, s[10:11]
	s_waitcnt vmcnt(0)
	v_add_f32_e32 v104, 1.0, v104
	v_add_f32_e32 v105, 1.0, v105
	v_add_f32_e32 v102, 1.0, v102
	v_add_f32_e32 v103, 1.0, v103
	v_mul_f32_e32 v104, v100, v104
	v_mul_f32_e32 v105, v101, v105
	v_mul_f32_e32 v102, v98, v102
	v_mul_f32_e32 v103, v99, v103
	global_load_dwordx4 v[98:101], v151, s[8:9]
	global_load_dwordx4 v[106:109], v[142:143], off
	global_load_dwordx4 v[110:113], v152, s[10:11]
	s_waitcnt vmcnt(0)
	v_add_f32_e32 v112, 1.0, v112
	v_add_f32_e32 v113, 1.0, v113
	v_add_f32_e32 v110, 1.0, v110
	v_add_f32_e32 v111, 1.0, v111
	v_mul_f32_e32 v112, v108, v112
	v_mul_f32_e32 v113, v109, v113
	v_mul_f32_e32 v110, v106, v110
	v_mul_f32_e32 v111, v107, v111
	global_load_dwordx4 v[106:109], v152, s[8:9]
	global_load_dwordx4 v[114:117], v[144:145], off
	global_load_dwordx4 v[118:121], v153, s[10:11]
	s_waitcnt vmcnt(0)
	v_add_f32_e32 v120, 1.0, v120
	v_add_f32_e32 v121, 1.0, v121
	v_add_f32_e32 v118, 1.0, v118
	v_add_f32_e32 v119, 1.0, v119
	v_mul_f32_e32 v120, v116, v120
	v_mul_f32_e32 v121, v117, v121
	v_mul_f32_e32 v118, v114, v118
	v_mul_f32_e32 v119, v115, v119
	global_load_dwordx4 v[114:117], v153, s[8:9]
	global_load_dwordx4 v[122:125], v[146:147], off
	global_load_dwordx4 v[126:129], v154, s[10:11]
	s_waitcnt vmcnt(0)
	v_add_f32_e32 v128, 1.0, v128
	v_add_f32_e32 v129, 1.0, v129
	v_add_f32_e32 v126, 1.0, v126
	v_add_f32_e32 v127, 1.0, v127
	v_mul_f32_e32 v124, v124, v128
	v_mul_f32_e32 v125, v125, v129
	v_mul_f32_e32 v122, v122, v126
	v_mul_f32_e32 v123, v123, v127
	global_load_dwordx4 v[126:129], v154, s[8:9]
	s_mov_b32 s8, s1
	s_branch .LBB0_1734

; #define GAS __attribute__((address_space(1)))
; __device__ __forceinline__ void final_norm_phase(Frame& F, const float* x, float* out, const float* gfin) {
;     ...
;     for (int r = gw; r < M; r += NGW) {
;         const GAS f32x4* xr = (const GAS f32x4*)(x + (size_t)r * D) + F.lane;
;         f32x4 v[8]; float s = 0.f;
; #pragma unroll
;         for (int j = 0; j < 8; ++j) { v[j] = xr[64 * j]; s += (v[j].x * v[j].x + v[j].y * v[j].y) + (v[j].z * v[j].z + v[j].w * v[j].w); }
;         const float rstd = 1.0f / sqrtf(wave_sum(s) * (1.0f / D) + RMS_EPS);
;         GAS f32x4* o = (GAS f32x4*)(out + (size_t)r * D) + F.lane;
; #pragma unroll
;         for (int j = 0; j < 8; ++j) { f32x4 y = v[j] * rstd * gs[j];
;     ...
;             y.x = (y.x == y.x && fabsf(y.x) < 1e30f) ? y.x : 0.f; y.y = (y.y == y.y && fabsf(y.y) < 1e30f) ? y.y : 0.f; y.z = (y.z == y.z && fabsf(y.z) < 1e30f) ? y.z : 0.f; y.w = (y.w == y.w && fabsf(y.w) < 1e30f) ? y.w : 0.f;
;     ...
;             o[64 * j] = y; }
.LBB0_1925:
	s_add_u32 s0, s12, s4
	s_addc_u32 s1, s13, s5
	global_load_dwordx4 v[32:35], v48, s[0:1]
	global_load_dwordx4 v[36:39], v48, s[0:1] offset:1024
	global_load_dwordx4 v[40:43], v48, s[0:1] offset:2048
	global_load_dwordx4 v[44:47], v48, s[0:1] offset:3072
	v_lshl_add_u64 v[52:53], s[0:1], 0, v[48:49]
	v_add_co_u32_e32 v68, vcc, s14, v52
	s_add_u32 s10, s6, s4
	s_nop 0
	v_addc_co_u32_e32 v69, vcc, 0, v53, vcc
	global_load_dwordx4 v[52:55], v[68:69], off
	global_load_dwordx4 v[56:59], v[68:69], off offset:1024
	global_load_dwordx4 v[60:63], v[68:69], off offset:2048
	global_load_dwordx4 v[64:67], v[68:69], off offset:3072
	s_addc_u32 s11, s7, s5
	v_lshl_add_u64 v[68:69], s[10:11], 0, v[48:49]
	v_add_co_u32_e32 v68, vcc, s14, v68
	s_add_i32 s2, s2, s16
	s_nop 0
	v_addc_co_u32_e32 v69, vcc, 0, v69, vcc
	s_add_u32 s4, s4, s8
	s_addc_u32 s5, s5, s9
	s_cmpk_lt_i32 s2, 0x4000
	s_waitcnt vmcnt(0)
	v_mul_f32_e32 v70, v33, v33
	v_mul_f32_e32 v71, v35, v35
	v_mul_f32_e32 v72, v37, v37
	v_mul_f32_e32 v73, v39, v39
	v_mul_f32_e32 v74, v41, v41
	v_mul_f32_e32 v75, v43, v43
	v_fmac_f32_e32 v70, v32, v32
	v_fmac_f32_e32 v71, v34, v34
	v_fmac_f32_e32 v72, v36, v36
	v_fmac_f32_e32 v73, v38, v38
	v_mul_f32_e32 v76, v45, v45
	v_mul_f32_e32 v77, v47, v47
	v_fmac_f32_e32 v74, v40, v40
	v_fmac_f32_e32 v75, v42, v42
	v_add_f32_e32 v70, v70, v71
	v_add_f32_e32 v71, v72, v73
	v_fmac_f32_e32 v76, v44, v44
	v_fmac_f32_e32 v77, v46, v46
	v_add_f32_e32 v72, v74, v75
	v_mul_f32_e32 v74, v53, v53
	v_mul_f32_e32 v75, v55, v55
	v_add_f32_e32 v70, v70, v71
	v_add_f32_e32 v73, v76, v77
	v_mul_f32_e32 v76, v57, v57
	v_mul_f32_e32 v77, v59, v59
	v_fmac_f32_e32 v74, v52, v52
	v_fmac_f32_e32 v75, v54, v54
	v_add_f32_e32 v70, v70, v72
	v_mul_f32_e32 v78, v61, v61
	v_mul_f32_e32 v79, v63, v63
	v_fmac_f32_e32 v76, v56, v56
	v_fmac_f32_e32 v77, v58, v58
	v_add_f32_e32 v71, v74, v75
	v_add_f32_e32 v70, v70, v73
	v_mul_f32_e32 v80, v65, v65
	v_mul_f32_e32 v81, v67, v67
	v_fmac_f32_e32 v78, v60, v60
	v_fmac_f32_e32 v79, v62, v62
	v_add_f32_e32 v72, v76, v77
	v_add_f32_e32 v70, v70, v71
	v_fmac_f32_e32 v80, v64, v64
	v_fmac_f32_e32 v81, v66, v66
	v_add_f32_e32 v74, v78, v79
	v_add_f32_e32 v70, v70, v72
	v_add_f32_e32 v75, v80, v81
	v_add_f32_e32 v70, v70, v74
	v_add_f32_e32 v70, v70, v75
	ds_swizzle_b32 v71, v70 offset:swizzle(SWAP,1)
	s_waitcnt lgkmcnt(0)
	v_add_f32_e32 v70, v70, v71
	ds_swizzle_b32 v71, v70 offset:swizzle(SWAP,2)
	s_waitcnt lgkmcnt(0)
	v_add_f32_e32 v70, v70, v71
	ds_swizzle_b32 v71, v70 offset:swizzle(SWAP,4)
	s_waitcnt lgkmcnt(0)
	v_add_f32_e32 v70, v70, v71
	ds_swizzle_b32 v71, v70 offset:swizzle(SWAP,8)
	s_waitcnt lgkmcnt(0)
	v_add_f32_e32 v70, v70, v71
	ds_swizzle_b32 v71, v70 offset:swizzle(SWAP,16)
	s_waitcnt lgkmcnt(0)
	v_add_f32_e32 v70, v70, v71
	v_mov_b32_e32 v71, v70
	s_nop 1
	v_permlane32_swap_b32_e32 v70, v71
	v_add_f32_e32 v70, v70, v71
	v_fmamk_f32 v70, v70, 0x3a000000, v50
	v_mul_f32_e32 v71, 0x4f800000, v70
	v_cmp_gt_f32_e32 vcc, s3, v70
	s_nop 1
	v_cndmask_b32_e32 v70, v70, v71, vcc
	v_sqrt_f32_e32 v71, v70
	s_nop 0
	v_add_u32_e32 v72, -1, v71
	v_add_u32_e32 v73, 1, v71
	v_fma_f32 v74, -v72, v71, v70
	v_fma_f32 v75, -v73, v71, v70
	v_cmp_ge_f32_e64 s[0:1], 0, v74
	s_nop 1
	v_cndmask_b32_e64 v71, v71, v72, s[0:1]
	v_cmp_lt_f32_e64 s[0:1], 0, v75
	s_nop 1
	v_cndmask_b32_e64 v71, v71, v73, s[0:1]
	v_mul_f32_e32 v72, 0x37800000, v71
	v_cndmask_b32_e32 v71, v71, v72, vcc
	v_cmp_class_f32_e32 vcc, v70, v51
	s_nop 1
	v_cndmask_b32_e32 v70, v71, v70, vcc
	v_div_scale_f32 v71, s[0:1], v70, v70, 1.0
	v_rcp_f32_e32 v73, v71
	v_div_scale_f32 v72, vcc, 1.0, v70, 1.0
	v_fma_f32 v74, -v71, v73, 1.0
	v_fmac_f32_e32 v73, v74, v73
	v_mul_f32_e32 v74, v72, v73
	v_fma_f32 v75, -v71, v74, v72
	v_fmac_f32_e32 v74, v75, v73
	v_fma_f32 v71, -v71, v74, v72
	v_div_fmas_f32 v71, v71, v73, v74
	v_div_fixup_f32 v70, v71, v70, 1.0
	v_mul_f32_e32 v32, v32, v70
	v_mul_f32_e32 v33, v33, v70
	v_mul_f32_e32 v34, v34, v70
	v_mul_f32_e32 v35, v35, v70
	v_mul_f32_e32 v36, v36, v70
	v_mul_f32_e32 v37, v37, v70
	v_mul_f32_e32 v38, v38, v70
	v_mul_f32_e32 v39, v39, v70
	v_mul_f32_e32 v40, v40, v70
	v_mul_f32_e32 v41, v41, v70
	v_mul_f32_e32 v42, v42, v70
	v_mul_f32_e32 v43, v43, v70
	v_mul_f32_e32 v44, v44, v70
	v_mul_f32_e32 v45, v45, v70
	v_mul_f32_e32 v46, v46, v70
	v_mul_f32_e32 v47, v47, v70
	v_mul_f32_e32 v52, v52, v70
	v_mul_f32_e32 v53, v53, v70
	v_mul_f32_e32 v54, v54, v70
	v_mul_f32_e32 v55, v55, v70
	v_mul_f32_e32 v56, v56, v70
	v_mul_f32_e32 v57, v57, v70
	v_mul_f32_e32 v58, v58, v70
	v_mul_f32_e32 v59, v59, v70
	v_mul_f32_e32 v60, v60, v70
	v_mul_f32_e32 v61, v61, v70
	v_mul_f32_e32 v62, v62, v70
	v_mul_f32_e32 v63, v63, v70
	v_mul_f32_e32 v64, v64, v70
	v_mul_f32_e32 v65, v65, v70
	v_mul_f32_e32 v66, v66, v70
	v_mul_f32_e32 v67, v67, v70
	v_mul_f32_e32 v34, v2, v34
	v_mul_f32_e32 v35, v3, v35
	v_mul_f32_e32 v32, v0, v32
	v_mul_f32_e32 v33, v1, v33
	v_mul_f32_e32 v38, v6, v38
	v_mul_f32_e32 v39, v7, v39
	v_mul_f32_e32 v36, v4, v36
	v_mul_f32_e32 v37, v5, v37
	v_mul_f32_e32 v42, v10, v42
	v_mul_f32_e32 v43, v11, v43
	v_mul_f32_e32 v40, v8, v40
	v_mul_f32_e32 v41, v9, v41
	v_mul_f32_e32 v46, v14, v46
	v_mul_f32_e32 v47, v15, v47
	v_mul_f32_e32 v44, v12, v44
	v_mul_f32_e32 v45, v13, v45
	v_mul_f32_e32 v54, v18, v54
	v_mul_f32_e32 v55, v19, v55
	v_mul_f32_e32 v52, v16, v52
	v_mul_f32_e32 v53, v17, v53
	v_mul_f32_e32 v58, v22, v58
	v_mul_f32_e32 v59, v23, v59
	v_mul_f32_e32 v56, v20, v56
	v_mul_f32_e32 v57, v21, v57
	v_mul_f32_e32 v62, v26, v62
	v_mul_f32_e32 v63, v27, v63
	v_mul_f32_e32 v60, v24, v60
	v_mul_f32_e32 v61, v25, v61
	v_mul_f32_e32 v66, v30, v66
	v_mul_f32_e32 v67, v31, v67
	v_mul_f32_e32 v64, v28, v64
	v_mul_f32_e32 v65, v29, v65
	global_store_dwordx4 v48, v[32:35], s[10:11]
	global_store_dwordx4 v48, v[36:39], s[10:11] offset:1024
	global_store_dwordx4 v48, v[40:43], s[10:11] offset:2048
	global_store_dwordx4 v48, v[44:47], s[10:11] offset:3072
	global_store_dwordx4 v[68:69], v[52:55], off
	global_store_dwordx4 v[68:69], v[56:59], off offset:1024
	global_store_dwordx4 v[68:69], v[60:63], off offset:2048
	global_store_dwordx4 v[68:69], v[64:67], off offset:3072
	s_cbranch_scc1 .LBB0_1925
